# cross-attention QK stages: hoisted K-fragment reads plus MFMAs interleaved across the four independent accumulators (kk-major) instead of four serial 8-deep chains
# speedup vs baseline: 1.0130x; 1.0130x over previous
.LBB0_318:
	s_or_b64 exec, exec, s[6:7]
	s_lshl_b32 s6, s52, 7
	s_add_u32 s6, s71, s6
	s_waitcnt lgkmcnt(0)
	s_barrier
	s_addc_u32 s7, s72, 0
	v_lshlrev_b32_e32 v1, 5, v144
	global_load_dwordx4 v[136:139], v1, s[6:7] offset:16
	global_load_dwordx4 v[144:147], v1, s[6:7]
	s_waitcnt lgkmcnt(0)
	global_load_dwordx4 v[132:135], v1, s[6:7] offset:528
	global_load_dwordx4 v[140:143], v1, s[6:7] offset:512
	s_lshl_b32 s6, s55, 10
	s_add_i32 s6, s6, 0
	v_lshl_add_u32 v3, v3, 4, s6
	v_add_u32_e32 v1, 0x20000, v3
	ds_read_b128 v[154:157], v1
	s_lshl_b32 s8, s52, 6
	s_add_i32 s15, s8, 0
	s_movk_i32 s16, 0x210
	s_ashr_i32 s6, s54, 3
	s_waitcnt lgkmcnt(0)
	v_mov_b32_e32 v158, v155
	v_mov_b32_e32 v159, v156
	v_mov_b32_e32 v155, v157
	v_pk_add_f32 v[154:155], v[158:159], v[154:155]
	v_readlane_b32 s10, v254, 18
	v_add_f32_e32 v1, v154, v155
	v_fmamk_f32 v1, v1, 0x3b800000, v213
	v_rsq_f32_e32 v1, v1
	v_readlane_b32 s11, v254, 19
	v_readlane_b32 s48, v254, 41
	v_readlane_b32 s49, v254, 42
	v_mul_f32_e32 v160, v0, v1
	v_add_u32_e32 v0, 0x20100, v3
	ds_read_b128 v[154:157], v0
	v_pk_mul_f32 v[128:129], v[128:129], v[160:161] op_sel_hi:[1,0]
	v_pk_mul_f32 v[120:121], v[120:121], v[160:161] op_sel_hi:[1,0]
	v_pk_mul_f32 v[124:125], v[124:125], v[160:161] op_sel_hi:[1,0]
	v_pk_mul_f32 v[126:127], v[126:127], v[160:161] op_sel_hi:[1,0]
	s_waitcnt lgkmcnt(0)
	v_mov_b32_e32 v0, v155
	v_mov_b32_e32 v1, v156
	v_mov_b32_e32 v155, v157
	v_pk_add_f32 v[0:1], v[0:1], v[154:155]
	v_pk_mul_f32 v[116:117], v[116:117], v[160:161] op_sel_hi:[1,0]
	v_add_f32_e32 v0, v0, v1
	v_fmamk_f32 v0, v0, 0x3b800000, v213
	v_rsq_f32_e32 v0, v0
	v_pk_mul_f32 v[118:119], v[118:119], v[160:161] op_sel_hi:[1,0]
	v_pk_mul_f32 v[130:131], v[130:131], v[160:161] op_sel_hi:[1,0]
	v_pk_mul_f32 v[122:123], v[122:123], v[160:161] op_sel_hi:[1,0]
	v_mul_f32_e32 v158, v148, v0
	v_add_u32_e32 v0, 0x20200, v3
	ds_read_b128 v[154:157], v0
	v_pk_mul_f32 v[112:113], v[112:113], v[158:159] op_sel_hi:[1,0]
	v_pk_mul_f32 v[100:101], v[100:101], v[158:159] op_sel_hi:[1,0]
	v_pk_mul_f32 v[108:109], v[108:109], v[158:159] op_sel_hi:[1,0]
	v_pk_mul_f32 v[110:111], v[110:111], v[158:159] op_sel_hi:[1,0]
	s_waitcnt lgkmcnt(0)
	v_mov_b32_e32 v0, v155
	v_mov_b32_e32 v1, v156
	v_mov_b32_e32 v155, v157
	v_pk_add_f32 v[0:1], v[0:1], v[154:155]
	v_pk_mul_f32 v[92:93], v[92:93], v[158:159] op_sel_hi:[1,0]
	v_add_f32_e32 v0, v0, v1
	v_fmamk_f32 v0, v0, 0x3b800000, v213
	v_rsq_f32_e32 v0, v0
	v_pk_mul_f32 v[94:95], v[94:95], v[158:159] op_sel_hi:[1,0]
	v_pk_mul_f32 v[102:103], v[102:103], v[158:159] op_sel_hi:[1,0]
	v_pk_mul_f32 v[114:115], v[114:115], v[158:159] op_sel_hi:[1,0]
	v_mul_f32_e32 v156, v150, v0
	v_add_u32_e32 v0, 0x20300, v3
	ds_read_b128 v[174:177], v0
	v_pk_mul_f32 v[84:85], v[84:85], v[156:157] op_sel_hi:[1,0]
	v_pk_mul_f32 v[96:97], v[96:97], v[156:157] op_sel_hi:[1,0]
	v_pk_mul_f32 v[98:99], v[98:99], v[156:157] op_sel_hi:[1,0]
	v_pk_mul_f32 v[76:77], v[76:77], v[156:157] op_sel_hi:[1,0]
	s_waitcnt lgkmcnt(0)
	v_mov_b32_e32 v0, v175
	v_mov_b32_e32 v1, v176
	v_mov_b32_e32 v175, v177
	v_pk_add_f32 v[0:1], v[0:1], v[174:175]
	v_pk_mul_f32 v[78:79], v[78:79], v[156:157] op_sel_hi:[1,0]
	v_add_f32_e32 v0, v0, v1
	v_fmamk_f32 v0, v0, 0x3b800000, v213
	v_rsq_f32_e32 v0, v0
	v_pk_mul_f32 v[86:87], v[86:87], v[156:157] op_sel_hi:[1,0]
	v_mul_f32_e32 v154, v152, v0
	v_add_u32_e32 v0, 0x20800, v3
	ds_read_b128 v[174:177], v0
	s_waitcnt vmcnt(0)
	v_pk_mul_f32 v[128:129], v[144:145], v[128:129]
	v_pk_mul_f32 v[112:113], v[144:145], v[112:113]
	v_pk_mul_f32 v[120:121], v[140:141], v[120:121]
	v_pk_mul_f32 v[100:101], v[140:141], v[100:101]
	s_waitcnt lgkmcnt(0)
	v_mov_b32_e32 v0, v175
	v_mov_b32_e32 v1, v176
	v_mov_b32_e32 v175, v177
	v_pk_add_f32 v[0:1], v[0:1], v[174:175]
	v_pk_mul_f32 v[84:85], v[140:141], v[84:85]
	v_add_f32_e32 v0, v0, v1
	v_fmamk_f32 v0, v0, 0x3b800000, v213
	v_rsq_f32_e32 v0, v0
	v_pk_mul_f32 v[72:73], v[72:73], v[154:155] op_sel_hi:[1,0]
	v_pk_mul_f32 v[80:81], v[80:81], v[154:155] op_sel_hi:[1,0]
	v_pk_mul_f32 v[82:83], v[82:83], v[154:155] op_sel_hi:[1,0]
	v_mul_f32_e32 v152, v162, v0
	v_add_u32_e32 v0, 0x20900, v3
	ds_read_b128 v[174:177], v0
	v_pk_mul_f32 v[72:73], v[140:141], v[72:73]
	v_pk_mul_f32 v[68:69], v[68:69], v[154:155] op_sel_hi:[1,0]
	v_pk_mul_f32 v[70:71], v[70:71], v[154:155] op_sel_hi:[1,0]
	v_pk_mul_f32 v[102:103], v[142:143], v[102:103]
	s_waitcnt lgkmcnt(0)
	v_mov_b32_e32 v0, v175
	v_mov_b32_e32 v1, v176
	v_mov_b32_e32 v175, v177
	v_pk_add_f32 v[0:1], v[0:1], v[174:175]
	v_pk_mul_f32 v[86:87], v[142:143], v[86:87]
	v_add_f32_e32 v0, v0, v1
	v_fmamk_f32 v0, v0, 0x3b800000, v213
	v_rsq_f32_e32 v0, v0
	v_pk_mul_f32 v[130:131], v[146:147], v[130:131]
	v_pk_mul_f32 v[74:75], v[74:75], v[154:155] op_sel_hi:[1,0]
	v_pk_mul_f32 v[122:123], v[142:143], v[122:123]
	v_mul_f32_e32 v150, v164, v0
	v_add_u32_e32 v0, 0x20a00, v3
	ds_read_b128 v[162:165], v0
	v_pk_mul_f32 v[56:57], v[56:57], v[150:151] op_sel_hi:[1,0]
	v_pk_mul_f32 v[20:21], v[20:21], v[150:151] op_sel_hi:[1,0]
	v_pk_mul_f32 v[22:23], v[22:23], v[150:151] op_sel_hi:[1,0]
	v_pk_mul_f32 v[56:57], v[136:137], v[56:57]
	s_waitcnt lgkmcnt(0)
	v_mov_b32_e32 v0, v163
	v_mov_b32_e32 v1, v164
	v_mov_b32_e32 v163, v165
	v_pk_add_f32 v[0:1], v[0:1], v[162:163]
	v_pk_mul_f32 v[22:23], v[142:143], v[22:23]
	v_add_f32_e32 v0, v0, v1
	v_fmamk_f32 v0, v0, 0x3b800000, v213
	v_rsq_f32_e32 v0, v0
	v_pk_mul_f32 v[20:21], v[140:141], v[20:21]
	v_pk_mul_f32 v[16:17], v[16:17], v[150:151] op_sel_hi:[1,0]
	v_pk_mul_f32 v[18:19], v[18:19], v[150:151] op_sel_hi:[1,0]
	v_mul_f32_e32 v148, v166, v0
	v_add_u32_e32 v0, 0x20b00, v3
	ds_read_b128 v[162:165], v0
	v_mov_b32_e32 v3, v217
	v_pk_mul_f32 v[48:49], v[48:49], v[148:149] op_sel_hi:[1,0]
	v_and_b32_e32 v153, 48, v3
	s_waitcnt lgkmcnt(0)
	v_mov_b32_e32 v0, v163
	v_mov_b32_e32 v1, v164
	v_mov_b32_e32 v163, v165
	v_pk_add_f32 v[0:1], v[0:1], v[162:163]
	v_pk_mul_f32 v[162:163], v[138:139], v[126:127]
	v_pk_mul_f32 v[126:127], v[136:137], v[124:125]
	v_cvt_pk_bf16_f32 v124, v128, v129
	v_pk_mul_f32 v[128:129], v[134:135], v[118:119]
	v_pk_mul_f32 v[118:119], v[132:133], v[116:117]
	v_cvt_pk_bf16_f32 v116, v120, v121
	v_pk_mul_f32 v[120:121], v[138:139], v[110:111]
	v_pk_mul_f32 v[110:111], v[136:137], v[108:109]
	v_cvt_pk_bf16_f32 v108, v112, v113
	v_pk_mul_f32 v[112:113], v[134:135], v[94:95]
	v_pk_mul_f32 v[94:95], v[132:133], v[92:93]
	v_cvt_pk_bf16_f32 v92, v100, v101
	v_pk_mul_f32 v[100:101], v[104:105], v[156:157] op_sel_hi:[1,0]
	v_add_f32_e32 v0, v0, v1
	v_pk_mul_f32 v[100:101], v[144:145], v[100:101]
	v_fmamk_f32 v0, v0, 0x3b800000, v213
	v_pk_mul_f32 v[104:105], v[138:139], v[98:99]
	v_pk_mul_f32 v[98:99], v[136:137], v[96:97]
	v_cvt_pk_bf16_f32 v96, v100, v101
	v_pk_mul_f32 v[100:101], v[134:135], v[78:79]
	v_pk_mul_f32 v[78:79], v[132:133], v[76:77]
	v_cvt_pk_bf16_f32 v76, v84, v85
	v_pk_mul_f32 v[84:85], v[88:89], v[154:155] op_sel_hi:[1,0]
	v_pk_mul_f32 v[64:65], v[64:65], v[152:153] op_sel_hi:[1,0]
	v_pk_mul_f32 v[12:13], v[12:13], v[152:153] op_sel_hi:[1,0]
	v_pk_mul_f32 v[14:15], v[14:15], v[152:153] op_sel_hi:[1,0]
	v_rsq_f32_e32 v0, v0
	v_pk_mul_f32 v[84:85], v[144:145], v[84:85]
	v_pk_mul_f32 v[64:65], v[144:145], v[64:65]
	v_pk_mul_f32 v[4:5], v[4:5], v[152:153] op_sel_hi:[1,0]
	v_pk_mul_f32 v[6:7], v[6:7], v[152:153] op_sel_hi:[1,0]
	v_pk_mul_f32 v[14:15], v[142:143], v[14:15]
	v_pk_mul_f32 v[12:13], v[140:141], v[12:13]
	v_pk_mul_f32 v[8:9], v[8:9], v[152:153] op_sel_hi:[1,0]
	v_pk_mul_f32 v[10:11], v[10:11], v[152:153] op_sel_hi:[1,0]
	v_pk_mul_f32 v[88:89], v[138:139], v[82:83]
	v_pk_mul_f32 v[82:83], v[136:137], v[80:81]
	v_cvt_pk_bf16_f32 v80, v84, v85
	v_pk_mul_f32 v[84:85], v[134:135], v[70:71]
	v_pk_mul_f32 v[70:71], v[132:133], v[68:69]
	v_cvt_pk_bf16_f32 v68, v72, v73
	v_pk_mul_f32 v[72:73], v[138:139], v[6:7]
	v_pk_mul_f32 v[6:7], v[136:137], v[4:5]
	v_cvt_pk_bf16_f32 v4, v64, v65
	v_pk_mul_f32 v[64:65], v[134:135], v[10:11]
	v_pk_mul_f32 v[10:11], v[132:133], v[8:9]
	v_cvt_pk_bf16_f32 v8, v12, v13
	v_cvt_pk_bf16_f32 v9, v14, v15
	v_pk_mul_f32 v[12:13], v[60:61], v[150:151] op_sel_hi:[1,0]
	v_pk_mul_f32 v[14:15], v[62:63], v[150:151] op_sel_hi:[1,0]
	v_pk_mul_f32 v[12:13], v[144:145], v[12:13]
	v_pk_mul_f32 v[14:15], v[146:147], v[14:15]
	v_cvt_pk_bf16_f32 v12, v12, v13
	v_cvt_pk_bf16_f32 v13, v14, v15
	v_cvt_pk_bf16_f32 v14, v56, v57
	v_pk_mul_f32 v[56:57], v[134:135], v[18:19]
	v_pk_mul_f32 v[18:19], v[132:133], v[16:17]
	v_cvt_pk_bf16_f32 v16, v20, v21
	v_cvt_pk_bf16_f32 v17, v22, v23
	v_pk_mul_f32 v[20:21], v[52:53], v[148:149] op_sel_hi:[1,0]
	v_pk_mul_f32 v[22:23], v[54:55], v[148:149] op_sel_hi:[1,0]
	v_pk_mul_f32 v[28:29], v[28:29], v[148:149] op_sel_hi:[1,0]
	v_pk_mul_f32 v[30:31], v[30:31], v[148:149] op_sel_hi:[1,0]
	v_mul_f32_e32 v0, v168, v0
	v_pk_mul_f32 v[22:23], v[146:147], v[22:23]
	v_pk_mul_f32 v[20:21], v[144:145], v[20:21]
	v_pk_mul_f32 v[48:49], v[136:137], v[48:49]
	v_pk_mul_f32 v[30:31], v[142:143], v[30:31]
	v_pk_mul_f32 v[28:29], v[140:141], v[28:29]
	v_pk_mul_f32 v[24:25], v[24:25], v[148:149] op_sel_hi:[1,0]
	v_pk_mul_f32 v[26:27], v[26:27], v[148:149] op_sel_hi:[1,0]
	v_cvt_pk_bf16_f32 v20, v20, v21
	v_cvt_pk_bf16_f32 v21, v22, v23
	v_cvt_pk_bf16_f32 v22, v48, v49
	v_pk_mul_f32 v[48:49], v[134:135], v[26:27]
	v_pk_mul_f32 v[26:27], v[132:133], v[24:25]
	v_cvt_pk_bf16_f32 v24, v28, v29
	v_cvt_pk_bf16_f32 v25, v30, v31
	v_pk_mul_f32 v[28:29], v[44:45], v[0:1] op_sel_hi:[1,0]
	v_pk_mul_f32 v[30:31], v[46:47], v[0:1] op_sel_hi:[1,0]
	v_pk_mul_f32 v[40:41], v[40:41], v[0:1] op_sel_hi:[1,0]
	v_pk_mul_f32 v[42:43], v[42:43], v[0:1] op_sel_hi:[1,0]
	v_pk_mul_f32 v[36:37], v[36:37], v[0:1] op_sel_hi:[1,0]
	v_pk_mul_f32 v[38:39], v[38:39], v[0:1] op_sel_hi:[1,0]
	v_pk_mul_f32 v[32:33], v[32:33], v[0:1] op_sel_hi:[1,0]
	v_pk_mul_f32 v[0:1], v[34:35], v[0:1] op_sel_hi:[1,0]
	v_readfirstlane_b32 s7, v3
	v_pk_mul_f32 v[0:1], v[134:135], v[0:1]
	v_pk_mul_f32 v[34:35], v[132:133], v[32:33]
	s_ashr_i32 s8, s7, 2
	v_pk_mul_f32 v[36:37], v[140:141], v[36:37]
	v_cvt_pk_bf16_f32 v34, v34, v35
	v_cvt_pk_bf16_f32 v35, v0, v1
	v_bfi_b32 v1, -16, s8, v3
	v_cvt_pk_bf16_f32 v32, v36, v37
	v_mul_lo_u32 v36, v1, s16
	v_add3_u32 v175, 0, v36, v153
	v_ashrrev_i32_e32 v36, 3, v3
	v_pk_mul_f32 v[30:31], v[146:147], v[30:31]
	v_pk_mul_f32 v[28:29], v[144:145], v[28:29]
	v_pk_mul_f32 v[40:41], v[136:137], v[40:41]
	v_pk_mul_f32 v[38:39], v[142:143], v[38:39]
	v_ashrrev_i32_e32 v37, 31, v36
	v_cvt_pk_bf16_f32 v28, v28, v29
	v_cvt_pk_bf16_f32 v29, v30, v31
	v_cvt_pk_bf16_f32 v30, v40, v41
	v_cvt_pk_bf16_f32 v33, v38, v39
	v_and_b32_e32 v38, 15, v3
	v_bfe_u32 v39, v3, 4, 2
	v_lshlrev_b64 v[44:45], 13, v[36:37]
	v_lshlrev_b32_e32 v37, 3, v3
	v_lshlrev_b32_e32 v40, 4, v3
	v_bfe_u32 v3, v3, 2, 2
	v_mul_lo_u32 v36, v36, s16
	v_and_b32_e32 v180, 0x70, v40
	v_lshl_or_b32 v3, v39, 2, v3
	s_ashr_i32 s7, s6, 31
	s_lshl_b32 s8, s53, 8
	v_add3_u32 v170, s10, v36, v180
	v_mul_u32_u24_e32 v38, 0x210, v38
	v_add3_u32 v168, s11, v36, v180
	v_mul_u32_u24_e32 v3, 0x210, v3
	v_and_b32_e32 v36, 24, v37
	s_lshl_b64 s[12:13], s[6:7], 21
	s_ashr_i32 s9, s8, 31
	v_add3_u32 v174, s10, v153, v38
	v_add3_u32 v173, s11, v153, v38
	v_add3_u32 v169, s10, v3, v36
	v_add3_u32 v3, s11, v3, v36
	s_lshl_b64 s[10:11], s[6:7], 22
	s_add_u32 s12, s60, s12
	s_addc_u32 s13, s61, s13
	v_lshl_add_u64 v[44:45], s[12:13], 0, v[44:45]
	s_lshl_b32 s12, s0, 11
	s_ashr_i32 s13, s12, 31
	v_cvt_pk_bf16_f32 v93, v102, v103
	v_pk_mul_f32 v[102:103], v[106:107], v[156:157] op_sel_hi:[1,0]
	v_cvt_pk_bf16_f32 v77, v86, v87
	v_pk_mul_f32 v[86:87], v[90:91], v[154:155] op_sel_hi:[1,0]
	v_mul_lo_u32 v36, v149, s16
	v_lshl_add_u64 v[44:45], s[12:13], 1, v[44:45]
	s_lshl_b64 s[8:9], s[8:9], 1
	v_cvt_pk_bf16_f32 v125, v130, v131
	v_cvt_pk_bf16_f32 v126, v126, v127
	v_cvt_pk_bf16_f32 v127, v162, v163
	v_pk_mul_f32 v[114:115], v[146:147], v[114:115]
	v_pk_mul_f32 v[102:103], v[146:147], v[102:103]
	v_pk_mul_f32 v[86:87], v[146:147], v[86:87]
	v_pk_mul_f32 v[74:75], v[142:143], v[74:75]
	v_add3_u32 v176, s15, v151, v36
	v_lshl_add_u64 v[44:45], v[44:45], 0, s[8:9]
	v_cvt_pk_bf16_f32 v117, v122, v123
	v_cvt_pk_bf16_f32 v118, v118, v119
	v_cvt_pk_bf16_f32 v119, v128, v129
	v_cvt_pk_bf16_f32 v109, v114, v115
	v_cvt_pk_bf16_f32 v110, v110, v111
	v_cvt_pk_bf16_f32 v111, v120, v121
	v_cvt_pk_bf16_f32 v94, v94, v95
	v_cvt_pk_bf16_f32 v95, v112, v113
	v_cvt_pk_bf16_f32 v97, v102, v103
	v_cvt_pk_bf16_f32 v98, v98, v99
	v_cvt_pk_bf16_f32 v99, v104, v105
	v_cvt_pk_bf16_f32 v78, v78, v79
	v_cvt_pk_bf16_f32 v79, v100, v101
	v_cvt_pk_bf16_f32 v81, v86, v87
	v_cvt_pk_bf16_f32 v82, v82, v83
	v_cvt_pk_bf16_f32 v83, v88, v89
	v_cvt_pk_bf16_f32 v69, v74, v75
	v_cvt_pk_bf16_f32 v70, v70, v71
	v_cvt_pk_bf16_f32 v71, v84, v85
	s_waitcnt lgkmcnt(0)
	s_barrier
	ds_write_b128 v176, v[124:127]
	ds_write_b128 v176, v[116:119] offset:256
	ds_write_b128 v176, v[108:111] offset:8448
	ds_write_b128 v176, v[92:95] offset:8704
	ds_write_b128 v176, v[96:99] offset:16896
	ds_write_b128 v176, v[76:79] offset:17152
	ds_write_b128 v176, v[80:83] offset:25344
	ds_write_b128 v176, v[68:71] offset:25600
	v_lshl_add_u64 v[166:167], v[44:45], 0, v[180:181]
	s_mov_b32 s7, 0x80000
	v_pk_mul_f32 v[66:67], v[66:67], v[152:153] op_sel_hi:[1,0]
	v_pk_mul_f32 v[58:59], v[58:59], v[150:151] op_sel_hi:[1,0]
	v_pk_mul_f32 v[50:51], v[50:51], v[148:149] op_sel_hi:[1,0]
	v_pk_mul_f32 v[42:43], v[138:139], v[42:43]
	s_waitcnt lgkmcnt(0)
	s_barrier
	v_add_co_u32_e32 v164, vcc, s7, v166
	v_pk_mul_f32 v[66:67], v[146:147], v[66:67]
	v_pk_mul_f32 v[58:59], v[138:139], v[58:59]
	v_pk_mul_f32 v[50:51], v[138:139], v[50:51]
	v_cvt_pk_bf16_f32 v31, v42, v43
	v_lshlrev_b32_e32 v0, 3, v39
	ds_read_b128 v[124:127], v175
	ds_read_b128 v[120:123], v175 offset:64
	ds_read_b128 v[116:119], v175 offset:128
	ds_read_b128 v[108:111], v175 offset:192
	ds_read_b128 v[80:83], v175 offset:256
	ds_read_b128 v[76:79], v175 offset:320
	ds_read_b128 v[40:43], v175 offset:384
	ds_read_b128 v[36:39], v175 offset:448
	global_load_dwordx4 v[60:63], v[166:167], off
	v_addc_co_u32_e32 v165, vcc, 0, v167, vcc
	v_cvt_pk_bf16_f32 v5, v66, v67
	v_cvt_pk_bf16_f32 v6, v6, v7
	v_cvt_pk_bf16_f32 v7, v72, v73
	v_cvt_pk_bf16_f32 v10, v10, v11
	v_cvt_pk_bf16_f32 v11, v64, v65
	v_cvt_pk_bf16_f32 v15, v58, v59
	v_cvt_pk_bf16_f32 v18, v18, v19
	v_cvt_pk_bf16_f32 v19, v56, v57
	v_cvt_pk_bf16_f32 v23, v50, v51
	v_cvt_pk_bf16_f32 v26, v26, v27
	v_cvt_pk_bf16_f32 v27, v48, v49
	global_load_dwordx4 v[44:47], v[164:165], off
	global_load_dwordx4 v[64:67], v[166:167], off offset:128
	global_load_dwordx4 v[48:51], v[164:165], off offset:128
	global_load_dwordx4 v[68:71], v[166:167], off offset:256
	global_load_dwordx4 v[52:55], v[164:165], off offset:256
	global_load_dwordx4 v[72:75], v[166:167], off offset:384
	global_load_dwordx4 v[56:59], v[164:165], off offset:384
	s_mov_b32 s7, 0x100000
	v_add_co_u32_e32 v162, vcc, s7, v166
	s_waitcnt vmcnt(7)
	ds_write_b128 v170, v[60:63]
	s_waitcnt vmcnt(5)
	ds_write_b128 v170, v[64:67] offset:128
	s_waitcnt vmcnt(3)
	ds_write_b128 v170, v[68:71] offset:256
	s_waitcnt vmcnt(1)
	ds_write_b128 v170, v[72:75] offset:384
	v_addc_co_u32_e32 v163, vcc, 0, v167, vcc
	global_load_dwordx4 v[60:63], v[162:163], off
	global_load_dwordx4 v[64:67], v[162:163], off offset:128
	global_load_dwordx4 v[68:71], v[162:163], off offset:256
	global_load_dwordx4 v[72:75], v[162:163], off offset:384
	s_waitcnt lgkmcnt(0)
	s_barrier
	ds_read_b128 v[204:207], v174
	ds_read_b128 v[208:211], v174 offset:8448
	ds_read_b128 v[218:221], v174 offset:16896
	ds_read_b128 v[224:227], v174 offset:25344
	ds_read_b128 v[228:231], v174 offset:64
	ds_read_b128 v[232:235], v174 offset:8512
	ds_read_b128 v[236:239], v174 offset:16960
	ds_read_b128 v[240:243], v174 offset:25408
	s_waitcnt lgkmcnt(7)
	v_mfma_f32_16x16x32_bf16 v[84:87], v[204:207], v[124:127], 0
	ds_read_b128 v[204:207], v174 offset:128
	s_waitcnt lgkmcnt(7)
	v_mfma_f32_16x16x32_bf16 v[88:91], v[208:211], v[124:127], 0
	ds_read_b128 v[208:211], v174 offset:8576
	s_mov_b32 s7, 0x180000
	v_add_co_u32_e32 v160, vcc, s7, v166
	s_nop 1
	s_waitcnt lgkmcnt(7)
	v_mfma_f32_16x16x32_bf16 v[92:95], v[218:221], v[124:127], 0
	ds_read_b128 v[218:221], v174 offset:17024
	v_addc_co_u32_e32 v161, vcc, 0, v167, vcc
	s_nop 1
	s_waitcnt lgkmcnt(7)
	v_mfma_f32_16x16x32_bf16 v[96:99], v[224:227], v[124:127], 0
	ds_read_b128 v[224:227], v174 offset:25472
	s_mov_b32 s7, 0xf149f2ca
	s_waitcnt lgkmcnt(7)
	v_mfma_f32_16x16x32_bf16 v[84:87], v[228:231], v[120:123], v[84:87]
	ds_read_b128 v[228:231], v174 offset:192
	s_waitcnt lgkmcnt(7)
	v_mfma_f32_16x16x32_bf16 v[88:91], v[232:235], v[120:123], v[88:91]
	ds_read_b128 v[232:235], v174 offset:8640
	s_waitcnt lgkmcnt(7)
	v_mfma_f32_16x16x32_bf16 v[92:95], v[236:239], v[120:123], v[92:95]
	ds_read_b128 v[236:239], v174 offset:17088
	s_waitcnt lgkmcnt(7)
	v_mfma_f32_16x16x32_bf16 v[96:99], v[240:243], v[120:123], v[96:99]
	ds_read_b128 v[240:243], v174 offset:25536
	s_waitcnt lgkmcnt(7)
	v_mfma_f32_16x16x32_bf16 v[84:87], v[204:207], v[116:119], v[84:87]
	ds_read_b128 v[204:207], v174 offset:256
	s_waitcnt lgkmcnt(7)
	v_mfma_f32_16x16x32_bf16 v[88:91], v[208:211], v[116:119], v[88:91]
	ds_read_b128 v[208:211], v174 offset:8704
	s_waitcnt lgkmcnt(7)
	v_mfma_f32_16x16x32_bf16 v[92:95], v[218:221], v[116:119], v[92:95]
	ds_read_b128 v[218:221], v174 offset:17152
	s_waitcnt lgkmcnt(7)
	v_mfma_f32_16x16x32_bf16 v[96:99], v[224:227], v[116:119], v[96:99]
	ds_read_b128 v[224:227], v174 offset:25600
	s_waitcnt lgkmcnt(7)
	v_mfma_f32_16x16x32_bf16 v[84:87], v[228:231], v[108:111], v[84:87]
	ds_read_b128 v[228:231], v174 offset:320
	s_waitcnt lgkmcnt(7)
	v_mfma_f32_16x16x32_bf16 v[88:91], v[232:235], v[108:111], v[88:91]
	ds_read_b128 v[232:235], v174 offset:8768
	s_waitcnt lgkmcnt(7)
	v_mfma_f32_16x16x32_bf16 v[92:95], v[236:239], v[108:111], v[92:95]
	ds_read_b128 v[236:239], v174 offset:17216
	s_waitcnt lgkmcnt(7)
	v_mfma_f32_16x16x32_bf16 v[96:99], v[240:243], v[108:111], v[96:99]
	ds_read_b128 v[240:243], v174 offset:25664
	s_waitcnt lgkmcnt(7)
	v_mfma_f32_16x16x32_bf16 v[84:87], v[204:207], v[80:83], v[84:87]
	ds_read_b128 v[204:207], v174 offset:384
	s_waitcnt lgkmcnt(7)
	v_mfma_f32_16x16x32_bf16 v[88:91], v[208:211], v[80:83], v[88:91]
	ds_read_b128 v[208:211], v174 offset:8832
	s_waitcnt lgkmcnt(7)
	v_mfma_f32_16x16x32_bf16 v[92:95], v[218:221], v[80:83], v[92:95]
	ds_read_b128 v[218:221], v174 offset:17280
	s_waitcnt lgkmcnt(7)
	v_mfma_f32_16x16x32_bf16 v[96:99], v[224:227], v[80:83], v[96:99]
	ds_read_b128 v[224:227], v174 offset:25728
	s_waitcnt lgkmcnt(7)
	v_mfma_f32_16x16x32_bf16 v[84:87], v[228:231], v[76:79], v[84:87]
	ds_read_b128 v[228:231], v174 offset:448
	s_waitcnt lgkmcnt(7)
	v_mfma_f32_16x16x32_bf16 v[88:91], v[232:235], v[76:79], v[88:91]
	ds_read_b128 v[232:235], v174 offset:8896
	s_waitcnt lgkmcnt(7)
	v_mfma_f32_16x16x32_bf16 v[92:95], v[236:239], v[76:79], v[92:95]
	ds_read_b128 v[236:239], v174 offset:17344
	s_waitcnt lgkmcnt(7)
	v_mfma_f32_16x16x32_bf16 v[96:99], v[240:243], v[76:79], v[96:99]
	s_waitcnt lgkmcnt(6)
	v_mfma_f32_16x16x32_bf16 v[84:87], v[204:207], v[40:43], v[84:87]
	s_waitcnt lgkmcnt(5)
	v_mfma_f32_16x16x32_bf16 v[88:91], v[208:211], v[40:43], v[88:91]
	s_waitcnt lgkmcnt(4)
	v_mfma_f32_16x16x32_bf16 v[92:95], v[218:221], v[40:43], v[92:95]
	s_waitcnt lgkmcnt(3)
	v_mfma_f32_16x16x32_bf16 v[96:99], v[224:227], v[40:43], v[96:99]
	s_waitcnt lgkmcnt(2)
	v_mfma_f32_16x16x32_bf16 v[84:87], v[228:231], v[36:39], v[84:87]
	s_waitcnt lgkmcnt(1)
	v_mfma_f32_16x16x32_bf16 v[88:91], v[232:235], v[36:39], v[88:91]
	s_waitcnt lgkmcnt(0)
	v_mfma_f32_16x16x32_bf16 v[92:95], v[236:239], v[36:39], v[92:95]
	s_nop 7
	ds_read_b128 v[100:103], v174 offset:25792
	ds_write_b128 v168, v[44:47]
	ds_write_b128 v168, v[48:51] offset:128
	ds_write_b128 v168, v[52:55] offset:256
	s_waitcnt vmcnt(4)
	ds_write_b128 v168, v[56:59] offset:384
	global_load_dwordx4 v[44:47], v[160:161], off
	global_load_dwordx4 v[48:51], v[160:161], off offset:128
	global_load_dwordx4 v[52:55], v[160:161], off offset:256
	global_load_dwordx4 v[56:59], v[160:161], off offset:384
	s_waitcnt lgkmcnt(0)
	s_barrier
	s_waitcnt lgkmcnt(4)
	v_mfma_f32_16x16x32_bf16 v[96:99], v[100:103], v[36:39], v[96:99]
	ds_read_b128 v[204:207], v173
	ds_read_b128 v[208:211], v173 offset:8448
	ds_read_b128 v[218:221], v173 offset:16896
	ds_read_b128 v[224:227], v173 offset:25344
	ds_read_b128 v[228:231], v173 offset:64
	ds_read_b128 v[232:235], v173 offset:8512
	ds_read_b128 v[236:239], v173 offset:16960
	ds_read_b128 v[240:243], v173 offset:25408
	s_waitcnt lgkmcnt(7)
	v_mfma_f32_16x16x32_bf16 v[100:103], v[204:207], v[124:127], 0
	ds_read_b128 v[204:207], v173 offset:128
	s_waitcnt lgkmcnt(7)
	v_mfma_f32_16x16x32_bf16 v[104:107], v[208:211], v[124:127], 0
	ds_read_b128 v[208:211], v173 offset:8576
	s_waitcnt lgkmcnt(7)
	v_mfma_f32_16x16x32_bf16 v[112:115], v[218:221], v[124:127], 0
	ds_read_b128 v[218:221], v173 offset:17024
	s_waitcnt lgkmcnt(7)
	v_mfma_f32_16x16x32_bf16 v[128:131], v[224:227], v[124:127], 0
	ds_read_b128 v[224:227], v173 offset:25472
	s_waitcnt lgkmcnt(7)
	v_mfma_f32_16x16x32_bf16 v[100:103], v[228:231], v[120:123], v[100:103]
	ds_read_b128 v[228:231], v173 offset:192
	s_waitcnt lgkmcnt(7)
	v_mfma_f32_16x16x32_bf16 v[104:107], v[232:235], v[120:123], v[104:107]
	ds_read_b128 v[232:235], v173 offset:8640
	s_waitcnt lgkmcnt(7)
	v_mfma_f32_16x16x32_bf16 v[112:115], v[236:239], v[120:123], v[112:115]
	ds_read_b128 v[236:239], v173 offset:17088
	s_waitcnt lgkmcnt(7)
	v_mfma_f32_16x16x32_bf16 v[128:131], v[240:243], v[120:123], v[128:131]
	ds_read_b128 v[240:243], v173 offset:25536
	s_waitcnt lgkmcnt(7)
	v_mfma_f32_16x16x32_bf16 v[100:103], v[204:207], v[116:119], v[100:103]
	ds_read_b128 v[204:207], v173 offset:256
	s_waitcnt lgkmcnt(7)
	v_mfma_f32_16x16x32_bf16 v[104:107], v[208:211], v[116:119], v[104:107]
	ds_read_b128 v[208:211], v173 offset:8704
	s_waitcnt lgkmcnt(7)
	v_mfma_f32_16x16x32_bf16 v[112:115], v[218:221], v[116:119], v[112:115]
	ds_read_b128 v[218:221], v173 offset:17152
	s_waitcnt lgkmcnt(7)
	v_mfma_f32_16x16x32_bf16 v[128:131], v[224:227], v[116:119], v[128:131]
	ds_read_b128 v[224:227], v173 offset:25600
	s_waitcnt lgkmcnt(7)
	v_mfma_f32_16x16x32_bf16 v[100:103], v[228:231], v[108:111], v[100:103]
	ds_read_b128 v[228:231], v173 offset:320
	s_waitcnt lgkmcnt(7)
	v_mfma_f32_16x16x32_bf16 v[104:107], v[232:235], v[108:111], v[104:107]
	ds_read_b128 v[232:235], v173 offset:8768
	s_waitcnt lgkmcnt(7)
	v_mfma_f32_16x16x32_bf16 v[112:115], v[236:239], v[108:111], v[112:115]
	ds_read_b128 v[236:239], v173 offset:17216
	s_waitcnt lgkmcnt(7)
	v_mfma_f32_16x16x32_bf16 v[128:131], v[240:243], v[108:111], v[128:131]
	ds_read_b128 v[240:243], v173 offset:25664
	s_waitcnt lgkmcnt(7)
	v_mfma_f32_16x16x32_bf16 v[100:103], v[204:207], v[80:83], v[100:103]
	ds_read_b128 v[204:207], v173 offset:384
	s_waitcnt lgkmcnt(7)
	v_mfma_f32_16x16x32_bf16 v[104:107], v[208:211], v[80:83], v[104:107]
	ds_read_b128 v[208:211], v173 offset:8832
	s_waitcnt lgkmcnt(7)
	v_mfma_f32_16x16x32_bf16 v[112:115], v[218:221], v[80:83], v[112:115]
	ds_read_b128 v[218:221], v173 offset:17280
	s_waitcnt lgkmcnt(7)
	v_mfma_f32_16x16x32_bf16 v[128:131], v[224:227], v[80:83], v[128:131]
	ds_read_b128 v[224:227], v173 offset:25728
	s_waitcnt lgkmcnt(7)
	v_mfma_f32_16x16x32_bf16 v[100:103], v[228:231], v[76:79], v[100:103]
	ds_read_b128 v[228:231], v173 offset:448
	s_waitcnt lgkmcnt(7)
	v_mfma_f32_16x16x32_bf16 v[104:107], v[232:235], v[76:79], v[104:107]
	ds_read_b128 v[232:235], v173 offset:8896
	s_waitcnt lgkmcnt(7)
	v_mfma_f32_16x16x32_bf16 v[112:115], v[236:239], v[76:79], v[112:115]
	ds_read_b128 v[236:239], v173 offset:17344
	s_waitcnt lgkmcnt(7)
	v_mfma_f32_16x16x32_bf16 v[128:131], v[240:243], v[76:79], v[128:131]
	s_waitcnt lgkmcnt(6)
	v_mfma_f32_16x16x32_bf16 v[100:103], v[204:207], v[40:43], v[100:103]
	s_waitcnt lgkmcnt(5)
	v_mfma_f32_16x16x32_bf16 v[104:107], v[208:211], v[40:43], v[104:107]
	s_waitcnt lgkmcnt(4)
	v_mfma_f32_16x16x32_bf16 v[112:115], v[218:221], v[40:43], v[112:115]
	s_waitcnt lgkmcnt(3)
	v_mfma_f32_16x16x32_bf16 v[128:131], v[224:227], v[40:43], v[128:131]
	s_waitcnt lgkmcnt(2)
	v_mfma_f32_16x16x32_bf16 v[100:103], v[228:231], v[36:39], v[100:103]
	s_waitcnt lgkmcnt(1)
	v_mfma_f32_16x16x32_bf16 v[104:107], v[232:235], v[36:39], v[104:107]
	s_waitcnt lgkmcnt(0)
	v_mfma_f32_16x16x32_bf16 v[112:115], v[236:239], v[36:39], v[112:115]
	s_nop 7
	ds_read_b128 v[132:135], v173 offset:25792
	s_waitcnt vmcnt(7)
	ds_write_b128 v170, v[60:63]
	s_waitcnt vmcnt(6)
	ds_write_b128 v170, v[64:67] offset:128
	s_waitcnt vmcnt(5)
	ds_write_b128 v170, v[68:71] offset:256
	s_waitcnt vmcnt(4)
	ds_write_b128 v170, v[72:75] offset:384
	global_load_dwordx4 v[60:63], v[166:167], off offset:2048
	global_load_dwordx4 v[64:67], v[166:167], off offset:2176
	global_load_dwordx4 v[68:71], v[166:167], off offset:2304
	global_load_dwordx4 v[72:75], v[166:167], off offset:2432
	s_waitcnt lgkmcnt(0)
	s_barrier
	s_waitcnt lgkmcnt(4)
	v_mfma_f32_16x16x32_bf16 v[128:131], v[132:135], v[36:39], v[128:131]
	ds_read_b128 v[204:207], v174
	ds_read_b128 v[208:211], v174 offset:8448
	ds_read_b128 v[218:221], v174 offset:16896
	ds_read_b128 v[224:227], v174 offset:25344
	ds_read_b128 v[228:231], v174 offset:64
	ds_read_b128 v[232:235], v174 offset:8512
	ds_read_b128 v[236:239], v174 offset:16960
	ds_read_b128 v[240:243], v174 offset:25408
	s_waitcnt lgkmcnt(7)
	v_mfma_f32_16x16x32_bf16 v[132:135], v[204:207], v[124:127], 0
	ds_read_b128 v[204:207], v174 offset:128
	s_waitcnt lgkmcnt(7)
	v_mfma_f32_16x16x32_bf16 v[136:139], v[208:211], v[124:127], 0
	ds_read_b128 v[208:211], v174 offset:8576
	s_waitcnt lgkmcnt(7)
	v_mfma_f32_16x16x32_bf16 v[140:143], v[218:221], v[124:127], 0
	ds_read_b128 v[218:221], v174 offset:17024
	s_waitcnt lgkmcnt(7)
	v_mfma_f32_16x16x32_bf16 v[144:147], v[224:227], v[124:127], 0
	ds_read_b128 v[224:227], v174 offset:25472
	s_waitcnt lgkmcnt(7)
	v_mfma_f32_16x16x32_bf16 v[132:135], v[228:231], v[120:123], v[132:135]
	ds_read_b128 v[228:231], v174 offset:192
	s_waitcnt lgkmcnt(7)
	v_mfma_f32_16x16x32_bf16 v[136:139], v[232:235], v[120:123], v[136:139]
	ds_read_b128 v[232:235], v174 offset:8640
	s_waitcnt lgkmcnt(7)
	v_mfma_f32_16x16x32_bf16 v[140:143], v[236:239], v[120:123], v[140:143]
	ds_read_b128 v[236:239], v174 offset:17088
	s_waitcnt lgkmcnt(7)
	v_mfma_f32_16x16x32_bf16 v[144:147], v[240:243], v[120:123], v[144:147]
	ds_read_b128 v[240:243], v174 offset:25536
	s_waitcnt lgkmcnt(7)
	v_mfma_f32_16x16x32_bf16 v[132:135], v[204:207], v[116:119], v[132:135]
	ds_read_b128 v[204:207], v174 offset:256
	s_waitcnt lgkmcnt(7)
	v_mfma_f32_16x16x32_bf16 v[136:139], v[208:211], v[116:119], v[136:139]
	ds_read_b128 v[208:211], v174 offset:8704
	s_waitcnt lgkmcnt(7)
	v_mfma_f32_16x16x32_bf16 v[140:143], v[218:221], v[116:119], v[140:143]
	ds_read_b128 v[218:221], v174 offset:17152
	s_waitcnt lgkmcnt(7)
	v_mfma_f32_16x16x32_bf16 v[144:147], v[224:227], v[116:119], v[144:147]
	ds_read_b128 v[224:227], v174 offset:25600
	s_waitcnt lgkmcnt(7)
	v_mfma_f32_16x16x32_bf16 v[132:135], v[228:231], v[108:111], v[132:135]
	ds_read_b128 v[228:231], v174 offset:320
	s_waitcnt lgkmcnt(7)
	v_mfma_f32_16x16x32_bf16 v[136:139], v[232:235], v[108:111], v[136:139]
	ds_read_b128 v[232:235], v174 offset:8768
	s_waitcnt lgkmcnt(7)
	v_mfma_f32_16x16x32_bf16 v[140:143], v[236:239], v[108:111], v[140:143]
	ds_read_b128 v[236:239], v174 offset:17216
	s_waitcnt lgkmcnt(7)
	v_mfma_f32_16x16x32_bf16 v[144:147], v[240:243], v[108:111], v[144:147]
	ds_read_b128 v[240:243], v174 offset:25664
	s_waitcnt lgkmcnt(7)
	v_mfma_f32_16x16x32_bf16 v[132:135], v[204:207], v[80:83], v[132:135]
	ds_read_b128 v[204:207], v174 offset:384
	s_waitcnt lgkmcnt(7)
	v_mfma_f32_16x16x32_bf16 v[136:139], v[208:211], v[80:83], v[136:139]
	ds_read_b128 v[208:211], v174 offset:8832
	s_waitcnt lgkmcnt(7)
	v_mfma_f32_16x16x32_bf16 v[140:143], v[218:221], v[80:83], v[140:143]
	ds_read_b128 v[218:221], v174 offset:17280
	s_waitcnt lgkmcnt(7)
	v_mfma_f32_16x16x32_bf16 v[144:147], v[224:227], v[80:83], v[144:147]
	ds_read_b128 v[224:227], v174 offset:25728
	s_waitcnt lgkmcnt(7)
	v_mfma_f32_16x16x32_bf16 v[132:135], v[228:231], v[76:79], v[132:135]
	ds_read_b128 v[228:231], v174 offset:448
	s_waitcnt lgkmcnt(7)
	v_mfma_f32_16x16x32_bf16 v[136:139], v[232:235], v[76:79], v[136:139]
	ds_read_b128 v[232:235], v174 offset:8896
	s_waitcnt lgkmcnt(7)
	v_mfma_f32_16x16x32_bf16 v[140:143], v[236:239], v[76:79], v[140:143]
	ds_read_b128 v[236:239], v174 offset:17344
	s_waitcnt lgkmcnt(7)
	v_mfma_f32_16x16x32_bf16 v[144:147], v[240:243], v[76:79], v[144:147]
	s_waitcnt lgkmcnt(6)
	v_mfma_f32_16x16x32_bf16 v[132:135], v[204:207], v[40:43], v[132:135]
	s_waitcnt lgkmcnt(5)
	v_mfma_f32_16x16x32_bf16 v[136:139], v[208:211], v[40:43], v[136:139]
	s_waitcnt lgkmcnt(4)
	v_mfma_f32_16x16x32_bf16 v[140:143], v[218:221], v[40:43], v[140:143]
	s_waitcnt lgkmcnt(3)
	v_mfma_f32_16x16x32_bf16 v[144:147], v[224:227], v[40:43], v[144:147]
	s_waitcnt lgkmcnt(2)
	v_mfma_f32_16x16x32_bf16 v[132:135], v[228:231], v[36:39], v[132:135]
	s_waitcnt lgkmcnt(1)
	v_mfma_f32_16x16x32_bf16 v[136:139], v[232:235], v[36:39], v[136:139]
	s_waitcnt lgkmcnt(0)
	v_mfma_f32_16x16x32_bf16 v[140:143], v[236:239], v[36:39], v[140:143]
	s_nop 7
	ds_read_b128 v[148:151], v174 offset:25792
	s_waitcnt vmcnt(7)
	ds_write_b128 v168, v[44:47]
	s_waitcnt vmcnt(6)
	ds_write_b128 v168, v[48:51] offset:128
	s_waitcnt vmcnt(5)
	ds_write_b128 v168, v[52:55] offset:256
	s_waitcnt vmcnt(4)
	ds_write_b128 v168, v[56:59] offset:384
	global_load_dwordx4 v[44:47], v[164:165], off offset:2048
	global_load_dwordx4 v[48:51], v[164:165], off offset:2176
	global_load_dwordx4 v[52:55], v[164:165], off offset:2304
	global_load_dwordx4 v[56:59], v[164:165], off offset:2432
	s_waitcnt lgkmcnt(0)
	s_barrier
	s_waitcnt lgkmcnt(4)
	v_mfma_f32_16x16x32_bf16 v[144:147], v[148:151], v[36:39], v[144:147]
	ds_read_b128 v[148:151], v173
	ds_read_b128 v[152:155], v173 offset:64
	ds_read_b128 v[156:159], v173 offset:8512
	s_waitcnt lgkmcnt(2)
	v_mfma_f32_16x16x32_bf16 v[148:151], v[148:151], v[124:127], 0
	ds_read_b128 v[190:193], v173 offset:16960
	s_waitcnt lgkmcnt(2)
	v_mfma_f32_16x16x32_bf16 v[148:151], v[152:155], v[120:123], v[148:151]
	ds_read_b128 v[152:155], v173 offset:128
	s_waitcnt lgkmcnt(0)
	v_mfma_f32_16x16x32_bf16 v[148:151], v[152:155], v[116:119], v[148:151]
	ds_read_b128 v[152:155], v173 offset:192
	s_waitcnt lgkmcnt(0)
	v_mfma_f32_16x16x32_bf16 v[148:151], v[152:155], v[108:111], v[148:151]
	ds_read_b128 v[152:155], v173 offset:256
	s_waitcnt lgkmcnt(0)
	v_mfma_f32_16x16x32_bf16 v[148:151], v[152:155], v[80:83], v[148:151]
	ds_read_b128 v[152:155], v173 offset:320
	s_waitcnt lgkmcnt(0)
	v_mfma_f32_16x16x32_bf16 v[148:151], v[152:155], v[76:79], v[148:151]
	ds_read_b128 v[152:155], v173 offset:384
	s_waitcnt lgkmcnt(0)
	v_mfma_f32_16x16x32_bf16 v[148:151], v[152:155], v[40:43], v[148:151]
	ds_read_b128 v[152:155], v173 offset:448
	s_waitcnt lgkmcnt(0)
	v_mfma_f32_16x16x32_bf16 v[148:151], v[152:155], v[36:39], v[148:151]
	ds_read_b128 v[152:155], v173 offset:8448
	s_waitcnt lgkmcnt(0)
	v_mfma_f32_16x16x32_bf16 v[152:155], v[152:155], v[124:127], 0
	v_mfma_f32_16x16x32_bf16 v[152:155], v[156:159], v[120:123], v[152:155]
	ds_read_b128 v[156:159], v173 offset:8576
	s_waitcnt lgkmcnt(0)
	v_mfma_f32_16x16x32_bf16 v[152:155], v[156:159], v[116:119], v[152:155]
	ds_read_b128 v[156:159], v173 offset:8640
	s_waitcnt lgkmcnt(0)
	v_mfma_f32_16x16x32_bf16 v[152:155], v[156:159], v[108:111], v[152:155]
	ds_read_b128 v[156:159], v173 offset:8704
	s_waitcnt lgkmcnt(0)
	v_mfma_f32_16x16x32_bf16 v[152:155], v[156:159], v[80:83], v[152:155]
	ds_read_b128 v[156:159], v173 offset:8768
	s_waitcnt lgkmcnt(0)
	v_mfma_f32_16x16x32_bf16 v[152:155], v[156:159], v[76:79], v[152:155]
	ds_read_b128 v[156:159], v173 offset:8832
	s_waitcnt lgkmcnt(0)
	v_mfma_f32_16x16x32_bf16 v[152:155], v[156:159], v[40:43], v[152:155]
	ds_read_b128 v[156:159], v173 offset:8896
	s_waitcnt lgkmcnt(0)
	v_mfma_f32_16x16x32_bf16 v[152:155], v[156:159], v[36:39], v[152:155]
	ds_read_b128 v[156:159], v173 offset:16896
	s_waitcnt lgkmcnt(0)
	v_mfma_f32_16x16x32_bf16 v[156:159], v[156:159], v[124:127], 0
	v_mfma_f32_16x16x32_bf16 v[156:159], v[190:193], v[120:123], v[156:159]
	ds_read_b128 v[190:193], v173 offset:17024
	s_waitcnt lgkmcnt(0)
	v_mfma_f32_16x16x32_bf16 v[156:159], v[190:193], v[116:119], v[156:159]
	ds_read_b128 v[190:193], v173 offset:17088
	s_waitcnt lgkmcnt(0)
	v_mfma_f32_16x16x32_bf16 v[156:159], v[190:193], v[108:111], v[156:159]
	ds_read_b128 v[190:193], v173 offset:17152
	s_waitcnt lgkmcnt(0)
	v_mfma_f32_16x16x32_bf16 v[156:159], v[190:193], v[80:83], v[156:159]
	ds_read_b128 v[190:193], v173 offset:17216
	s_waitcnt lgkmcnt(0)
	v_mfma_f32_16x16x32_bf16 v[156:159], v[190:193], v[76:79], v[156:159]
	ds_read_b128 v[190:193], v173 offset:17280
	s_waitcnt lgkmcnt(0)
	v_mfma_f32_16x16x32_bf16 v[156:159], v[190:193], v[40:43], v[156:159]
	ds_read_b128 v[190:193], v173 offset:17344
	s_waitcnt lgkmcnt(0)
	v_mfma_f32_16x16x32_bf16 v[156:159], v[190:193], v[36:39], v[156:159]
	ds_read_b128 v[190:193], v173 offset:25344
	s_waitcnt lgkmcnt(0)
	v_mfma_f32_16x16x32_bf16 v[124:127], v[190:193], v[124:127], 0
	ds_read_b128 v[190:193], v173 offset:25408
	s_waitcnt lgkmcnt(0)
	v_mfma_f32_16x16x32_bf16 v[120:123], v[190:193], v[120:123], v[124:127]
	s_nop 4
	ds_read_b128 v[124:127], v173 offset:25472
	s_waitcnt lgkmcnt(0)
	v_mfma_f32_16x16x32_bf16 v[116:119], v[124:127], v[116:119], v[120:123]
	s_nop 2
	ds_read_b128 v[120:123], v173 offset:25536
	s_waitcnt lgkmcnt(0)
	v_mfma_f32_16x16x32_bf16 v[108:111], v[120:123], v[108:111], v[116:119]
	s_nop 2
	ds_read_b128 v[116:119], v173 offset:25600
	s_waitcnt lgkmcnt(0)
	v_mfma_f32_16x16x32_bf16 v[80:83], v[116:119], v[80:83], v[108:111]
	s_nop 2
	ds_read_b128 v[108:111], v173 offset:25664
	s_waitcnt lgkmcnt(0)
	v_mfma_f32_16x16x32_bf16 v[76:79], v[108:111], v[76:79], v[80:83]
	s_nop 2
	ds_read_b128 v[80:83], v173 offset:25728
	s_waitcnt lgkmcnt(0)
	v_mfma_f32_16x16x32_bf16 v[40:43], v[80:83], v[40:43], v[76:79]
	s_nop 2
	ds_read_b128 v[76:79], v173 offset:25792
	s_waitcnt vmcnt(7)
	ds_write_b128 v170, v[60:63]
	s_waitcnt vmcnt(6)
	ds_write_b128 v170, v[64:67] offset:128
	s_waitcnt vmcnt(5)
	ds_write_b128 v170, v[68:71] offset:256
	s_waitcnt vmcnt(4)
	ds_write_b128 v170, v[72:75] offset:384
	global_load_dwordx4 v[60:63], v[162:163], off offset:2048
	global_load_dwordx4 v[64:67], v[162:163], off offset:2176
	global_load_dwordx4 v[68:71], v[162:163], off offset:2304
	global_load_dwordx4 v[72:75], v[162:163], off offset:2432
	s_waitcnt lgkmcnt(4)
	v_mfma_f32_16x16x32_bf16 v[36:39], v[76:79], v[36:39], v[40:43]
	s_nop 2
	v_max_f32_e32 v40, v87, v87
	v_max_f32_e32 v41, v86, v86
	v_max_f32_e32 v40, v41, v40
	v_max_f32_e32 v41, v91, v91
	v_max_f32_e32 v42, v90, v90
	v_max_f32_e32 v41, v42, v41
	v_max3_f32 v40, v84, v85, v40
	v_max3_f32 v41, v88, v89, v41
	v_max3_f32 v40, v40, s7, v41
	v_max_f32_e32 v41, v95, v95
	v_max_f32_e32 v42, v94, v94
	v_max_f32_e32 v41, v42, v41
	v_max_f32_e32 v42, v99, v99
	v_max_f32_e32 v43, v98, v98
	v_max_f32_e32 v42, v43, v42
	v_max3_f32 v41, v92, v93, v41
	v_max3_f32 v42, v96, v97, v42
	v_max3_f32 v40, v40, v41, v42
	v_max_f32_e32 v41, v103, v103
	v_max_f32_e32 v42, v102, v102
	v_max_f32_e32 v41, v42, v41
	v_max_f32_e32 v42, v107, v107
	v_max_f32_e32 v43, v106, v106
	v_max_f32_e32 v42, v43, v42
	v_max3_f32 v41, v100, v101, v41
	v_max3_f32 v42, v104, v105, v42
	v_max3_f32 v40, v40, v41, v42
	v_max_f32_e32 v41, v115, v115
	v_max_f32_e32 v42, v114, v114
	v_max_f32_e32 v41, v42, v41
	v_max_f32_e32 v42, v131, v131
	v_max_f32_e32 v43, v130, v130
	v_max_f32_e32 v42, v43, v42
	v_max3_f32 v41, v112, v113, v41
	v_max3_f32 v42, v128, v129, v42
	v_max3_f32 v40, v40, v41, v42
	v_max_f32_e32 v41, v135, v135
	v_max_f32_e32 v42, v134, v134
	v_max_f32_e32 v41, v42, v41
	v_max_f32_e32 v42, v139, v139
	v_max_f32_e32 v43, v138, v138
	v_max_f32_e32 v42, v43, v42
	v_max3_f32 v41, v132, v133, v41
	v_max3_f32 v42, v136, v137, v42
	v_max3_f32 v40, v40, v41, v42
	v_max_f32_e32 v41, v143, v143
	v_max_f32_e32 v42, v142, v142
	v_max_f32_e32 v41, v42, v41
	v_max_f32_e32 v42, v147, v147
	v_max_f32_e32 v43, v146, v146
	v_max_f32_e32 v42, v43, v42
	v_max3_f32 v41, v140, v141, v41
	v_max3_f32 v42, v144, v145, v42
	v_max3_f32 v40, v40, v41, v42
	v_max_f32_e32 v41, v151, v151
	v_max_f32_e32 v42, v150, v150
	v_max_f32_e32 v41, v42, v41
	v_max_f32_e32 v42, v155, v155
	v_max_f32_e32 v43, v154, v154
	v_max_f32_e32 v42, v43, v42
	v_max3_f32 v41, v148, v149, v41
	v_max3_f32 v42, v152, v153, v42
	v_max3_f32 v40, v40, v41, v42
	v_max_f32_e32 v41, v159, v159
	v_max_f32_e32 v42, v158, v158
	v_max_f32_e32 v41, v42, v41
	v_max_f32_e32 v42, v39, v39
	v_max_f32_e32 v43, v38, v38
	v_max_f32_e32 v42, v43, v42
	v_max3_f32 v41, v156, v157, v41
	v_max3_f32 v42, v36, v37, v42
	v_max3_f32 v40, v40, v41, v42
	ds_bpermute_b32 v41, v171, v40
	s_waitcnt lgkmcnt(0)
	s_barrier
	s_waitcnt lgkmcnt(0)
	v_max_f32_e32 v41, v41, v41
	v_max_f32_e32 v40, v40, v41
	ds_bpermute_b32 v41, v172, v40
	s_waitcnt lgkmcnt(0)
	v_max_f32_e32 v41, v41, v41
	v_max_f32_e32 v182, v40, v41
	v_sub_f32_e32 v40, v84, v182
	v_mul_f32_e32 v40, 0x3d800000, v40
	v_sub_f32_e32 v41, v85, v182
	v_mul_f32_e32 v40, 0x3fb8aa3b, v40
	v_mul_f32_e32 v41, 0x3d800000, v41
	v_exp_f32_e32 v40, v40
	v_mul_f32_e32 v41, 0x3fb8aa3b, v41
	v_exp_f32_e32 v41, v41
	v_sub_f32_e32 v85, v96, v182
	v_add_f32_e32 v42, 0, v40
	v_mul_f32_e32 v85, 0x3d800000, v85
	v_add_f32_e32 v43, v41, v42
	v_sub_f32_e32 v42, v86, v182
	v_mul_f32_e32 v42, 0x3d800000, v42
	v_mul_f32_e32 v42, 0x3fb8aa3b, v42
	v_exp_f32_e32 v42, v42
	v_mul_f32_e32 v85, 0x3fb8aa3b, v85
	v_sub_f32_e32 v36, v36, v182
	v_mul_f32_e32 v36, 0x3d800000, v36
	v_add_f32_e32 v76, v42, v43
	v_sub_f32_e32 v43, v87, v182
	v_mul_f32_e32 v43, 0x3d800000, v43
	v_mul_f32_e32 v43, 0x3fb8aa3b, v43
	v_exp_f32_e32 v43, v43
	v_mul_f32_e32 v36, 0x3fb8aa3b, v36
	v_exp_f32_e32 v195, v36
	v_sub_f32_e32 v37, v37, v182
	v_add_f32_e32 v77, v43, v76
	v_sub_f32_e32 v76, v88, v182
	v_mul_f32_e32 v76, 0x3d800000, v76
	v_mul_f32_e32 v76, 0x3fb8aa3b, v76
	v_exp_f32_e32 v76, v76
	v_exp_f32_e32 v88, v85
	v_sub_f32_e32 v85, v97, v182
	v_mul_f32_e32 v85, 0x3d800000, v85
	v_add_f32_e32 v78, v76, v77
	v_sub_f32_e32 v77, v89, v182
	v_mul_f32_e32 v77, 0x3d800000, v77
	v_mul_f32_e32 v77, 0x3fb8aa3b, v77
	v_exp_f32_e32 v77, v77
	v_mul_f32_e32 v85, 0x3fb8aa3b, v85
	v_exp_f32_e32 v89, v85
	v_sub_f32_e32 v85, v98, v182
	v_add_f32_e32 v79, v77, v78
	v_sub_f32_e32 v78, v90, v182
	v_mul_f32_e32 v78, 0x3d800000, v78
	v_mul_f32_e32 v78, 0x3fb8aa3b, v78
	v_mul_f32_e32 v85, 0x3d800000, v85
	v_exp_f32_e32 v78, v78
	v_mul_f32_e32 v85, 0x3fb8aa3b, v85
	v_exp_f32_e32 v90, v85
	v_sub_f32_e32 v85, v99, v182
	v_mul_f32_e32 v85, 0x3d800000, v85
	v_mul_f32_e32 v85, 0x3fb8aa3b, v85
	v_add_f32_e32 v80, v78, v79
	v_sub_f32_e32 v79, v91, v182
	v_exp_f32_e32 v91, v85
	v_sub_f32_e32 v85, v100, v182
	v_mul_f32_e32 v85, 0x3d800000, v85
	v_mul_f32_e32 v85, 0x3fb8aa3b, v85
	v_exp_f32_e32 v96, v85
	v_sub_f32_e32 v85, v101, v182
	v_mul_f32_e32 v85, 0x3d800000, v85
	v_mul_f32_e32 v85, 0x3fb8aa3b, v85
	v_exp_f32_e32 v97, v85
	v_sub_f32_e32 v85, v102, v182
	v_mul_f32_e32 v85, 0x3d800000, v85
	v_mul_f32_e32 v85, 0x3fb8aa3b, v85
	v_exp_f32_e32 v98, v85
	v_sub_f32_e32 v85, v103, v182
	v_mul_f32_e32 v85, 0x3d800000, v85
	v_mul_f32_e32 v85, 0x3fb8aa3b, v85
	v_exp_f32_e32 v99, v85
	v_sub_f32_e32 v85, v104, v182
	v_mul_f32_e32 v85, 0x3d800000, v85
	v_mul_f32_e32 v85, 0x3fb8aa3b, v85
	v_exp_f32_e32 v100, v85
	v_sub_f32_e32 v85, v105, v182
	v_mul_f32_e32 v85, 0x3d800000, v85
	v_mul_f32_e32 v85, 0x3fb8aa3b, v85
	v_exp_f32_e32 v101, v85
	v_sub_f32_e32 v85, v106, v182
	v_mul_f32_e32 v85, 0x3d800000, v85
	v_mul_f32_e32 v85, 0x3fb8aa3b, v85
	v_exp_f32_e32 v102, v85
	v_sub_f32_e32 v85, v107, v182
	v_mul_f32_e32 v85, 0x3d800000, v85
	v_mul_f32_e32 v85, 0x3fb8aa3b, v85
	v_exp_f32_e32 v103, v85
	v_sub_f32_e32 v85, v112, v182
	v_mul_f32_e32 v85, 0x3d800000, v85
	v_mul_f32_e32 v85, 0x3fb8aa3b, v85
	v_exp_f32_e32 v104, v85
	v_sub_f32_e32 v85, v113, v182
	v_mul_f32_e32 v85, 0x3d800000, v85
	v_mul_f32_e32 v85, 0x3fb8aa3b, v85
	v_exp_f32_e32 v105, v85
	v_sub_f32_e32 v85, v114, v182
	v_mul_f32_e32 v85, 0x3d800000, v85
	v_mul_f32_e32 v85, 0x3fb8aa3b, v85
	v_exp_f32_e32 v106, v85
	v_sub_f32_e32 v85, v115, v182
	v_mul_f32_e32 v85, 0x3d800000, v85
	v_mul_f32_e32 v85, 0x3fb8aa3b, v85
	v_exp_f32_e32 v107, v85
	v_sub_f32_e32 v85, v128, v182
	v_mul_f32_e32 v85, 0x3d800000, v85
	v_mul_f32_e32 v85, 0x3fb8aa3b, v85
	v_exp_f32_e32 v108, v85
	v_sub_f32_e32 v85, v129, v182
	v_mul_f32_e32 v85, 0x3d800000, v85
	v_mul_f32_e32 v85, 0x3fb8aa3b, v85
	v_exp_f32_e32 v109, v85
	v_sub_f32_e32 v85, v130, v182
	v_mul_f32_e32 v85, 0x3d800000, v85
	v_mul_f32_e32 v85, 0x3fb8aa3b, v85
	v_exp_f32_e32 v110, v85
	v_sub_f32_e32 v85, v131, v182
	v_mul_f32_e32 v85, 0x3d800000, v85
	v_mul_f32_e32 v85, 0x3fb8aa3b, v85
	v_exp_f32_e32 v111, v85
	v_sub_f32_e32 v85, v132, v182
	v_mul_f32_e32 v85, 0x3d800000, v85
	v_mul_f32_e32 v85, 0x3fb8aa3b, v85
	v_exp_f32_e32 v112, v85
	v_sub_f32_e32 v85, v133, v182
	v_mul_f32_e32 v85, 0x3d800000, v85
	v_mul_f32_e32 v85, 0x3fb8aa3b, v85
	v_mul_f32_e32 v79, 0x3d800000, v79
	v_exp_f32_e32 v113, v85
	v_sub_f32_e32 v85, v134, v182
	v_mul_f32_e32 v79, 0x3fb8aa3b, v79
	v_mul_f32_e32 v85, 0x3d800000, v85
	v_exp_f32_e32 v79, v79
	v_mul_f32_e32 v85, 0x3fb8aa3b, v85
	v_exp_f32_e32 v114, v85
	v_sub_f32_e32 v85, v135, v182
	v_mul_f32_e32 v85, 0x3d800000, v85
	v_mul_f32_e32 v85, 0x3fb8aa3b, v85
	v_add_f32_e32 v81, v79, v80
	v_sub_f32_e32 v80, v92, v182
	v_exp_f32_e32 v115, v85
	v_sub_f32_e32 v85, v136, v182
	v_mul_f32_e32 v80, 0x3d800000, v80
	v_mul_f32_e32 v85, 0x3d800000, v85
	v_mul_f32_e32 v80, 0x3fb8aa3b, v80
	v_mul_f32_e32 v85, 0x3fb8aa3b, v85
	v_exp_f32_e32 v80, v80
	v_exp_f32_e32 v116, v85
	v_sub_f32_e32 v85, v137, v182
	v_mul_f32_e32 v85, 0x3d800000, v85
	v_mul_f32_e32 v85, 0x3fb8aa3b, v85
	v_exp_f32_e32 v117, v85
	v_sub_f32_e32 v85, v138, v182
	v_add_f32_e32 v82, v80, v81
	v_sub_f32_e32 v81, v93, v182
	v_mul_f32_e32 v85, 0x3d800000, v85
	v_mul_f32_e32 v81, 0x3d800000, v81
	v_mul_f32_e32 v85, 0x3fb8aa3b, v85
	v_mul_f32_e32 v81, 0x3fb8aa3b, v81
	v_exp_f32_e32 v118, v85
	v_sub_f32_e32 v85, v139, v182
	v_exp_f32_e32 v81, v81
	v_mul_f32_e32 v85, 0x3d800000, v85
	v_mul_f32_e32 v85, 0x3fb8aa3b, v85
	v_exp_f32_e32 v119, v85
	v_sub_f32_e32 v85, v140, v182
	v_mul_f32_e32 v85, 0x3d800000, v85
	v_add_f32_e32 v83, v81, v82
	v_sub_f32_e32 v82, v94, v182
	v_mul_f32_e32 v85, 0x3fb8aa3b, v85
	v_mul_f32_e32 v82, 0x3d800000, v82
	v_exp_f32_e32 v120, v85
	v_sub_f32_e32 v85, v141, v182
	v_mul_f32_e32 v82, 0x3fb8aa3b, v82
	v_mul_f32_e32 v85, 0x3d800000, v85
	v_exp_f32_e32 v82, v82
	v_mul_f32_e32 v85, 0x3fb8aa3b, v85
	v_exp_f32_e32 v121, v85
	v_sub_f32_e32 v85, v142, v182
	v_mul_f32_e32 v85, 0x3d800000, v85
	v_mul_f32_e32 v85, 0x3fb8aa3b, v85
	v_add_f32_e32 v84, v82, v83
	v_sub_f32_e32 v83, v95, v182
	v_exp_f32_e32 v122, v85
	v_sub_f32_e32 v85, v143, v182
	v_mul_f32_e32 v83, 0x3d800000, v83
	v_mul_f32_e32 v85, 0x3d800000, v85
	v_mul_f32_e32 v83, 0x3fb8aa3b, v83
	v_mul_f32_e32 v85, 0x3fb8aa3b, v85
	v_exp_f32_e32 v83, v83
	v_exp_f32_e32 v123, v85
	v_sub_f32_e32 v85, v144, v182
	v_mul_f32_e32 v85, 0x3d800000, v85
	v_mul_f32_e32 v85, 0x3fb8aa3b, v85
	v_exp_f32_e32 v124, v85
	v_sub_f32_e32 v85, v145, v182
	v_add_f32_e32 v84, v83, v84
	v_mul_f32_e32 v85, 0x3d800000, v85
	v_add_f32_e32 v84, v88, v84
	v_mul_f32_e32 v85, 0x3fb8aa3b, v85
	v_add_f32_e32 v84, v89, v84
	v_exp_f32_e32 v125, v85
	v_sub_f32_e32 v85, v146, v182
	v_add_f32_e32 v84, v90, v84
	v_mul_f32_e32 v85, 0x3d800000, v85
	v_add_f32_e32 v84, v91, v84
	v_mul_f32_e32 v85, 0x3fb8aa3b, v85
	v_add_f32_e32 v84, v96, v84
	v_exp_f32_e32 v126, v85
	v_sub_f32_e32 v85, v147, v182
	v_add_f32_e32 v84, v97, v84
	v_mul_f32_e32 v85, 0x3d800000, v85
	v_add_f32_e32 v84, v98, v84
	v_mul_f32_e32 v85, 0x3fb8aa3b, v85
	v_add_f32_e32 v84, v99, v84
	v_exp_f32_e32 v127, v85
	v_sub_f32_e32 v85, v148, v182
	v_add_f32_e32 v84, v100, v84
	v_mul_f32_e32 v85, 0x3d800000, v85
	v_add_f32_e32 v84, v101, v84
	v_mul_f32_e32 v85, 0x3fb8aa3b, v85
	v_add_f32_e32 v84, v102, v84
	v_exp_f32_e32 v177, v85
	v_sub_f32_e32 v85, v149, v182
	v_add_f32_e32 v84, v103, v84
	v_mul_f32_e32 v85, 0x3d800000, v85
	v_add_f32_e32 v84, v104, v84
	v_mul_f32_e32 v85, 0x3fb8aa3b, v85
	v_add_f32_e32 v84, v105, v84
	v_exp_f32_e32 v178, v85
	v_sub_f32_e32 v85, v150, v182
	v_add_f32_e32 v84, v106, v84
	v_mul_f32_e32 v85, 0x3d800000, v85
	v_add_f32_e32 v84, v107, v84
	v_mul_f32_e32 v85, 0x3fb8aa3b, v85
	v_add_f32_e32 v84, v108, v84
	v_exp_f32_e32 v179, v85
	v_sub_f32_e32 v85, v151, v182
	v_add_f32_e32 v84, v109, v84
	v_mul_f32_e32 v85, 0x3d800000, v85
	v_add_f32_e32 v84, v110, v84
	v_mul_f32_e32 v85, 0x3fb8aa3b, v85
	v_add_f32_e32 v84, v111, v84
	v_exp_f32_e32 v180, v85
	v_sub_f32_e32 v85, v152, v182
	v_add_f32_e32 v84, v112, v84
	v_mul_f32_e32 v85, 0x3d800000, v85
	v_add_f32_e32 v84, v113, v84
	v_mul_f32_e32 v85, 0x3fb8aa3b, v85
	v_add_f32_e32 v84, v114, v84
	v_exp_f32_e32 v187, v85
	v_sub_f32_e32 v85, v153, v182
	v_add_f32_e32 v84, v115, v84
	v_mul_f32_e32 v85, 0x3d800000, v85
	v_add_f32_e32 v84, v116, v84
	v_mul_f32_e32 v85, 0x3fb8aa3b, v85
	v_add_f32_e32 v84, v117, v84
	v_exp_f32_e32 v190, v85
	v_sub_f32_e32 v85, v154, v182
	v_add_f32_e32 v84, v118, v84
	v_mul_f32_e32 v85, 0x3d800000, v85
	v_add_f32_e32 v84, v119, v84
	v_mul_f32_e32 v85, 0x3fb8aa3b, v85
	v_add_f32_e32 v84, v120, v84
	v_exp_f32_e32 v191, v85
	v_sub_f32_e32 v85, v155, v182
	v_add_f32_e32 v84, v121, v84
	v_mul_f32_e32 v85, 0x3d800000, v85
	v_add_f32_e32 v84, v122, v84
	v_mul_f32_e32 v85, 0x3fb8aa3b, v85
	v_add_f32_e32 v84, v123, v84
	v_exp_f32_e32 v192, v85
	v_sub_f32_e32 v85, v156, v182
	v_add_f32_e32 v84, v124, v84
	v_mul_f32_e32 v85, 0x3d800000, v85
	v_add_f32_e32 v84, v125, v84
	v_mul_f32_e32 v85, 0x3fb8aa3b, v85
	v_add_f32_e32 v84, v126, v84
	v_exp_f32_e32 v193, v85
	v_sub_f32_e32 v85, v157, v182
	v_add_f32_e32 v84, v127, v84
	v_mul_f32_e32 v85, 0x3d800000, v85
	v_add_f32_e32 v84, v177, v84
	v_mul_f32_e32 v85, 0x3fb8aa3b, v85
	v_add_f32_e32 v84, v178, v84
	v_exp_f32_e32 v194, v85
	v_sub_f32_e32 v85, v158, v182
	v_add_f32_e32 v84, v179, v84
	v_mul_f32_e32 v85, 0x3d800000, v85
	v_add_f32_e32 v84, v180, v84
	v_mul_f32_e32 v85, 0x3fb8aa3b, v85
	v_add_f32_e32 v84, v187, v84
	v_exp_f32_e32 v158, v85
	v_sub_f32_e32 v85, v159, v182
	v_add_f32_e32 v84, v190, v84
	v_mul_f32_e32 v85, 0x3d800000, v85
	v_add_f32_e32 v84, v191, v84
	v_mul_f32_e32 v85, 0x3fb8aa3b, v85
	v_add_f32_e32 v84, v192, v84
	v_exp_f32_e32 v159, v85
	v_add_f32_e32 v84, v193, v84
	v_add_f32_e32 v84, v194, v84
	v_add_f32_e32 v84, v158, v84
	v_cvt_pk_bf16_f32 v92, v80, v81
	v_cvt_pk_bf16_f32 v93, v82, v83
	v_cvt_pk_bf16_f32 v94, v88, v89
	v_cvt_pk_bf16_f32 v95, v90, v91
	v_cvt_pk_bf16_f32 v80, v96, v97
	v_cvt_pk_bf16_f32 v81, v98, v99
	v_cvt_pk_bf16_f32 v82, v100, v101
	ds_read_b64_tr_b16 v[88:89], v169
	ds_read_b64_tr_b16 v[96:97], v169 offset:32
	ds_read_b64_tr_b16 v[90:91], v169 offset:8448
	ds_read_b64_tr_b16 v[98:99], v169 offset:16896
	ds_read_b64_tr_b16 v[100:101], v169 offset:25344
	v_add_f32_e32 v84, v159, v84
	v_add_f32_e32 v36, v195, v84
	v_cvt_pk_bf16_f32 v84, v40, v41
	v_cvt_pk_bf16_f32 v85, v42, v43
	v_cvt_pk_bf16_f32 v86, v76, v77
	v_cvt_pk_bf16_f32 v87, v78, v79
	v_cvt_pk_bf16_f32 v83, v102, v103
	v_mul_f32_e32 v37, 0x3d800000, v37
	s_waitcnt lgkmcnt(2)
	v_mfma_f32_16x16x32_bf16 v[88:91], v[88:91], v[84:87], 0
	v_mul_f32_e32 v37, 0x3fb8aa3b, v37
	v_exp_f32_e32 v196, v37
	v_sub_f32_e32 v37, v38, v182
	s_waitcnt lgkmcnt(0)
	v_mfma_f32_16x16x32_bf16 v[152:155], v[98:101], v[92:95], v[88:91]
	ds_read_b64_tr_b16 v[98:99], v169 offset:8480
	s_nop 1
	ds_read_b64_tr_b16 v[88:89], v169 offset:16928
	ds_read_b64_tr_b16 v[90:91], v169 offset:25376
	v_mul_f32_e32 v37, 0x3d800000, v37
	v_mul_f32_e32 v37, 0x3fb8aa3b, v37
	s_waitcnt lgkmcnt(2)
	v_mfma_f32_16x16x32_bf16 v[96:99], v[96:99], v[84:87], 0
	v_cvt_pk_bf16_f32 v76, v104, v105
	v_cvt_pk_bf16_f32 v77, v106, v107
	v_exp_f32_e32 v197, v37
	s_waitcnt lgkmcnt(0)
	v_mfma_f32_16x16x32_bf16 v[88:91], v[88:91], v[92:95], v[96:99]
	s_nop 2
	ds_read_b64_tr_b16 v[96:97], v169 offset:64
	ds_read_b64_tr_b16 v[98:99], v169 offset:8512
	ds_read_b64_tr_b16 v[100:101], v169 offset:16960
	ds_read_b64_tr_b16 v[102:103], v169 offset:25408
	v_sub_f32_e32 v37, v39, v182
	v_mul_f32_e32 v37, 0x3d800000, v37
	s_waitcnt lgkmcnt(2)
	v_mfma_f32_16x16x32_bf16 v[96:99], v[96:99], v[84:87], 0
	v_mul_f32_e32 v37, 0x3fb8aa3b, v37
	v_exp_f32_e32 v198, v37
	v_add_f32_e32 v36, v196, v36
	s_waitcnt lgkmcnt(0)
	v_mfma_f32_16x16x32_bf16 v[128:131], v[100:103], v[92:95], v[96:99]
	s_nop 2
	ds_read_b64_tr_b16 v[96:97], v169 offset:96
	ds_read_b64_tr_b16 v[98:99], v169 offset:8544
	ds_read_b64_tr_b16 v[100:101], v169 offset:16992
	ds_read_b64_tr_b16 v[102:103], v169 offset:25440
	v_add_f32_e32 v36, v197, v36
	v_add_f32_e32 v36, v198, v36
	s_waitcnt lgkmcnt(2)
	v_mfma_f32_16x16x32_bf16 v[96:99], v[96:99], v[84:87], 0
	ds_bpermute_b32 v37, v171, v36
	v_cvt_pk_bf16_f32 v38, v124, v125
	v_cvt_pk_bf16_f32 v39, v126, v127
	s_waitcnt lgkmcnt(1)
	v_mfma_f32_16x16x32_bf16 v[104:107], v[100:103], v[92:95], v[96:99]
	s_nop 2
	ds_read_b64_tr_b16 v[96:97], v169 offset:128
	ds_read_b64_tr_b16 v[98:99], v169 offset:8576
	ds_read_b64_tr_b16 v[100:101], v169 offset:17024
	ds_read_b64_tr_b16 v[102:103], v169 offset:25472
	s_waitcnt lgkmcnt(4)
	v_add_f32_e32 v156, v36, v37
	v_cvt_pk_bf16_f32 v36, v120, v121
	s_waitcnt lgkmcnt(2)
	v_mfma_f32_16x16x32_bf16 v[96:99], v[96:99], v[84:87], 0
	v_cvt_pk_bf16_f32 v37, v122, v123
	v_cvt_pk_bf16_f32 v78, v108, v109
	v_cvt_pk_bf16_f32 v79, v110, v111
	s_waitcnt lgkmcnt(0)
	v_mfma_f32_16x16x32_bf16 v[148:151], v[100:103], v[92:95], v[96:99]
	s_nop 2
	ds_read_b64_tr_b16 v[96:97], v169 offset:160
	ds_read_b64_tr_b16 v[98:99], v169 offset:8608
	ds_read_b64_tr_b16 v[100:101], v169 offset:17056
	ds_read_b64_tr_b16 v[102:103], v169 offset:25504
	v_cvt_pk_bf16_f32 v40, v112, v113
	v_cvt_pk_bf16_f32 v41, v114, v115
	s_waitcnt lgkmcnt(2)
	v_mfma_f32_16x16x32_bf16 v[96:99], v[96:99], v[84:87], 0
	v_cvt_pk_bf16_f32 v42, v116, v117
	v_cvt_pk_bf16_f32 v43, v118, v119
	ds_bpermute_b32 v157, v172, v156
	s_waitcnt lgkmcnt(1)
	v_mfma_f32_16x16x32_bf16 v[120:123], v[100:103], v[92:95], v[96:99]
	s_nop 2
	ds_read_b64_tr_b16 v[96:97], v169 offset:192
	ds_read_b64_tr_b16 v[98:99], v169 offset:8640
	ds_read_b64_tr_b16 v[100:101], v169 offset:17088
	ds_read_b64_tr_b16 v[102:103], v169 offset:25536
	s_waitcnt lgkmcnt(2)
	v_mfma_f32_16x16x32_bf16 v[96:99], v[96:99], v[84:87], 0
	s_waitcnt lgkmcnt(0)
	v_mfma_f32_16x16x32_bf16 v[124:127], v[100:103], v[92:95], v[96:99]
	s_nop 5
	ds_read_b64_tr_b16 v[96:97], v169 offset:224
	ds_read_b64_tr_b16 v[98:99], v169 offset:8672
	ds_read_b64_tr_b16 v[100:101], v169 offset:17120
	ds_read_b64_tr_b16 v[102:103], v169 offset:25568
	s_waitcnt lgkmcnt(2)
	v_mfma_f32_16x16x32_bf16 v[96:99], v[96:99], v[84:87], 0
	s_waitcnt lgkmcnt(0)
	v_mfma_f32_16x16x32_bf16 v[108:111], v[100:103], v[92:95], v[96:99]
	s_nop 5
	ds_read_b64_tr_b16 v[96:97], v169 offset:256
	ds_read_b64_tr_b16 v[98:99], v169 offset:8704
	ds_read_b64_tr_b16 v[100:101], v169 offset:17152
	ds_read_b64_tr_b16 v[102:103], v169 offset:25600
	s_waitcnt lgkmcnt(2)
	v_mfma_f32_16x16x32_bf16 v[96:99], v[96:99], v[84:87], 0
	s_waitcnt lgkmcnt(0)
	v_mfma_f32_16x16x32_bf16 v[100:103], v[100:103], v[92:95], v[96:99]
	s_nop 5
	ds_read_b64_tr_b16 v[96:97], v169 offset:288
	ds_read_b64_tr_b16 v[98:99], v169 offset:8736
	ds_read_b64_tr_b16 v[112:113], v169 offset:17184
	ds_read_b64_tr_b16 v[114:115], v169 offset:25632
	s_waitcnt lgkmcnt(2)
	v_mfma_f32_16x16x32_bf16 v[96:99], v[96:99], v[84:87], 0
	s_waitcnt lgkmcnt(0)
	v_mfma_f32_16x16x32_bf16 v[112:115], v[112:115], v[92:95], v[96:99]
	s_nop 5
	ds_read_b64_tr_b16 v[96:97], v169 offset:320
	ds_read_b64_tr_b16 v[98:99], v169 offset:8768
	ds_read_b64_tr_b16 v[116:117], v169 offset:17216
	ds_read_b64_tr_b16 v[118:119], v169 offset:25664
	s_waitcnt lgkmcnt(2)
	v_mfma_f32_16x16x32_bf16 v[96:99], v[96:99], v[84:87], 0
	s_waitcnt lgkmcnt(0)
	v_mfma_f32_16x16x32_bf16 v[116:119], v[116:119], v[92:95], v[96:99]
	s_nop 5
	ds_read_b64_tr_b16 v[96:97], v169 offset:352
	ds_read_b64_tr_b16 v[98:99], v169 offset:8800
	ds_read_b64_tr_b16 v[132:133], v169 offset:17248
	ds_read_b64_tr_b16 v[134:135], v169 offset:25696
	s_waitcnt lgkmcnt(2)
	v_mfma_f32_16x16x32_bf16 v[96:99], v[96:99], v[84:87], 0
	s_waitcnt lgkmcnt(0)
	v_mfma_f32_16x16x32_bf16 v[132:135], v[132:135], v[92:95], v[96:99]
	s_nop 5
	ds_read_b64_tr_b16 v[96:97], v169 offset:384
	ds_read_b64_tr_b16 v[98:99], v169 offset:8832
	ds_read_b64_tr_b16 v[136:137], v169 offset:17280
	ds_read_b64_tr_b16 v[138:139], v169 offset:25728
	s_waitcnt lgkmcnt(2)
	v_mfma_f32_16x16x32_bf16 v[96:99], v[96:99], v[84:87], 0
	s_waitcnt lgkmcnt(0)
	v_mfma_f32_16x16x32_bf16 v[136:139], v[136:139], v[92:95], v[96:99]
	s_nop 5
	ds_read_b64_tr_b16 v[96:97], v169 offset:416
	ds_read_b64_tr_b16 v[98:99], v169 offset:8864
	ds_read_b64_tr_b16 v[140:141], v169 offset:17312
	ds_read_b64_tr_b16 v[142:143], v169 offset:25760
	s_waitcnt lgkmcnt(2)
	v_mfma_f32_16x16x32_bf16 v[96:99], v[96:99], v[84:87], 0
	s_waitcnt lgkmcnt(0)
	v_mfma_f32_16x16x32_bf16 v[140:143], v[140:143], v[92:95], v[96:99]
	s_nop 5
	ds_read_b64_tr_b16 v[96:97], v169 offset:448
	ds_read_b64_tr_b16 v[98:99], v169 offset:8896
	ds_read_b64_tr_b16 v[144:145], v169 offset:17344
	ds_read_b64_tr_b16 v[146:147], v169 offset:25792
	s_waitcnt lgkmcnt(2)
	v_mfma_f32_16x16x32_bf16 v[96:99], v[96:99], v[84:87], 0
	s_waitcnt lgkmcnt(0)
	v_mfma_f32_16x16x32_bf16 v[144:147], v[144:147], v[92:95], v[96:99]
	s_nop 5
	ds_read_b64_tr_b16 v[96:97], v169 offset:480
	ds_read_b64_tr_b16 v[98:99], v169 offset:8928
	ds_read_b64_tr_b16 v[200:201], v169 offset:17376
	ds_read_b64_tr_b16 v[202:203], v169 offset:25824
	s_waitcnt vmcnt(7)
	ds_write_b128 v168, v[44:47]
	s_waitcnt vmcnt(6)
	ds_write_b128 v168, v[48:51] offset:128
	s_waitcnt vmcnt(5)
	ds_write_b128 v168, v[52:55] offset:256
	s_waitcnt vmcnt(4)
	ds_write_b128 v168, v[56:59] offset:384
	global_load_dwordx4 v[44:47], v[160:161], off offset:2048
	global_load_dwordx4 v[48:51], v[160:161], off offset:2176
	global_load_dwordx4 v[52:55], v[160:161], off offset:2304
	global_load_dwordx4 v[56:59], v[160:161], off offset:2432
	s_waitcnt lgkmcnt(6)
	v_mfma_f32_16x16x32_bf16 v[84:87], v[96:99], v[84:87], 0
	s_waitcnt lgkmcnt(0)
	s_barrier
	s_waitcnt lgkmcnt(4)
	v_mfma_f32_16x16x32_bf16 v[96:99], v[200:203], v[92:95], v[84:87]
	s_nop 4
	ds_read_b64_tr_b16 v[84:85], v3
	ds_read_b64_tr_b16 v[92:93], v3 offset:32
	ds_read_b64_tr_b16 v[86:87], v3 offset:8448
	ds_read_b64_tr_b16 v[200:201], v3 offset:16896
	ds_read_b64_tr_b16 v[202:203], v3 offset:25344
	s_waitcnt lgkmcnt(2)
	v_mfma_f32_16x16x32_bf16 v[84:87], v[84:87], v[80:83], v[152:155]
	ds_read_b64_tr_b16 v[94:95], v3 offset:8480
	s_nop 1
	ds_read_b64_tr_b16 v[152:153], v3 offset:16928
	ds_read_b64_tr_b16 v[154:155], v3 offset:25376
	s_waitcnt lgkmcnt(2)
	v_mfma_f32_16x16x32_bf16 v[88:91], v[92:95], v[80:83], v[88:91]
	s_waitcnt lgkmcnt(0)
	v_mfma_f32_16x16x32_bf16 v[92:95], v[152:155], v[76:79], v[88:91]
	s_nop 5
	ds_read_b64_tr_b16 v[88:89], v3 offset:64
	ds_read_b64_tr_b16 v[90:91], v3 offset:8512
	ds_read_b64_tr_b16 v[152:153], v3 offset:16960
	ds_read_b64_tr_b16 v[154:155], v3 offset:25408
	s_waitcnt lgkmcnt(2)
	v_mfma_f32_16x16x32_bf16 v[88:91], v[88:91], v[80:83], v[128:131]
	s_waitcnt lgkmcnt(0)
	v_mfma_f32_16x16x32_bf16 v[88:91], v[152:155], v[76:79], v[88:91]
	s_nop 0
	ds_read_b64_tr_b16 v[128:129], v3 offset:96
	ds_read_b64_tr_b16 v[130:131], v3 offset:8544
	ds_read_b64_tr_b16 v[152:153], v3 offset:16992
	ds_read_b64_tr_b16 v[154:155], v3 offset:25440
	s_waitcnt lgkmcnt(2)
	v_mfma_f32_16x16x32_bf16 v[104:107], v[128:131], v[80:83], v[104:107]
	s_waitcnt lgkmcnt(0)
	v_mfma_f32_16x16x32_bf16 v[128:131], v[152:155], v[76:79], v[104:107]
	s_nop 5
	ds_read_b64_tr_b16 v[104:105], v3 offset:128
	ds_read_b64_tr_b16 v[106:107], v3 offset:8576
	ds_read_b64_tr_b16 v[152:153], v3 offset:17024
	ds_read_b64_tr_b16 v[154:155], v3 offset:25472
	s_waitcnt lgkmcnt(2)
	v_mfma_f32_16x16x32_bf16 v[104:107], v[104:107], v[80:83], v[148:151]
	s_waitcnt lgkmcnt(0)
	v_mfma_f32_16x16x32_bf16 v[104:107], v[152:155], v[76:79], v[104:107]
	s_nop 0
	ds_read_b64_tr_b16 v[148:149], v3 offset:160
	ds_read_b64_tr_b16 v[150:151], v3 offset:8608
	ds_read_b64_tr_b16 v[152:153], v3 offset:17056
	ds_read_b64_tr_b16 v[154:155], v3 offset:25504
	s_waitcnt lgkmcnt(2)
	v_mfma_f32_16x16x32_bf16 v[120:123], v[148:151], v[80:83], v[120:123]
	s_waitcnt lgkmcnt(0)
	v_mfma_f32_16x16x32_bf16 v[120:123], v[152:155], v[76:79], v[120:123]
	ds_read_b64_tr_b16 v[148:149], v3 offset:192
	ds_read_b64_tr_b16 v[150:151], v3 offset:8640
	ds_read_b64_tr_b16 v[152:153], v3 offset:17088
	ds_read_b64_tr_b16 v[154:155], v3 offset:25536
	s_waitcnt lgkmcnt(2)
	v_mfma_f32_16x16x32_bf16 v[124:127], v[148:151], v[80:83], v[124:127]
	s_waitcnt lgkmcnt(0)
	v_mfma_f32_16x16x32_bf16 v[124:127], v[152:155], v[76:79], v[124:127]
	ds_read_b64_tr_b16 v[148:149], v3 offset:224
	ds_read_b64_tr_b16 v[150:151], v3 offset:8672
	ds_read_b64_tr_b16 v[152:153], v3 offset:17120
	ds_read_b64_tr_b16 v[154:155], v3 offset:25568
	s_waitcnt lgkmcnt(2)
	v_mfma_f32_16x16x32_bf16 v[108:111], v[148:151], v[80:83], v[108:111]
	s_waitcnt lgkmcnt(0)
	v_mfma_f32_16x16x32_bf16 v[108:111], v[152:155], v[76:79], v[108:111]
	ds_read_b64_tr_b16 v[148:149], v3 offset:256
	ds_read_b64_tr_b16 v[150:151], v3 offset:8704
	ds_read_b64_tr_b16 v[152:153], v3 offset:17152
	ds_read_b64_tr_b16 v[154:155], v3 offset:25600
	s_waitcnt lgkmcnt(2)
	v_mfma_f32_16x16x32_bf16 v[100:103], v[148:151], v[80:83], v[100:103]
	s_waitcnt lgkmcnt(0)
	v_mfma_f32_16x16x32_bf16 v[100:103], v[152:155], v[76:79], v[100:103]
	ds_read_b64_tr_b16 v[148:149], v3 offset:288
	ds_read_b64_tr_b16 v[150:151], v3 offset:8736
	ds_read_b64_tr_b16 v[152:153], v3 offset:17184
	ds_read_b64_tr_b16 v[154:155], v3 offset:25632
	s_waitcnt lgkmcnt(2)
	v_mfma_f32_16x16x32_bf16 v[112:115], v[148:151], v[80:83], v[112:115]
	s_waitcnt lgkmcnt(0)
	v_mfma_f32_16x16x32_bf16 v[112:115], v[152:155], v[76:79], v[112:115]
	ds_read_b64_tr_b16 v[148:149], v3 offset:320
	ds_read_b64_tr_b16 v[150:151], v3 offset:8768
	ds_read_b64_tr_b16 v[152:153], v3 offset:17216
	ds_read_b64_tr_b16 v[154:155], v3 offset:25664
	s_waitcnt lgkmcnt(2)
	v_mfma_f32_16x16x32_bf16 v[116:119], v[148:151], v[80:83], v[116:119]
	s_waitcnt lgkmcnt(0)
	v_mfma_f32_16x16x32_bf16 v[116:119], v[152:155], v[76:79], v[116:119]
	ds_read_b64_tr_b16 v[148:149], v3 offset:352
	ds_read_b64_tr_b16 v[150:151], v3 offset:8800
	ds_read_b64_tr_b16 v[152:153], v3 offset:17248
	ds_read_b64_tr_b16 v[154:155], v3 offset:25696
	s_waitcnt lgkmcnt(2)
	v_mfma_f32_16x16x32_bf16 v[132:135], v[148:151], v[80:83], v[132:135]
	s_waitcnt lgkmcnt(0)
	v_mfma_f32_16x16x32_bf16 v[132:135], v[152:155], v[76:79], v[132:135]
	ds_read_b64_tr_b16 v[148:149], v3 offset:384
	ds_read_b64_tr_b16 v[150:151], v3 offset:8832
	ds_read_b64_tr_b16 v[152:153], v3 offset:17280
	ds_read_b64_tr_b16 v[154:155], v3 offset:25728
	s_waitcnt lgkmcnt(2)
	v_mfma_f32_16x16x32_bf16 v[136:139], v[148:151], v[80:83], v[136:139]
	s_waitcnt lgkmcnt(0)
	v_mfma_f32_16x16x32_bf16 v[136:139], v[152:155], v[76:79], v[136:139]
	ds_read_b64_tr_b16 v[148:149], v3 offset:416
	ds_read_b64_tr_b16 v[150:151], v3 offset:8864
	ds_read_b64_tr_b16 v[152:153], v3 offset:17312
	ds_read_b64_tr_b16 v[154:155], v3 offset:25760
	s_waitcnt lgkmcnt(2)
	v_mfma_f32_16x16x32_bf16 v[140:143], v[148:151], v[80:83], v[140:143]
	s_waitcnt lgkmcnt(0)
	v_mfma_f32_16x16x32_bf16 v[140:143], v[152:155], v[76:79], v[140:143]
	ds_read_b64_tr_b16 v[148:149], v3 offset:448
	ds_read_b64_tr_b16 v[150:151], v3 offset:8896
	ds_read_b64_tr_b16 v[152:153], v3 offset:17344
	ds_read_b64_tr_b16 v[154:155], v3 offset:25792
	s_waitcnt lgkmcnt(2)
	v_mfma_f32_16x16x32_bf16 v[144:147], v[148:151], v[80:83], v[144:147]
	s_waitcnt lgkmcnt(0)
	v_mfma_f32_16x16x32_bf16 v[144:147], v[152:155], v[76:79], v[144:147]
	ds_read_b64_tr_b16 v[152:153], v3 offset:480
	ds_read_b64_tr_b16 v[154:155], v3 offset:8928
	ds_read_b64_tr_b16 v[148:149], v3 offset:17376
	ds_read_b64_tr_b16 v[150:151], v3 offset:25824
	s_waitcnt vmcnt(7)
	ds_write_b128 v170, v[60:63]
	s_waitcnt vmcnt(6)
	ds_write_b128 v170, v[64:67] offset:128
	s_waitcnt vmcnt(5)
	ds_write_b128 v170, v[68:71] offset:256
	s_waitcnt vmcnt(4)
	ds_write_b128 v170, v[72:75] offset:384
	s_waitcnt lgkmcnt(0)
	v_mfma_f32_16x16x32_bf16 v[84:87], v[200:203], v[76:79], v[84:87]
	s_barrier
	ds_read_b64_tr_b16 v[60:61], v169
	ds_read_b64_tr_b16 v[64:65], v169 offset:32
	ds_read_b64_tr_b16 v[62:63], v169 offset:8448
	ds_read_b64_tr_b16 v[66:67], v169 offset:16896
	ds_read_b64_tr_b16 v[68:69], v169 offset:25344
	s_waitcnt lgkmcnt(2)
	v_mfma_f32_16x16x32_bf16 v[60:63], v[60:63], v[40:43], v[84:87]
	s_waitcnt lgkmcnt(0)
	v_mfma_f32_16x16x32_bf16 v[60:63], v[66:69], v[36:39], v[60:63]
	ds_read_b64_tr_b16 v[66:67], v169 offset:8480
	ds_read_b64_tr_b16 v[68:69], v169 offset:16928
	ds_read_b64_tr_b16 v[70:71], v169 offset:25376
	s_waitcnt lgkmcnt(2)
	v_mfma_f32_16x16x32_bf16 v[64:67], v[64:67], v[40:43], v[92:95]
	s_waitcnt lgkmcnt(0)
	v_mfma_f32_16x16x32_bf16 v[64:67], v[68:71], v[36:39], v[64:67]
	ds_read_b64_tr_b16 v[68:69], v169 offset:64
	ds_read_b64_tr_b16 v[70:71], v169 offset:8512
	ds_read_b64_tr_b16 v[72:73], v169 offset:16960
	ds_read_b64_tr_b16 v[74:75], v169 offset:25408
	v_mfma_f32_16x16x32_bf16 v[80:83], v[152:155], v[80:83], v[96:99]
	v_mov_b32_e32 v155, 0xa00000
	s_waitcnt lgkmcnt(2)
	v_mfma_f32_16x16x32_bf16 v[68:71], v[68:71], v[40:43], v[88:91]
	v_mfma_f32_16x16x32_bf16 v[76:79], v[148:151], v[76:79], v[80:83]
	s_waitcnt lgkmcnt(0)
	v_mfma_f32_16x16x32_bf16 v[68:71], v[72:75], v[36:39], v[68:71]
	ds_read_b64_tr_b16 v[72:73], v169 offset:96
	ds_read_b64_tr_b16 v[74:75], v169 offset:8544
	ds_read_b64_tr_b16 v[80:81], v169 offset:16992
	ds_read_b64_tr_b16 v[82:83], v169 offset:25440
	s_waitcnt lgkmcnt(2)
	v_mfma_f32_16x16x32_bf16 v[72:75], v[72:75], v[40:43], v[128:131]
	s_waitcnt lgkmcnt(0)
	v_mfma_f32_16x16x32_bf16 v[128:131], v[80:83], v[36:39], v[72:75]
	s_nop 5
	ds_read_b64_tr_b16 v[72:73], v169 offset:128
	ds_read_b64_tr_b16 v[74:75], v169 offset:8576
	ds_read_b64_tr_b16 v[80:81], v169 offset:17024
	ds_read_b64_tr_b16 v[82:83], v169 offset:25472
	s_waitcnt lgkmcnt(2)
	v_mfma_f32_16x16x32_bf16 v[72:75], v[72:75], v[40:43], v[104:107]
	s_waitcnt lgkmcnt(0)
	v_mfma_f32_16x16x32_bf16 v[72:75], v[80:83], v[36:39], v[72:75]
	ds_read_b64_tr_b16 v[80:81], v169 offset:160
	ds_read_b64_tr_b16 v[82:83], v169 offset:8608
	ds_read_b64_tr_b16 v[84:85], v169 offset:17056
	ds_read_b64_tr_b16 v[86:87], v169 offset:25504
	s_waitcnt lgkmcnt(2)
	v_mfma_f32_16x16x32_bf16 v[80:83], v[80:83], v[40:43], v[120:123]
	s_waitcnt lgkmcnt(0)
	v_mfma_f32_16x16x32_bf16 v[80:83], v[84:87], v[36:39], v[80:83]
	ds_read_b64_tr_b16 v[84:85], v169 offset:192
	ds_read_b64_tr_b16 v[86:87], v169 offset:8640
	ds_read_b64_tr_b16 v[88:89], v169 offset:17088
	ds_read_b64_tr_b16 v[90:91], v169 offset:25536
	s_waitcnt lgkmcnt(2)
	v_mfma_f32_16x16x32_bf16 v[84:87], v[84:87], v[40:43], v[124:127]
	s_waitcnt lgkmcnt(0)
	v_mfma_f32_16x16x32_bf16 v[84:87], v[88:91], v[36:39], v[84:87]
	ds_read_b64_tr_b16 v[88:89], v169 offset:224
	ds_read_b64_tr_b16 v[90:91], v169 offset:8672
	ds_read_b64_tr_b16 v[92:93], v169 offset:17120
	ds_read_b64_tr_b16 v[94:95], v169 offset:25568
	s_waitcnt lgkmcnt(2)
	v_mfma_f32_16x16x32_bf16 v[88:91], v[88:91], v[40:43], v[108:111]
	s_waitcnt lgkmcnt(0)
	v_mfma_f32_16x16x32_bf16 v[120:123], v[92:95], v[36:39], v[88:91]
	s_nop 5
	ds_read_b64_tr_b16 v[88:89], v169 offset:256
	ds_read_b64_tr_b16 v[90:91], v169 offset:8704
	ds_read_b64_tr_b16 v[92:93], v169 offset:17152
	ds_read_b64_tr_b16 v[94:95], v169 offset:25600
	s_waitcnt lgkmcnt(2)
	v_mfma_f32_16x16x32_bf16 v[88:91], v[88:91], v[40:43], v[100:103]
	s_waitcnt lgkmcnt(0)
	v_mfma_f32_16x16x32_bf16 v[88:91], v[92:95], v[36:39], v[88:91]
	ds_read_b64_tr_b16 v[92:93], v169 offset:288
	ds_read_b64_tr_b16 v[94:95], v169 offset:8736
	ds_read_b64_tr_b16 v[96:97], v169 offset:17184
	ds_read_b64_tr_b16 v[98:99], v169 offset:25632
	s_waitcnt lgkmcnt(2)
	v_mfma_f32_16x16x32_bf16 v[92:95], v[92:95], v[40:43], v[112:115]
	s_waitcnt lgkmcnt(0)
	v_mfma_f32_16x16x32_bf16 v[92:95], v[96:99], v[36:39], v[92:95]
	ds_read_b64_tr_b16 v[96:97], v169 offset:320
	ds_read_b64_tr_b16 v[98:99], v169 offset:8768
	ds_read_b64_tr_b16 v[100:101], v169 offset:17216
	ds_read_b64_tr_b16 v[102:103], v169 offset:25664
	s_waitcnt lgkmcnt(2)
	v_mfma_f32_16x16x32_bf16 v[96:99], v[96:99], v[40:43], v[116:119]
	s_waitcnt lgkmcnt(0)
	v_mfma_f32_16x16x32_bf16 v[96:99], v[100:103], v[36:39], v[96:99]
	ds_read_b64_tr_b16 v[100:101], v169 offset:352
	ds_read_b64_tr_b16 v[102:103], v169 offset:8800
	ds_read_b64_tr_b16 v[104:105], v169 offset:17248
	ds_read_b64_tr_b16 v[106:107], v169 offset:25696
	s_waitcnt lgkmcnt(2)
	v_mfma_f32_16x16x32_bf16 v[100:103], v[100:103], v[40:43], v[132:135]
	s_waitcnt lgkmcnt(0)
	v_mfma_f32_16x16x32_bf16 v[112:115], v[104:107], v[36:39], v[100:103]
	s_nop 5
	ds_read_b64_tr_b16 v[100:101], v169 offset:384
	ds_read_b64_tr_b16 v[102:103], v169 offset:8832
	ds_read_b64_tr_b16 v[104:105], v169 offset:17280
	ds_read_b64_tr_b16 v[106:107], v169 offset:25728
	s_waitcnt lgkmcnt(2)
	v_mfma_f32_16x16x32_bf16 v[100:103], v[100:103], v[40:43], v[136:139]
	s_waitcnt lgkmcnt(0)
	v_mfma_f32_16x16x32_bf16 v[100:103], v[104:107], v[36:39], v[100:103]
	ds_read_b64_tr_b16 v[104:105], v169 offset:416
	ds_read_b64_tr_b16 v[106:107], v169 offset:8864
	ds_read_b64_tr_b16 v[108:109], v169 offset:17312
	ds_read_b64_tr_b16 v[110:111], v169 offset:25760
	v_add_u32_e32 v136, s14, v1
	v_add_f32_e32 v1, v156, v157
	s_waitcnt lgkmcnt(2)
	v_mfma_f32_16x16x32_bf16 v[104:107], v[104:107], v[40:43], v[140:143]
	v_ashrrev_i32_e32 v137, 31, v136
	s_waitcnt lgkmcnt(0)
	v_mfma_f32_16x16x32_bf16 v[104:107], v[108:111], v[36:39], v[104:107]
	ds_read_b64_tr_b16 v[108:109], v169 offset:448
	ds_read_b64_tr_b16 v[110:111], v169 offset:8896
	ds_read_b64_tr_b16 v[116:117], v169 offset:17344
	ds_read_b64_tr_b16 v[118:119], v169 offset:25792
	s_waitcnt lgkmcnt(2)
	v_mfma_f32_16x16x32_bf16 v[108:111], v[108:111], v[40:43], v[144:147]
	s_waitcnt lgkmcnt(0)
	v_mfma_f32_16x16x32_bf16 v[108:111], v[116:119], v[36:39], v[108:111]
	ds_read_b64_tr_b16 v[116:117], v169 offset:480
	ds_read_b64_tr_b16 v[118:119], v169 offset:8928
	ds_read_b64_tr_b16 v[124:125], v169 offset:17376
	ds_read_b64_tr_b16 v[126:127], v169 offset:25824
	s_waitcnt vmcnt(3)
	ds_write_b128 v168, v[44:47]
	s_waitcnt vmcnt(2)
	ds_write_b128 v168, v[48:51] offset:128
	s_waitcnt vmcnt(1)
	ds_write_b128 v168, v[52:55] offset:256
	s_waitcnt vmcnt(0)
	ds_write_b128 v168, v[56:59] offset:384
	s_waitcnt lgkmcnt(0)
	s_waitcnt lgkmcnt(6)
	v_mfma_f32_16x16x32_bf16 v[40:43], v[116:119], v[40:43], v[76:79]
	s_barrier
	v_cvt_pk_bf16_f32 v52, v177, v178
	s_waitcnt lgkmcnt(4)
	v_mfma_f32_16x16x32_bf16 v[36:39], v[124:127], v[36:39], v[40:43]
	s_nop 3
	ds_read_b64_tr_b16 v[40:41], v3
	ds_read_b64_tr_b16 v[56:57], v3 offset:32
	ds_read_b64_tr_b16 v[42:43], v3 offset:8448
	ds_read_b64_tr_b16 v[44:45], v3 offset:16896
	ds_read_b64_tr_b16 v[46:47], v3 offset:25344
	v_cvt_pk_bf16_f32 v53, v179, v180
	v_cvt_pk_bf16_f32 v54, v187, v190
	v_cvt_pk_bf16_f32 v55, v191, v192
	v_cvt_pk_bf16_f32 v48, v193, v194
	v_cvt_pk_bf16_f32 v49, v158, v159
	s_waitcnt lgkmcnt(2)
	v_mfma_f32_16x16x32_bf16 v[40:43], v[40:43], v[52:55], v[60:63]
	v_cvt_pk_bf16_f32 v50, v195, v196
	v_cvt_pk_bf16_f32 v51, v197, v198
	s_waitcnt lgkmcnt(0)
	s_nop 0
	v_mfma_f32_16x16x32_bf16 v[44:47], v[44:47], v[48:51], v[40:43]
	ds_read_b64_tr_b16 v[58:59], v3 offset:8480
	s_nop 1
	ds_read_b64_tr_b16 v[40:41], v3 offset:16928
	ds_read_b64_tr_b16 v[42:43], v3 offset:25376
	s_waitcnt lgkmcnt(2)
	v_mfma_f32_16x16x32_bf16 v[56:59], v[56:59], v[52:55], v[64:67]
	s_waitcnt lgkmcnt(0)
	v_mfma_f32_16x16x32_bf16 v[40:43], v[40:43], v[48:51], v[56:59]
	s_nop 5
	ds_read_b64_tr_b16 v[56:57], v3 offset:64
	ds_read_b64_tr_b16 v[58:59], v3 offset:8512
	ds_read_b64_tr_b16 v[60:61], v3 offset:16960
	ds_read_b64_tr_b16 v[62:63], v3 offset:25408
	s_waitcnt lgkmcnt(2)
	v_mfma_f32_16x16x32_bf16 v[56:59], v[56:59], v[52:55], v[68:71]
	s_waitcnt lgkmcnt(0)
	v_mfma_f32_16x16x32_bf16 v[56:59], v[60:63], v[48:51], v[56:59]
	ds_read_b64_tr_b16 v[60:61], v3 offset:96
	ds_read_b64_tr_b16 v[62:63], v3 offset:8544
	ds_read_b64_tr_b16 v[64:65], v3 offset:16992
	ds_read_b64_tr_b16 v[66:67], v3 offset:25440
	s_waitcnt lgkmcnt(2)
	v_mfma_f32_16x16x32_bf16 v[60:63], v[60:63], v[52:55], v[128:131]
	s_waitcnt lgkmcnt(0)
	v_mfma_f32_16x16x32_bf16 v[60:63], v[64:67], v[48:51], v[60:63]
	ds_read_b64_tr_b16 v[64:65], v3 offset:128
	ds_read_b64_tr_b16 v[66:67], v3 offset:8576
	ds_read_b64_tr_b16 v[68:69], v3 offset:17024
	ds_read_b64_tr_b16 v[70:71], v3 offset:25472
	s_waitcnt lgkmcnt(2)
	v_mfma_f32_16x16x32_bf16 v[64:67], v[64:67], v[52:55], v[72:75]
	s_waitcnt lgkmcnt(0)
	v_mfma_f32_16x16x32_bf16 v[64:67], v[68:71], v[48:51], v[64:67]
	ds_read_b64_tr_b16 v[68:69], v3 offset:160
	ds_read_b64_tr_b16 v[70:71], v3 offset:8608
	ds_read_b64_tr_b16 v[72:73], v3 offset:17056
	ds_read_b64_tr_b16 v[74:75], v3 offset:25504
	s_waitcnt lgkmcnt(2)
	v_mfma_f32_16x16x32_bf16 v[68:71], v[68:71], v[52:55], v[80:83]
	s_waitcnt lgkmcnt(0)
	v_mfma_f32_16x16x32_bf16 v[68:71], v[72:75], v[48:51], v[68:71]
	ds_read_b64_tr_b16 v[72:73], v3 offset:192
	ds_read_b64_tr_b16 v[74:75], v3 offset:8640
	ds_read_b64_tr_b16 v[76:77], v3 offset:17088
	ds_read_b64_tr_b16 v[78:79], v3 offset:25536
	s_waitcnt lgkmcnt(2)
	v_mfma_f32_16x16x32_bf16 v[72:75], v[72:75], v[52:55], v[84:87]
	s_waitcnt lgkmcnt(0)
	v_mfma_f32_16x16x32_bf16 v[72:75], v[76:79], v[48:51], v[72:75]
	ds_read_b64_tr_b16 v[76:77], v3 offset:224
	ds_read_b64_tr_b16 v[78:79], v3 offset:8672
	ds_read_b64_tr_b16 v[80:81], v3 offset:17120
	ds_read_b64_tr_b16 v[82:83], v3 offset:25568
	s_waitcnt lgkmcnt(2)
	v_mfma_f32_16x16x32_bf16 v[76:79], v[76:79], v[52:55], v[120:123]
	s_waitcnt lgkmcnt(0)
	v_mfma_f32_16x16x32_bf16 v[76:79], v[80:83], v[48:51], v[76:79]
	ds_read_b64_tr_b16 v[80:81], v3 offset:256
	ds_read_b64_tr_b16 v[82:83], v3 offset:8704
	ds_read_b64_tr_b16 v[84:85], v3 offset:17152
	ds_read_b64_tr_b16 v[86:87], v3 offset:25600
	s_waitcnt lgkmcnt(2)
	v_mfma_f32_16x16x32_bf16 v[80:83], v[80:83], v[52:55], v[88:91]
	s_waitcnt lgkmcnt(0)
	v_mfma_f32_16x16x32_bf16 v[80:83], v[84:87], v[48:51], v[80:83]
	ds_read_b64_tr_b16 v[84:85], v3 offset:288
	ds_read_b64_tr_b16 v[86:87], v3 offset:8736
	ds_read_b64_tr_b16 v[88:89], v3 offset:17184
	ds_read_b64_tr_b16 v[90:91], v3 offset:25632
	s_waitcnt lgkmcnt(2)
	v_mfma_f32_16x16x32_bf16 v[84:87], v[84:87], v[52:55], v[92:95]
	s_waitcnt lgkmcnt(0)
	v_mfma_f32_16x16x32_bf16 v[84:87], v[88:91], v[48:51], v[84:87]
	ds_read_b64_tr_b16 v[88:89], v3 offset:320
	ds_read_b64_tr_b16 v[90:91], v3 offset:8768
	ds_read_b64_tr_b16 v[92:93], v3 offset:17216
	ds_read_b64_tr_b16 v[94:95], v3 offset:25664
	s_waitcnt lgkmcnt(2)
	v_mfma_f32_16x16x32_bf16 v[88:91], v[88:91], v[52:55], v[96:99]
	s_waitcnt lgkmcnt(0)
	v_mfma_f32_16x16x32_bf16 v[88:91], v[92:95], v[48:51], v[88:91]
	ds_read_b64_tr_b16 v[92:93], v3 offset:352
	ds_read_b64_tr_b16 v[94:95], v3 offset:8800
	ds_read_b64_tr_b16 v[96:97], v3 offset:17248
	ds_read_b64_tr_b16 v[98:99], v3 offset:25696
	s_waitcnt lgkmcnt(2)
	v_mfma_f32_16x16x32_bf16 v[92:95], v[92:95], v[52:55], v[112:115]
	s_waitcnt lgkmcnt(0)
	v_mfma_f32_16x16x32_bf16 v[92:95], v[96:99], v[48:51], v[92:95]
	ds_read_b64_tr_b16 v[96:97], v3 offset:384
	ds_read_b64_tr_b16 v[98:99], v3 offset:8832
	ds_read_b64_tr_b16 v[112:113], v3 offset:17280
	ds_read_b64_tr_b16 v[114:115], v3 offset:25728
	s_waitcnt lgkmcnt(2)
	v_mfma_f32_16x16x32_bf16 v[96:99], v[96:99], v[52:55], v[100:103]
	s_waitcnt lgkmcnt(0)
	v_mfma_f32_16x16x32_bf16 v[96:99], v[112:115], v[48:51], v[96:99]
	s_nop 0
	ds_read_b64_tr_b16 v[100:101], v3 offset:416
	ds_read_b64_tr_b16 v[102:103], v3 offset:8864
	ds_read_b64_tr_b16 v[112:113], v3 offset:17312
	ds_read_b64_tr_b16 v[114:115], v3 offset:25760
	s_waitcnt lgkmcnt(2)
	v_mfma_f32_16x16x32_bf16 v[100:103], v[100:103], v[52:55], v[104:107]
	s_waitcnt lgkmcnt(0)
	v_mfma_f32_16x16x32_bf16 v[100:103], v[112:115], v[48:51], v[100:103]
	s_nop 0
	ds_read_b64_tr_b16 v[104:105], v3 offset:448
	ds_read_b64_tr_b16 v[106:107], v3 offset:8896
	ds_read_b64_tr_b16 v[112:113], v3 offset:17344
	ds_read_b64_tr_b16 v[114:115], v3 offset:25792
	s_waitcnt lgkmcnt(2)
	v_mfma_f32_16x16x32_bf16 v[104:107], v[104:107], v[52:55], v[108:111]
	s_waitcnt lgkmcnt(0)
	v_mfma_f32_16x16x32_bf16 v[104:107], v[112:115], v[48:51], v[104:107]
	s_nop 0
	ds_read_b64_tr_b16 v[108:109], v3 offset:480
	ds_read_b64_tr_b16 v[110:111], v3 offset:8928
	ds_read_b64_tr_b16 v[112:113], v3 offset:17376
	ds_read_b64_tr_b16 v[114:115], v3 offset:25824
	s_waitcnt lgkmcnt(2)
	v_mfma_f32_16x16x32_bf16 v[36:39], v[108:111], v[52:55], v[36:39]
	s_waitcnt lgkmcnt(0)
	v_mfma_f32_16x16x32_bf16 v[36:39], v[112:115], v[48:51], v[36:39]
	v_div_scale_f32 v48, s[12:13], v1, v1, 1.0
	v_rcp_f32_e32 v49, v48
	v_readlane_b32 s12, v253, 35
	v_readlane_b32 s13, v253, 36
	s_add_u32 s10, s12, s10
	v_fma_f32 v50, -v48, v49, 1.0
	v_fmac_f32_e32 v49, v50, v49
	v_div_scale_f32 v50, vcc, 1.0, v1, 1.0
	v_mul_f32_e32 v51, v50, v49
	v_fma_f32 v52, -v48, v51, v50
	v_fmac_f32_e32 v51, v52, v49
	v_fma_f32 v48, -v48, v51, v50
	v_div_fmas_f32 v48, v48, v49, v51
	s_addc_u32 s11, s13, s11
	v_lshlrev_b64 v[50:51], 11, v[136:137]
	v_lshl_add_u64 v[50:51], s[10:11], 0, v[50:51]
	v_div_fixup_f32 v48, v48, v1, 1.0
	v_mad_i64_i32 v[50:51], s[12:13], s6, v155, v[50:51]
	v_lshl_add_u64 v[50:51], v[50:51], 0, s[8:9]
	v_mov_b32_e32 v1, v181
	v_pk_mul_f32 v[40:41], v[48:49], v[40:41] op_sel_hi:[0,1]
	v_pk_mul_f32 v[42:43], v[48:49], v[42:43] op_sel_hi:[0,1]
	v_lshl_add_u64 v[50:51], v[50:51], 0, v[0:1]
	v_cvt_pk_bf16_f32 v40, v40, v41
	v_cvt_pk_bf16_f32 v41, v42, v43
	global_store_dwordx2 v[50:51], v[40:41], off offset:32
	v_pk_mul_f32 v[40:41], v[48:49], v[56:57] op_sel_hi:[0,1]
	v_pk_mul_f32 v[42:43], v[48:49], v[58:59] op_sel_hi:[0,1]
	v_cvt_pk_bf16_f32 v40, v40, v41
	v_cvt_pk_bf16_f32 v41, v42, v43
	global_store_dwordx2 v[50:51], v[40:41], off offset:64
	v_pk_mul_f32 v[40:41], v[48:49], v[60:61] op_sel_hi:[0,1]
	v_pk_mul_f32 v[42:43], v[48:49], v[62:63] op_sel_hi:[0,1]
	v_cvt_pk_bf16_f32 v40, v40, v41
	v_cvt_pk_bf16_f32 v41, v42, v43
	global_store_dwordx2 v[50:51], v[40:41], off offset:96
	v_pk_mul_f32 v[40:41], v[48:49], v[64:65] op_sel_hi:[0,1]
	v_pk_mul_f32 v[42:43], v[48:49], v[66:67] op_sel_hi:[0,1]
	v_cvt_pk_bf16_f32 v40, v40, v41
	v_cvt_pk_bf16_f32 v41, v42, v43
	global_store_dwordx2 v[50:51], v[40:41], off offset:128
	v_pk_mul_f32 v[40:41], v[48:49], v[68:69] op_sel_hi:[0,1]
	v_pk_mul_f32 v[42:43], v[48:49], v[70:71] op_sel_hi:[0,1]
	v_cvt_pk_bf16_f32 v40, v40, v41
	v_cvt_pk_bf16_f32 v41, v42, v43
	global_store_dwordx2 v[50:51], v[40:41], off offset:160
	v_pk_mul_f32 v[40:41], v[48:49], v[72:73] op_sel_hi:[0,1]
	v_pk_mul_f32 v[42:43], v[48:49], v[74:75] op_sel_hi:[0,1]
	v_cvt_pk_bf16_f32 v40, v40, v41
	v_cvt_pk_bf16_f32 v41, v42, v43
	global_store_dwordx2 v[50:51], v[40:41], off offset:192
	v_pk_mul_f32 v[40:41], v[48:49], v[76:77] op_sel_hi:[0,1]
	v_pk_mul_f32 v[42:43], v[48:49], v[78:79] op_sel_hi:[0,1]
	v_cvt_pk_bf16_f32 v40, v40, v41
	v_cvt_pk_bf16_f32 v41, v42, v43
	global_store_dwordx2 v[50:51], v[40:41], off offset:224
	v_pk_mul_f32 v[40:41], v[48:49], v[80:81] op_sel_hi:[0,1]
	v_pk_mul_f32 v[42:43], v[48:49], v[82:83] op_sel_hi:[0,1]
	v_cvt_pk_bf16_f32 v40, v40, v41
	v_cvt_pk_bf16_f32 v41, v42, v43
	global_store_dwordx2 v[50:51], v[40:41], off offset:256
	v_pk_mul_f32 v[40:41], v[48:49], v[84:85] op_sel_hi:[0,1]
	v_pk_mul_f32 v[42:43], v[48:49], v[86:87] op_sel_hi:[0,1]
	v_cvt_pk_bf16_f32 v40, v40, v41
	v_cvt_pk_bf16_f32 v41, v42, v43
	global_store_dwordx2 v[50:51], v[40:41], off offset:288
	v_pk_mul_f32 v[40:41], v[48:49], v[88:89] op_sel_hi:[0,1]
	v_pk_mul_f32 v[42:43], v[48:49], v[90:91] op_sel_hi:[0,1]
	v_cvt_pk_bf16_f32 v40, v40, v41
	v_cvt_pk_bf16_f32 v41, v42, v43
	global_store_dwordx2 v[50:51], v[40:41], off offset:320
	v_pk_mul_f32 v[40:41], v[48:49], v[92:93] op_sel_hi:[0,1]
	v_pk_mul_f32 v[42:43], v[48:49], v[94:95] op_sel_hi:[0,1]
	v_cvt_pk_bf16_f32 v40, v40, v41
	v_cvt_pk_bf16_f32 v41, v42, v43
	global_store_dwordx2 v[50:51], v[40:41], off offset:352
	v_pk_mul_f32 v[40:41], v[48:49], v[96:97] op_sel_hi:[0,1]
	v_pk_mul_f32 v[42:43], v[48:49], v[98:99] op_sel_hi:[0,1]
	v_cvt_pk_bf16_f32 v40, v40, v41
	v_cvt_pk_bf16_f32 v41, v42, v43
	global_store_dwordx2 v[50:51], v[40:41], off offset:384
	v_pk_mul_f32 v[40:41], v[48:49], v[100:101] op_sel_hi:[0,1]
	v_pk_mul_f32 v[42:43], v[48:49], v[102:103] op_sel_hi:[0,1]
	v_cvt_pk_bf16_f32 v40, v40, v41
	v_cvt_pk_bf16_f32 v41, v42, v43
	v_pk_mul_f32 v[44:45], v[48:49], v[44:45] op_sel_hi:[0,1]
	v_pk_mul_f32 v[46:47], v[48:49], v[46:47] op_sel_hi:[0,1]
	global_store_dwordx2 v[50:51], v[40:41], off offset:416
	v_pk_mul_f32 v[40:41], v[48:49], v[104:105] op_sel_hi:[0,1]
	v_pk_mul_f32 v[42:43], v[48:49], v[106:107] op_sel_hi:[0,1]
	v_pk_mul_f32 v[36:37], v[48:49], v[36:37] op_sel_hi:[0,1]
	v_pk_mul_f32 v[38:39], v[48:49], v[38:39] op_sel_hi:[0,1]
	v_cvt_pk_bf16_f32 v44, v44, v45
	v_cvt_pk_bf16_f32 v45, v46, v47
	v_cvt_pk_bf16_f32 v40, v40, v41
	v_cvt_pk_bf16_f32 v41, v42, v43
	v_cvt_pk_bf16_f32 v36, v36, v37
	v_cvt_pk_bf16_f32 v37, v38, v39
	global_store_dwordx2 v[50:51], v[44:45], off
	global_store_dwordx2 v[50:51], v[40:41], off offset:448
	global_store_dwordx2 v[50:51], v[36:37], off offset:480
	s_waitcnt lgkmcnt(0)
	s_barrier
	s_waitcnt lgkmcnt(0)
	s_barrier
	ds_write_b128 v176, v[4:7]
	ds_write_b128 v176, v[8:11] offset:256
	ds_write_b128 v176, v[12:15] offset:8448
	ds_write_b128 v176, v[16:19] offset:8704
	ds_write_b128 v176, v[20:23] offset:16896
	ds_write_b128 v176, v[24:27] offset:17152
	ds_write_b128 v176, v[28:31] offset:25344
	ds_write_b128 v176, v[32:35] offset:25600
	s_waitcnt lgkmcnt(0)
	s_barrier
	ds_read_b128 v[64:67], v175
	ds_read_b128 v[60:63], v175 offset:64
	ds_read_b128 v[56:59], v175 offset:128
	ds_read_b128 v[52:55], v175 offset:192
	ds_read_b128 v[48:51], v175 offset:256
	ds_read_b128 v[44:47], v175 offset:320
	ds_read_b128 v[8:11], v175 offset:384
	ds_read_b128 v[4:7], v175 offset:448
	global_load_dwordx4 v[28:31], v[166:167], off
	global_load_dwordx4 v[12:15], v[164:165], off
	global_load_dwordx4 v[32:35], v[166:167], off offset:128
	global_load_dwordx4 v[16:19], v[164:165], off offset:128
	global_load_dwordx4 v[36:39], v[166:167], off offset:256
	global_load_dwordx4 v[20:23], v[164:165], off offset:256
	global_load_dwordx4 v[40:43], v[166:167], off offset:384
	global_load_dwordx4 v[24:27], v[164:165], off offset:384
	s_waitcnt vmcnt(7)
	ds_write_b128 v170, v[28:31]
	s_waitcnt vmcnt(5)
	ds_write_b128 v170, v[32:35] offset:128
	s_waitcnt vmcnt(3)
	ds_write_b128 v170, v[36:39] offset:256
	s_waitcnt vmcnt(1)
	ds_write_b128 v170, v[40:43] offset:384
	global_load_dwordx4 v[28:31], v[162:163], off
	global_load_dwordx4 v[32:35], v[162:163], off offset:128
	global_load_dwordx4 v[36:39], v[162:163], off offset:256
	global_load_dwordx4 v[40:43], v[162:163], off offset:384
	s_waitcnt lgkmcnt(0)
	s_barrier
	ds_read_b128 v[204:207], v174
	ds_read_b128 v[208:211], v174 offset:8448
	ds_read_b128 v[218:221], v174 offset:16896
	ds_read_b128 v[224:227], v174 offset:25344
	ds_read_b128 v[228:231], v174 offset:64
	ds_read_b128 v[232:235], v174 offset:8512
	ds_read_b128 v[236:239], v174 offset:16960
	ds_read_b128 v[240:243], v174 offset:25408
	s_waitcnt lgkmcnt(7)
	v_mfma_f32_16x16x32_bf16 v[68:71], v[204:207], v[64:67], 0
	ds_read_b128 v[204:207], v174 offset:128
	s_waitcnt lgkmcnt(7)
	v_mfma_f32_16x16x32_bf16 v[72:75], v[208:211], v[64:67], 0
	ds_read_b128 v[208:211], v174 offset:8576
	s_waitcnt lgkmcnt(7)
	v_mfma_f32_16x16x32_bf16 v[76:79], v[218:221], v[64:67], 0
	ds_read_b128 v[218:221], v174 offset:17024
	s_waitcnt lgkmcnt(7)
	v_mfma_f32_16x16x32_bf16 v[80:83], v[224:227], v[64:67], 0
	ds_read_b128 v[224:227], v174 offset:25472
	s_waitcnt lgkmcnt(7)
	v_mfma_f32_16x16x32_bf16 v[68:71], v[228:231], v[60:63], v[68:71]
	ds_read_b128 v[228:231], v174 offset:192
	s_waitcnt lgkmcnt(7)
	v_mfma_f32_16x16x32_bf16 v[72:75], v[232:235], v[60:63], v[72:75]
	ds_read_b128 v[232:235], v174 offset:8640
	s_waitcnt lgkmcnt(7)
	v_mfma_f32_16x16x32_bf16 v[76:79], v[236:239], v[60:63], v[76:79]
	ds_read_b128 v[236:239], v174 offset:17088
	s_waitcnt lgkmcnt(7)
	v_mfma_f32_16x16x32_bf16 v[80:83], v[240:243], v[60:63], v[80:83]
	ds_read_b128 v[240:243], v174 offset:25536
	s_waitcnt lgkmcnt(7)
	v_mfma_f32_16x16x32_bf16 v[68:71], v[204:207], v[56:59], v[68:71]
	ds_read_b128 v[204:207], v174 offset:256
	s_waitcnt lgkmcnt(7)
	v_mfma_f32_16x16x32_bf16 v[72:75], v[208:211], v[56:59], v[72:75]
	ds_read_b128 v[208:211], v174 offset:8704
	s_waitcnt lgkmcnt(7)
	v_mfma_f32_16x16x32_bf16 v[76:79], v[218:221], v[56:59], v[76:79]
	ds_read_b128 v[218:221], v174 offset:17152
	s_waitcnt lgkmcnt(7)
	v_mfma_f32_16x16x32_bf16 v[80:83], v[224:227], v[56:59], v[80:83]
	ds_read_b128 v[224:227], v174 offset:25600
	s_waitcnt lgkmcnt(7)
	v_mfma_f32_16x16x32_bf16 v[68:71], v[228:231], v[52:55], v[68:71]
	ds_read_b128 v[228:231], v174 offset:320
	s_waitcnt lgkmcnt(7)
	v_mfma_f32_16x16x32_bf16 v[72:75], v[232:235], v[52:55], v[72:75]
	ds_read_b128 v[232:235], v174 offset:8768
	s_waitcnt lgkmcnt(7)
	v_mfma_f32_16x16x32_bf16 v[76:79], v[236:239], v[52:55], v[76:79]
	ds_read_b128 v[236:239], v174 offset:17216
	s_waitcnt lgkmcnt(7)
	v_mfma_f32_16x16x32_bf16 v[80:83], v[240:243], v[52:55], v[80:83]
	ds_read_b128 v[240:243], v174 offset:25664
	s_waitcnt lgkmcnt(7)
	v_mfma_f32_16x16x32_bf16 v[68:71], v[204:207], v[48:51], v[68:71]
	ds_read_b128 v[204:207], v174 offset:384
	s_waitcnt lgkmcnt(7)
	v_mfma_f32_16x16x32_bf16 v[72:75], v[208:211], v[48:51], v[72:75]
	ds_read_b128 v[208:211], v174 offset:8832
	s_waitcnt lgkmcnt(7)
	v_mfma_f32_16x16x32_bf16 v[76:79], v[218:221], v[48:51], v[76:79]
	ds_read_b128 v[218:221], v174 offset:17280
	s_waitcnt lgkmcnt(7)
	v_mfma_f32_16x16x32_bf16 v[80:83], v[224:227], v[48:51], v[80:83]
	ds_read_b128 v[224:227], v174 offset:25728
	s_waitcnt lgkmcnt(7)
	v_mfma_f32_16x16x32_bf16 v[68:71], v[228:231], v[44:47], v[68:71]
	ds_read_b128 v[228:231], v174 offset:448
	s_waitcnt lgkmcnt(7)
	v_mfma_f32_16x16x32_bf16 v[72:75], v[232:235], v[44:47], v[72:75]
	ds_read_b128 v[232:235], v174 offset:8896
	s_waitcnt lgkmcnt(7)
	v_mfma_f32_16x16x32_bf16 v[76:79], v[236:239], v[44:47], v[76:79]
	ds_read_b128 v[236:239], v174 offset:17344
	s_waitcnt lgkmcnt(7)
	v_mfma_f32_16x16x32_bf16 v[80:83], v[240:243], v[44:47], v[80:83]
	s_waitcnt lgkmcnt(6)
	v_mfma_f32_16x16x32_bf16 v[68:71], v[204:207], v[8:11], v[68:71]
	s_waitcnt lgkmcnt(5)
	v_mfma_f32_16x16x32_bf16 v[72:75], v[208:211], v[8:11], v[72:75]
	s_waitcnt lgkmcnt(4)
	v_mfma_f32_16x16x32_bf16 v[76:79], v[218:221], v[8:11], v[76:79]
	s_waitcnt lgkmcnt(3)
	v_mfma_f32_16x16x32_bf16 v[80:83], v[224:227], v[8:11], v[80:83]
	s_waitcnt lgkmcnt(2)
	v_mfma_f32_16x16x32_bf16 v[68:71], v[228:231], v[4:7], v[68:71]
	s_waitcnt lgkmcnt(1)
	v_mfma_f32_16x16x32_bf16 v[72:75], v[232:235], v[4:7], v[72:75]
	s_waitcnt lgkmcnt(0)
	v_mfma_f32_16x16x32_bf16 v[76:79], v[236:239], v[4:7], v[76:79]
	s_nop 7
	ds_read_b128 v[84:87], v174 offset:25792
	ds_write_b128 v168, v[12:15]
	ds_write_b128 v168, v[16:19] offset:128
	ds_write_b128 v168, v[20:23] offset:256
	s_waitcnt vmcnt(4)
	ds_write_b128 v168, v[24:27] offset:384
	global_load_dwordx4 v[12:15], v[160:161], off
	global_load_dwordx4 v[16:19], v[160:161], off offset:128
	global_load_dwordx4 v[20:23], v[160:161], off offset:256
	global_load_dwordx4 v[24:27], v[160:161], off offset:384
	s_waitcnt lgkmcnt(0)
	s_barrier
	s_waitcnt lgkmcnt(4)
	v_mfma_f32_16x16x32_bf16 v[80:83], v[84:87], v[4:7], v[80:83]
	ds_read_b128 v[204:207], v173
	ds_read_b128 v[208:211], v173 offset:8448
	ds_read_b128 v[218:221], v173 offset:16896
	ds_read_b128 v[224:227], v173 offset:25344
	ds_read_b128 v[228:231], v173 offset:64
	ds_read_b128 v[232:235], v173 offset:8512
	ds_read_b128 v[236:239], v173 offset:16960
	ds_read_b128 v[240:243], v173 offset:25408
	s_waitcnt lgkmcnt(7)
	v_mfma_f32_16x16x32_bf16 v[84:87], v[204:207], v[64:67], 0
	ds_read_b128 v[204:207], v173 offset:128
	s_waitcnt lgkmcnt(7)
	v_mfma_f32_16x16x32_bf16 v[88:91], v[208:211], v[64:67], 0
	ds_read_b128 v[208:211], v173 offset:8576
	s_waitcnt lgkmcnt(7)
	v_mfma_f32_16x16x32_bf16 v[92:95], v[218:221], v[64:67], 0
	ds_read_b128 v[218:221], v173 offset:17024
	s_waitcnt lgkmcnt(7)
	v_mfma_f32_16x16x32_bf16 v[96:99], v[224:227], v[64:67], 0
	ds_read_b128 v[224:227], v173 offset:25472
	s_waitcnt lgkmcnt(7)
	v_mfma_f32_16x16x32_bf16 v[84:87], v[228:231], v[60:63], v[84:87]
	ds_read_b128 v[228:231], v173 offset:192
	s_waitcnt lgkmcnt(7)
	v_mfma_f32_16x16x32_bf16 v[88:91], v[232:235], v[60:63], v[88:91]
	ds_read_b128 v[232:235], v173 offset:8640
	s_waitcnt lgkmcnt(7)
	v_mfma_f32_16x16x32_bf16 v[92:95], v[236:239], v[60:63], v[92:95]
	ds_read_b128 v[236:239], v173 offset:17088
	s_waitcnt lgkmcnt(7)
	v_mfma_f32_16x16x32_bf16 v[96:99], v[240:243], v[60:63], v[96:99]
	ds_read_b128 v[240:243], v173 offset:25536
	s_waitcnt lgkmcnt(7)
	v_mfma_f32_16x16x32_bf16 v[84:87], v[204:207], v[56:59], v[84:87]
	ds_read_b128 v[204:207], v173 offset:256
	s_waitcnt lgkmcnt(7)
	v_mfma_f32_16x16x32_bf16 v[88:91], v[208:211], v[56:59], v[88:91]
	ds_read_b128 v[208:211], v173 offset:8704
	s_waitcnt lgkmcnt(7)
	v_mfma_f32_16x16x32_bf16 v[92:95], v[218:221], v[56:59], v[92:95]
	ds_read_b128 v[218:221], v173 offset:17152
	s_waitcnt lgkmcnt(7)
	v_mfma_f32_16x16x32_bf16 v[96:99], v[224:227], v[56:59], v[96:99]
	ds_read_b128 v[224:227], v173 offset:25600
	s_waitcnt lgkmcnt(7)
	v_mfma_f32_16x16x32_bf16 v[84:87], v[228:231], v[52:55], v[84:87]
	ds_read_b128 v[228:231], v173 offset:320
	s_waitcnt lgkmcnt(7)
	v_mfma_f32_16x16x32_bf16 v[88:91], v[232:235], v[52:55], v[88:91]
	ds_read_b128 v[232:235], v173 offset:8768
	s_waitcnt lgkmcnt(7)
	v_mfma_f32_16x16x32_bf16 v[92:95], v[236:239], v[52:55], v[92:95]
	ds_read_b128 v[236:239], v173 offset:17216
	s_waitcnt lgkmcnt(7)
	v_mfma_f32_16x16x32_bf16 v[96:99], v[240:243], v[52:55], v[96:99]
	ds_read_b128 v[240:243], v173 offset:25664
	s_waitcnt lgkmcnt(7)
	v_mfma_f32_16x16x32_bf16 v[84:87], v[204:207], v[48:51], v[84:87]
	ds_read_b128 v[204:207], v173 offset:384
	s_waitcnt lgkmcnt(7)
	v_mfma_f32_16x16x32_bf16 v[88:91], v[208:211], v[48:51], v[88:91]
	ds_read_b128 v[208:211], v173 offset:8832
	s_waitcnt lgkmcnt(7)
	v_mfma_f32_16x16x32_bf16 v[92:95], v[218:221], v[48:51], v[92:95]
	ds_read_b128 v[218:221], v173 offset:17280
	s_waitcnt lgkmcnt(7)
	v_mfma_f32_16x16x32_bf16 v[96:99], v[224:227], v[48:51], v[96:99]
	ds_read_b128 v[224:227], v173 offset:25728
	s_waitcnt lgkmcnt(7)
	v_mfma_f32_16x16x32_bf16 v[84:87], v[228:231], v[44:47], v[84:87]
	ds_read_b128 v[228:231], v173 offset:448
	s_waitcnt lgkmcnt(7)
	v_mfma_f32_16x16x32_bf16 v[88:91], v[232:235], v[44:47], v[88:91]
	ds_read_b128 v[232:235], v173 offset:8896
	s_waitcnt lgkmcnt(7)
	v_mfma_f32_16x16x32_bf16 v[92:95], v[236:239], v[44:47], v[92:95]
	ds_read_b128 v[236:239], v173 offset:17344
	s_waitcnt lgkmcnt(7)
	v_mfma_f32_16x16x32_bf16 v[96:99], v[240:243], v[44:47], v[96:99]
	s_waitcnt lgkmcnt(6)
	v_mfma_f32_16x16x32_bf16 v[84:87], v[204:207], v[8:11], v[84:87]
	s_waitcnt lgkmcnt(5)
	v_mfma_f32_16x16x32_bf16 v[88:91], v[208:211], v[8:11], v[88:91]
	s_waitcnt lgkmcnt(4)
	v_mfma_f32_16x16x32_bf16 v[92:95], v[218:221], v[8:11], v[92:95]
	s_waitcnt lgkmcnt(3)
	v_mfma_f32_16x16x32_bf16 v[96:99], v[224:227], v[8:11], v[96:99]
	s_waitcnt lgkmcnt(2)
	v_mfma_f32_16x16x32_bf16 v[84:87], v[228:231], v[4:7], v[84:87]
	s_waitcnt lgkmcnt(1)
	v_mfma_f32_16x16x32_bf16 v[88:91], v[232:235], v[4:7], v[88:91]
	s_waitcnt lgkmcnt(0)
	v_mfma_f32_16x16x32_bf16 v[92:95], v[236:239], v[4:7], v[92:95]
	s_nop 7
	ds_read_b128 v[100:103], v173 offset:25792
	s_waitcnt vmcnt(7)
	ds_write_b128 v170, v[28:31]
	s_waitcnt vmcnt(6)
	ds_write_b128 v170, v[32:35] offset:128
	s_waitcnt vmcnt(5)
	ds_write_b128 v170, v[36:39] offset:256
	s_waitcnt vmcnt(4)
	ds_write_b128 v170, v[40:43] offset:384
	global_load_dwordx4 v[28:31], v[166:167], off offset:2048
	global_load_dwordx4 v[32:35], v[166:167], off offset:2176
	global_load_dwordx4 v[36:39], v[166:167], off offset:2304
	global_load_dwordx4 v[40:43], v[166:167], off offset:2432
	s_waitcnt lgkmcnt(0)
	s_barrier
	s_waitcnt lgkmcnt(4)
	v_mfma_f32_16x16x32_bf16 v[96:99], v[100:103], v[4:7], v[96:99]
	ds_read_b128 v[204:207], v174
	ds_read_b128 v[208:211], v174 offset:8448
	ds_read_b128 v[218:221], v174 offset:16896
	ds_read_b128 v[224:227], v174 offset:25344
	ds_read_b128 v[228:231], v174 offset:64
	ds_read_b128 v[232:235], v174 offset:8512
	ds_read_b128 v[236:239], v174 offset:16960
	ds_read_b128 v[240:243], v174 offset:25408
	s_waitcnt lgkmcnt(7)
	v_mfma_f32_16x16x32_bf16 v[100:103], v[204:207], v[64:67], 0
	ds_read_b128 v[204:207], v174 offset:128
	s_waitcnt lgkmcnt(7)
	v_mfma_f32_16x16x32_bf16 v[104:107], v[208:211], v[64:67], 0
	ds_read_b128 v[208:211], v174 offset:8576
	s_waitcnt lgkmcnt(7)
	v_mfma_f32_16x16x32_bf16 v[108:111], v[218:221], v[64:67], 0
	ds_read_b128 v[218:221], v174 offset:17024
	s_waitcnt lgkmcnt(7)
	v_mfma_f32_16x16x32_bf16 v[112:115], v[224:227], v[64:67], 0
	ds_read_b128 v[224:227], v174 offset:25472
	s_waitcnt lgkmcnt(7)
	v_mfma_f32_16x16x32_bf16 v[100:103], v[228:231], v[60:63], v[100:103]
	ds_read_b128 v[228:231], v174 offset:192
	s_waitcnt lgkmcnt(7)
	v_mfma_f32_16x16x32_bf16 v[104:107], v[232:235], v[60:63], v[104:107]
	ds_read_b128 v[232:235], v174 offset:8640
	s_waitcnt lgkmcnt(7)
	v_mfma_f32_16x16x32_bf16 v[108:111], v[236:239], v[60:63], v[108:111]
	ds_read_b128 v[236:239], v174 offset:17088
	s_waitcnt lgkmcnt(7)
	v_mfma_f32_16x16x32_bf16 v[112:115], v[240:243], v[60:63], v[112:115]
	ds_read_b128 v[240:243], v174 offset:25536
	s_waitcnt lgkmcnt(7)
	v_mfma_f32_16x16x32_bf16 v[100:103], v[204:207], v[56:59], v[100:103]
	ds_read_b128 v[204:207], v174 offset:256
	s_waitcnt lgkmcnt(7)
	v_mfma_f32_16x16x32_bf16 v[104:107], v[208:211], v[56:59], v[104:107]
	ds_read_b128 v[208:211], v174 offset:8704
	s_waitcnt lgkmcnt(7)
	v_mfma_f32_16x16x32_bf16 v[108:111], v[218:221], v[56:59], v[108:111]
	ds_read_b128 v[218:221], v174 offset:17152
	s_waitcnt lgkmcnt(7)
	v_mfma_f32_16x16x32_bf16 v[112:115], v[224:227], v[56:59], v[112:115]
	ds_read_b128 v[224:227], v174 offset:25600
	s_waitcnt lgkmcnt(7)
	v_mfma_f32_16x16x32_bf16 v[100:103], v[228:231], v[52:55], v[100:103]
	ds_read_b128 v[228:231], v174 offset:320
	s_waitcnt lgkmcnt(7)
	v_mfma_f32_16x16x32_bf16 v[104:107], v[232:235], v[52:55], v[104:107]
	ds_read_b128 v[232:235], v174 offset:8768
	s_waitcnt lgkmcnt(7)
	v_mfma_f32_16x16x32_bf16 v[108:111], v[236:239], v[52:55], v[108:111]
	ds_read_b128 v[236:239], v174 offset:17216
	s_waitcnt lgkmcnt(7)
	v_mfma_f32_16x16x32_bf16 v[112:115], v[240:243], v[52:55], v[112:115]
	ds_read_b128 v[240:243], v174 offset:25664
	s_waitcnt lgkmcnt(7)
	v_mfma_f32_16x16x32_bf16 v[100:103], v[204:207], v[48:51], v[100:103]
	ds_read_b128 v[204:207], v174 offset:384
	s_waitcnt lgkmcnt(7)
	v_mfma_f32_16x16x32_bf16 v[104:107], v[208:211], v[48:51], v[104:107]
	ds_read_b128 v[208:211], v174 offset:8832
	s_waitcnt lgkmcnt(7)
	v_mfma_f32_16x16x32_bf16 v[108:111], v[218:221], v[48:51], v[108:111]
	ds_read_b128 v[218:221], v174 offset:17280
	s_waitcnt lgkmcnt(7)
	v_mfma_f32_16x16x32_bf16 v[112:115], v[224:227], v[48:51], v[112:115]
	ds_read_b128 v[224:227], v174 offset:25728
	s_waitcnt lgkmcnt(7)
	v_mfma_f32_16x16x32_bf16 v[100:103], v[228:231], v[44:47], v[100:103]
	ds_read_b128 v[228:231], v174 offset:448
	s_waitcnt lgkmcnt(7)
	v_mfma_f32_16x16x32_bf16 v[104:107], v[232:235], v[44:47], v[104:107]
	ds_read_b128 v[232:235], v174 offset:8896
	s_waitcnt lgkmcnt(7)
	v_mfma_f32_16x16x32_bf16 v[108:111], v[236:239], v[44:47], v[108:111]
	ds_read_b128 v[236:239], v174 offset:17344
	s_waitcnt lgkmcnt(7)
	v_mfma_f32_16x16x32_bf16 v[112:115], v[240:243], v[44:47], v[112:115]
	s_waitcnt lgkmcnt(6)
	v_mfma_f32_16x16x32_bf16 v[100:103], v[204:207], v[8:11], v[100:103]
	s_waitcnt lgkmcnt(5)
	v_mfma_f32_16x16x32_bf16 v[104:107], v[208:211], v[8:11], v[104:107]
	s_waitcnt lgkmcnt(4)
	v_mfma_f32_16x16x32_bf16 v[108:111], v[218:221], v[8:11], v[108:111]
	s_waitcnt lgkmcnt(3)
	v_mfma_f32_16x16x32_bf16 v[112:115], v[224:227], v[8:11], v[112:115]
	s_waitcnt lgkmcnt(2)
	v_mfma_f32_16x16x32_bf16 v[100:103], v[228:231], v[4:7], v[100:103]
	s_waitcnt lgkmcnt(1)
	v_mfma_f32_16x16x32_bf16 v[104:107], v[232:235], v[4:7], v[104:107]
	s_waitcnt lgkmcnt(0)
	v_mfma_f32_16x16x32_bf16 v[108:111], v[236:239], v[4:7], v[108:111]
	s_nop 7
	ds_read_b128 v[116:119], v174 offset:25792
	s_waitcnt vmcnt(7)
	ds_write_b128 v168, v[12:15]
	s_waitcnt vmcnt(6)
	ds_write_b128 v168, v[16:19] offset:128
	s_waitcnt vmcnt(5)
	ds_write_b128 v168, v[20:23] offset:256
	s_waitcnt vmcnt(4)
	ds_write_b128 v168, v[24:27] offset:384
	global_load_dwordx4 v[12:15], v[164:165], off offset:2048
	global_load_dwordx4 v[16:19], v[164:165], off offset:2176
	global_load_dwordx4 v[20:23], v[164:165], off offset:2304
	global_load_dwordx4 v[24:27], v[164:165], off offset:2432
	s_waitcnt lgkmcnt(0)
	s_barrier
	s_waitcnt lgkmcnt(4)
	v_mfma_f32_16x16x32_bf16 v[112:115], v[116:119], v[4:7], v[112:115]
	ds_read_b128 v[116:119], v173
	ds_read_b128 v[120:123], v173 offset:64
	ds_read_b128 v[124:127], v173 offset:8512
	s_waitcnt lgkmcnt(2)
	v_mfma_f32_16x16x32_bf16 v[116:119], v[116:119], v[64:67], 0
	ds_read_b128 v[128:131], v173 offset:16960
	s_waitcnt lgkmcnt(2)
	v_mfma_f32_16x16x32_bf16 v[116:119], v[120:123], v[60:63], v[116:119]
	ds_read_b128 v[120:123], v173 offset:128
	s_waitcnt lgkmcnt(0)
	v_mfma_f32_16x16x32_bf16 v[116:119], v[120:123], v[56:59], v[116:119]
	ds_read_b128 v[120:123], v173 offset:192
	s_waitcnt lgkmcnt(0)
	v_mfma_f32_16x16x32_bf16 v[116:119], v[120:123], v[52:55], v[116:119]
	ds_read_b128 v[120:123], v173 offset:256
	s_waitcnt lgkmcnt(0)
	v_mfma_f32_16x16x32_bf16 v[116:119], v[120:123], v[48:51], v[116:119]
	ds_read_b128 v[120:123], v173 offset:320
	s_waitcnt lgkmcnt(0)
	v_mfma_f32_16x16x32_bf16 v[116:119], v[120:123], v[44:47], v[116:119]
	ds_read_b128 v[120:123], v173 offset:384
	s_waitcnt lgkmcnt(0)
	v_mfma_f32_16x16x32_bf16 v[116:119], v[120:123], v[8:11], v[116:119]
	ds_read_b128 v[120:123], v173 offset:448
	s_waitcnt lgkmcnt(0)
	v_mfma_f32_16x16x32_bf16 v[116:119], v[120:123], v[4:7], v[116:119]
	ds_read_b128 v[120:123], v173 offset:8448
	s_waitcnt lgkmcnt(0)
	v_mfma_f32_16x16x32_bf16 v[120:123], v[120:123], v[64:67], 0
	v_mfma_f32_16x16x32_bf16 v[120:123], v[124:127], v[60:63], v[120:123]
	ds_read_b128 v[124:127], v173 offset:8576
	s_waitcnt lgkmcnt(0)
	v_mfma_f32_16x16x32_bf16 v[120:123], v[124:127], v[56:59], v[120:123]
	ds_read_b128 v[124:127], v173 offset:8640
	s_waitcnt lgkmcnt(0)
	v_mfma_f32_16x16x32_bf16 v[120:123], v[124:127], v[52:55], v[120:123]
	ds_read_b128 v[124:127], v173 offset:8704
	s_waitcnt lgkmcnt(0)
	v_mfma_f32_16x16x32_bf16 v[120:123], v[124:127], v[48:51], v[120:123]
	ds_read_b128 v[124:127], v173 offset:8768
	s_waitcnt lgkmcnt(0)
	v_mfma_f32_16x16x32_bf16 v[120:123], v[124:127], v[44:47], v[120:123]
	ds_read_b128 v[124:127], v173 offset:8832
	s_waitcnt lgkmcnt(0)
	v_mfma_f32_16x16x32_bf16 v[120:123], v[124:127], v[8:11], v[120:123]
	ds_read_b128 v[124:127], v173 offset:8896
	s_waitcnt lgkmcnt(0)
	v_mfma_f32_16x16x32_bf16 v[120:123], v[124:127], v[4:7], v[120:123]
	ds_read_b128 v[124:127], v173 offset:16896
	s_waitcnt lgkmcnt(0)
	v_mfma_f32_16x16x32_bf16 v[124:127], v[124:127], v[64:67], 0
	v_mfma_f32_16x16x32_bf16 v[124:127], v[128:131], v[60:63], v[124:127]
	ds_read_b128 v[128:131], v173 offset:17024
	s_waitcnt lgkmcnt(0)
	v_mfma_f32_16x16x32_bf16 v[124:127], v[128:131], v[56:59], v[124:127]
	ds_read_b128 v[128:131], v173 offset:17088
	s_waitcnt lgkmcnt(0)
	v_mfma_f32_16x16x32_bf16 v[124:127], v[128:131], v[52:55], v[124:127]
	ds_read_b128 v[128:131], v173 offset:17152
	s_waitcnt lgkmcnt(0)
	v_mfma_f32_16x16x32_bf16 v[124:127], v[128:131], v[48:51], v[124:127]
	ds_read_b128 v[128:131], v173 offset:17216
	s_waitcnt lgkmcnt(0)
	v_mfma_f32_16x16x32_bf16 v[124:127], v[128:131], v[44:47], v[124:127]
	ds_read_b128 v[128:131], v173 offset:17280
	s_waitcnt lgkmcnt(0)
	v_mfma_f32_16x16x32_bf16 v[124:127], v[128:131], v[8:11], v[124:127]
	ds_read_b128 v[128:131], v173 offset:17344
	s_waitcnt lgkmcnt(0)
	v_mfma_f32_16x16x32_bf16 v[124:127], v[128:131], v[4:7], v[124:127]
	ds_read_b128 v[128:131], v173 offset:25344
	s_waitcnt lgkmcnt(0)
	v_mfma_f32_16x16x32_bf16 v[64:67], v[128:131], v[64:67], 0
	ds_read_b128 v[128:131], v173 offset:25408
	s_waitcnt lgkmcnt(0)
	v_mfma_f32_16x16x32_bf16 v[60:63], v[128:131], v[60:63], v[64:67]
	s_nop 4
	ds_read_b128 v[64:67], v173 offset:25472
	s_waitcnt lgkmcnt(0)
	v_mfma_f32_16x16x32_bf16 v[56:59], v[64:67], v[56:59], v[60:63]
	s_nop 2
	ds_read_b128 v[60:63], v173 offset:25536
	s_waitcnt lgkmcnt(0)
	v_mfma_f32_16x16x32_bf16 v[52:55], v[60:63], v[52:55], v[56:59]
	s_nop 2
	ds_read_b128 v[56:59], v173 offset:25600
	s_waitcnt lgkmcnt(0)
	v_mfma_f32_16x16x32_bf16 v[48:51], v[56:59], v[48:51], v[52:55]
	s_nop 2
	ds_read_b128 v[52:55], v173 offset:25664
	s_waitcnt lgkmcnt(0)
	v_mfma_f32_16x16x32_bf16 v[44:47], v[52:55], v[44:47], v[48:51]
	s_nop 2
	ds_read_b128 v[48:51], v173 offset:25728
	s_waitcnt lgkmcnt(0)
	v_mfma_f32_16x16x32_bf16 v[8:11], v[48:51], v[8:11], v[44:47]
	s_nop 2
	ds_read_b128 v[44:47], v173 offset:25792
	s_waitcnt vmcnt(7)
	ds_write_b128 v170, v[28:31]
	s_waitcnt vmcnt(6)
	ds_write_b128 v170, v[32:35] offset:128
	s_waitcnt vmcnt(5)
	ds_write_b128 v170, v[36:39] offset:256
	s_waitcnt vmcnt(4)
	ds_write_b128 v170, v[40:43] offset:384
	global_load_dwordx4 v[28:31], v[162:163], off offset:2048
	global_load_dwordx4 v[32:35], v[162:163], off offset:2176
	global_load_dwordx4 v[36:39], v[162:163], off offset:2304
	global_load_dwordx4 v[40:43], v[162:163], off offset:2432
	s_waitcnt lgkmcnt(4)
	v_mfma_f32_16x16x32_bf16 v[4:7], v[44:47], v[4:7], v[8:11]
	s_nop 2
	v_max_f32_e32 v8, v71, v71
	v_max_f32_e32 v9, v70, v70
	v_max_f32_e32 v8, v9, v8
	v_max_f32_e32 v9, v75, v75
	v_max_f32_e32 v10, v74, v74
	v_max_f32_e32 v9, v10, v9
	v_max3_f32 v8, v68, v69, v8
	v_max3_f32 v9, v72, v73, v9
	v_max3_f32 v8, v8, s7, v9
	v_max_f32_e32 v9, v79, v79
	v_max_f32_e32 v10, v78, v78
	v_max_f32_e32 v9, v10, v9
	v_max_f32_e32 v10, v83, v83
	v_max_f32_e32 v11, v82, v82
	v_max_f32_e32 v10, v11, v10
	v_max3_f32 v9, v76, v77, v9
	v_max3_f32 v10, v80, v81, v10
	v_max3_f32 v8, v8, v9, v10
	v_max_f32_e32 v9, v87, v87
	v_max_f32_e32 v10, v86, v86
	v_max_f32_e32 v9, v10, v9
	v_max_f32_e32 v10, v91, v91
	v_max_f32_e32 v11, v90, v90
	v_max_f32_e32 v10, v11, v10
	v_max3_f32 v9, v84, v85, v9
	v_max3_f32 v10, v88, v89, v10
	v_max3_f32 v8, v8, v9, v10
	v_max_f32_e32 v9, v95, v95
	v_max_f32_e32 v10, v94, v94
	v_max_f32_e32 v9, v10, v9
	v_max_f32_e32 v10, v99, v99
	v_max_f32_e32 v11, v98, v98
	v_max_f32_e32 v10, v11, v10
	v_max3_f32 v9, v92, v93, v9
	v_max3_f32 v10, v96, v97, v10
	v_max3_f32 v8, v8, v9, v10
	v_max_f32_e32 v9, v103, v103
	v_max_f32_e32 v10, v102, v102
	v_max_f32_e32 v9, v10, v9
	v_max_f32_e32 v10, v107, v107
	v_max_f32_e32 v11, v106, v106
	v_max_f32_e32 v10, v11, v10
	v_max3_f32 v9, v100, v101, v9
	v_max3_f32 v10, v104, v105, v10
	v_max3_f32 v8, v8, v9, v10
	v_max_f32_e32 v9, v111, v111
	v_max_f32_e32 v10, v110, v110
	v_max_f32_e32 v9, v10, v9
	v_max_f32_e32 v10, v115, v115
	v_max_f32_e32 v11, v114, v114
	v_max_f32_e32 v10, v11, v10
	v_max3_f32 v9, v108, v109, v9
	v_max3_f32 v10, v112, v113, v10
	v_max3_f32 v8, v8, v9, v10
	v_max_f32_e32 v9, v119, v119
	v_max_f32_e32 v10, v118, v118
	v_max_f32_e32 v9, v10, v9
	v_max_f32_e32 v10, v123, v123
	v_max_f32_e32 v11, v122, v122
	v_max_f32_e32 v10, v11, v10
	v_max3_f32 v9, v116, v117, v9
	v_max3_f32 v10, v120, v121, v10
	v_max3_f32 v8, v8, v9, v10
	v_max_f32_e32 v9, v127, v127
	v_max_f32_e32 v10, v126, v126
	v_max_f32_e32 v9, v10, v9
	v_max_f32_e32 v10, v7, v7
	v_max_f32_e32 v11, v6, v6
	v_max_f32_e32 v10, v11, v10
	v_max3_f32 v9, v124, v125, v9
	v_max3_f32 v10, v4, v5, v10
	v_max3_f32 v8, v8, v9, v10
	ds_bpermute_b32 v9, v171, v8
	s_waitcnt lgkmcnt(0)
	s_barrier
	s_waitcnt lgkmcnt(0)
	v_max_f32_e32 v9, v9, v9
	v_max_f32_e32 v8, v8, v9
	ds_bpermute_b32 v9, v172, v8
	s_waitcnt lgkmcnt(0)
	v_max_f32_e32 v9, v9, v9
	v_max_f32_e32 v52, v8, v9
	v_sub_f32_e32 v8, v68, v52
	v_mul_f32_e32 v8, 0x3d800000, v8
	v_sub_f32_e32 v9, v69, v52
	v_mul_f32_e32 v8, 0x3fb8aa3b, v8
	v_mul_f32_e32 v9, 0x3d800000, v9
	v_exp_f32_e32 v8, v8
	v_mul_f32_e32 v9, 0x3fb8aa3b, v9
	v_exp_f32_e32 v9, v9
	v_sub_f32_e32 v56, v82, v52
	v_add_f32_e32 v10, 0, v8
	v_mul_f32_e32 v56, 0x3d800000, v56
	v_add_f32_e32 v11, v9, v10
	v_sub_f32_e32 v10, v70, v52
	v_mul_f32_e32 v10, 0x3d800000, v10
	v_mul_f32_e32 v10, 0x3fb8aa3b, v10
	v_exp_f32_e32 v10, v10
	v_mul_f32_e32 v56, 0x3fb8aa3b, v56
	v_exp_f32_e32 v60, v56
	v_sub_f32_e32 v56, v83, v52
	v_add_f32_e32 v44, v10, v11
	v_sub_f32_e32 v11, v71, v52
	v_mul_f32_e32 v56, 0x3d800000, v56
	v_mul_f32_e32 v11, 0x3d800000, v11
	v_mul_f32_e32 v56, 0x3fb8aa3b, v56
	v_mul_f32_e32 v11, 0x3fb8aa3b, v11
	v_exp_f32_e32 v61, v56
	v_sub_f32_e32 v56, v84, v52
	v_exp_f32_e32 v11, v11
	v_mul_f32_e32 v56, 0x3d800000, v56
	v_mul_f32_e32 v56, 0x3fb8aa3b, v56
	v_exp_f32_e32 v62, v56
	v_sub_f32_e32 v56, v85, v52
	v_mul_f32_e32 v56, 0x3d800000, v56
	v_add_f32_e32 v45, v11, v44
	v_sub_f32_e32 v44, v72, v52
	v_mul_f32_e32 v56, 0x3fb8aa3b, v56
	v_mul_f32_e32 v44, 0x3d800000, v44
	v_exp_f32_e32 v63, v56
	v_sub_f32_e32 v56, v86, v52
	v_mul_f32_e32 v44, 0x3fb8aa3b, v44
	v_mul_f32_e32 v56, 0x3d800000, v56
	v_exp_f32_e32 v44, v44
	v_mul_f32_e32 v56, 0x3fb8aa3b, v56
	v_exp_f32_e32 v64, v56
	v_sub_f32_e32 v56, v87, v52
	v_mul_f32_e32 v56, 0x3d800000, v56
	v_mul_f32_e32 v56, 0x3fb8aa3b, v56
	v_add_f32_e32 v46, v44, v45
	v_sub_f32_e32 v45, v73, v52
	v_exp_f32_e32 v65, v56
	v_sub_f32_e32 v56, v88, v52
	v_mul_f32_e32 v45, 0x3d800000, v45
	v_mul_f32_e32 v56, 0x3d800000, v56
	v_mul_f32_e32 v45, 0x3fb8aa3b, v45
	v_mul_f32_e32 v56, 0x3fb8aa3b, v56
	v_exp_f32_e32 v45, v45
	v_exp_f32_e32 v66, v56
	v_sub_f32_e32 v56, v89, v52
	v_mul_f32_e32 v56, 0x3d800000, v56
	v_mul_f32_e32 v56, 0x3fb8aa3b, v56
	v_exp_f32_e32 v67, v56
	v_sub_f32_e32 v56, v90, v52
	v_add_f32_e32 v47, v45, v46
	v_sub_f32_e32 v46, v74, v52
	v_mul_f32_e32 v56, 0x3d800000, v56
	v_mul_f32_e32 v46, 0x3d800000, v46
	v_mul_f32_e32 v56, 0x3fb8aa3b, v56
	v_mul_f32_e32 v46, 0x3fb8aa3b, v46
	v_exp_f32_e32 v68, v56
	v_sub_f32_e32 v56, v91, v52
	v_exp_f32_e32 v46, v46
	v_mul_f32_e32 v56, 0x3d800000, v56
	v_mul_f32_e32 v56, 0x3fb8aa3b, v56
	v_exp_f32_e32 v69, v56
	v_sub_f32_e32 v56, v92, v52
	v_mul_f32_e32 v56, 0x3d800000, v56
	v_add_f32_e32 v48, v46, v47
	v_sub_f32_e32 v47, v75, v52
	v_mul_f32_e32 v56, 0x3fb8aa3b, v56
	v_mul_f32_e32 v47, 0x3d800000, v47
	v_exp_f32_e32 v70, v56
	v_sub_f32_e32 v56, v93, v52
	v_mul_f32_e32 v47, 0x3fb8aa3b, v47
	v_mul_f32_e32 v56, 0x3d800000, v56
	v_exp_f32_e32 v47, v47
	v_mul_f32_e32 v56, 0x3fb8aa3b, v56
	v_exp_f32_e32 v71, v56
	v_sub_f32_e32 v56, v94, v52
	v_mul_f32_e32 v56, 0x3d800000, v56
	v_mul_f32_e32 v56, 0x3fb8aa3b, v56
	v_add_f32_e32 v49, v47, v48
	v_sub_f32_e32 v48, v76, v52
	v_exp_f32_e32 v72, v56
	v_sub_f32_e32 v56, v95, v52
	v_mul_f32_e32 v48, 0x3d800000, v48
	v_mul_f32_e32 v56, 0x3d800000, v56
	v_mul_f32_e32 v48, 0x3fb8aa3b, v48
	v_mul_f32_e32 v56, 0x3fb8aa3b, v56
	v_exp_f32_e32 v48, v48
	v_exp_f32_e32 v73, v56
	v_sub_f32_e32 v56, v96, v52
	v_mul_f32_e32 v56, 0x3d800000, v56
	v_mul_f32_e32 v56, 0x3fb8aa3b, v56
	v_exp_f32_e32 v74, v56
	v_sub_f32_e32 v56, v97, v52
	v_add_f32_e32 v50, v48, v49
	v_sub_f32_e32 v49, v77, v52
	v_mul_f32_e32 v56, 0x3d800000, v56
	v_mul_f32_e32 v49, 0x3d800000, v49
	v_mul_f32_e32 v56, 0x3fb8aa3b, v56
	v_mul_f32_e32 v49, 0x3fb8aa3b, v49
	v_exp_f32_e32 v75, v56
	v_sub_f32_e32 v56, v98, v52
	v_exp_f32_e32 v49, v49
	v_mul_f32_e32 v56, 0x3d800000, v56
	v_mul_f32_e32 v56, 0x3fb8aa3b, v56
	v_exp_f32_e32 v76, v56
	v_sub_f32_e32 v56, v99, v52
	v_mul_f32_e32 v56, 0x3d800000, v56
	v_add_f32_e32 v51, v49, v50
	v_sub_f32_e32 v50, v78, v52
	v_mul_f32_e32 v56, 0x3fb8aa3b, v56
	v_mul_f32_e32 v50, 0x3d800000, v50
	v_exp_f32_e32 v77, v56
	v_sub_f32_e32 v56, v100, v52
	v_mul_f32_e32 v50, 0x3fb8aa3b, v50
	v_mul_f32_e32 v56, 0x3d800000, v56
	v_exp_f32_e32 v50, v50
	v_mul_f32_e32 v56, 0x3fb8aa3b, v56
	v_exp_f32_e32 v78, v56
	v_sub_f32_e32 v56, v101, v52
	v_mul_f32_e32 v56, 0x3d800000, v56
	v_mul_f32_e32 v56, 0x3fb8aa3b, v56
	v_add_f32_e32 v53, v50, v51
	v_sub_f32_e32 v51, v79, v52
	v_exp_f32_e32 v79, v56
	v_sub_f32_e32 v56, v102, v52
	v_mul_f32_e32 v56, 0x3d800000, v56
	v_mul_f32_e32 v56, 0x3fb8aa3b, v56
	v_sub_f32_e32 v54, v80, v52
	v_exp_f32_e32 v80, v56
	v_sub_f32_e32 v56, v103, v52
	v_mul_f32_e32 v56, 0x3d800000, v56
	v_mul_f32_e32 v56, 0x3fb8aa3b, v56
	v_sub_f32_e32 v55, v81, v52
	v_exp_f32_e32 v81, v56
	v_sub_f32_e32 v56, v104, v52
	v_mul_f32_e32 v56, 0x3d800000, v56
	v_mul_f32_e32 v56, 0x3fb8aa3b, v56
	v_exp_f32_e32 v82, v56
	v_sub_f32_e32 v56, v105, v52
	v_mul_f32_e32 v56, 0x3d800000, v56
	v_mul_f32_e32 v56, 0x3fb8aa3b, v56
	v_exp_f32_e32 v83, v56
	v_sub_f32_e32 v56, v106, v52
	v_mul_f32_e32 v56, 0x3d800000, v56
	v_mul_f32_e32 v56, 0x3fb8aa3b, v56
	v_exp_f32_e32 v84, v56
	v_sub_f32_e32 v56, v107, v52
	v_mul_f32_e32 v56, 0x3d800000, v56
	v_mul_f32_e32 v56, 0x3fb8aa3b, v56
	v_exp_f32_e32 v85, v56
	v_sub_f32_e32 v56, v108, v52
	v_mul_f32_e32 v56, 0x3d800000, v56
	v_mul_f32_e32 v56, 0x3fb8aa3b, v56
	v_exp_f32_e32 v86, v56
	v_sub_f32_e32 v56, v109, v52
	v_mul_f32_e32 v56, 0x3d800000, v56
	v_mul_f32_e32 v56, 0x3fb8aa3b, v56
	v_exp_f32_e32 v87, v56
	v_sub_f32_e32 v56, v110, v52
	v_mul_f32_e32 v56, 0x3d800000, v56
	v_mul_f32_e32 v56, 0x3fb8aa3b, v56
	v_exp_f32_e32 v88, v56
	v_sub_f32_e32 v56, v111, v52
	v_mul_f32_e32 v51, 0x3d800000, v51
	v_mul_f32_e32 v56, 0x3d800000, v56
	v_mul_f32_e32 v51, 0x3fb8aa3b, v51
	v_mul_f32_e32 v54, 0x3d800000, v54
	v_mul_f32_e32 v56, 0x3fb8aa3b, v56
	v_exp_f32_e32 v51, v51
	v_mul_f32_e32 v54, 0x3fb8aa3b, v54
	v_mul_f32_e32 v55, 0x3d800000, v55
	v_exp_f32_e32 v89, v56
	v_sub_f32_e32 v56, v112, v52
	v_exp_f32_e32 v54, v54
	v_mul_f32_e32 v55, 0x3fb8aa3b, v55
	v_mul_f32_e32 v56, 0x3d800000, v56
	v_exp_f32_e32 v55, v55
	v_mul_f32_e32 v56, 0x3fb8aa3b, v56
	v_exp_f32_e32 v90, v56
	v_sub_f32_e32 v56, v113, v52
	v_add_f32_e32 v53, v51, v53
	v_mul_f32_e32 v56, 0x3d800000, v56
	v_add_f32_e32 v53, v54, v53
	v_mul_f32_e32 v56, 0x3fb8aa3b, v56
	v_add_f32_e32 v53, v55, v53
	v_exp_f32_e32 v91, v56
	v_sub_f32_e32 v56, v114, v52
	v_add_f32_e32 v53, v60, v53
	v_mul_f32_e32 v56, 0x3d800000, v56
	v_add_f32_e32 v53, v61, v53
	v_mul_f32_e32 v56, 0x3fb8aa3b, v56
	v_add_f32_e32 v53, v62, v53
	v_exp_f32_e32 v92, v56
	v_sub_f32_e32 v56, v115, v52
	v_add_f32_e32 v53, v63, v53
	v_mul_f32_e32 v56, 0x3d800000, v56
	v_add_f32_e32 v53, v64, v53
	v_mul_f32_e32 v56, 0x3fb8aa3b, v56
	v_add_f32_e32 v53, v65, v53
	v_exp_f32_e32 v93, v56
	v_sub_f32_e32 v56, v116, v52
	v_add_f32_e32 v53, v66, v53
	v_mul_f32_e32 v56, 0x3d800000, v56
	v_add_f32_e32 v53, v67, v53
	v_mul_f32_e32 v56, 0x3fb8aa3b, v56
	v_add_f32_e32 v53, v68, v53
	v_exp_f32_e32 v139, v56
	v_sub_f32_e32 v56, v117, v52
	v_add_f32_e32 v53, v69, v53
	v_mul_f32_e32 v56, 0x3d800000, v56
	v_add_f32_e32 v53, v70, v53
	v_mul_f32_e32 v56, 0x3fb8aa3b, v56
	v_add_f32_e32 v53, v71, v53
	v_exp_f32_e32 v140, v56
	v_sub_f32_e32 v56, v118, v52
	v_add_f32_e32 v53, v72, v53
	v_mul_f32_e32 v56, 0x3d800000, v56
	v_add_f32_e32 v53, v73, v53
	v_mul_f32_e32 v56, 0x3fb8aa3b, v56
	v_add_f32_e32 v53, v74, v53
	v_exp_f32_e32 v141, v56
	v_sub_f32_e32 v56, v119, v52
	v_add_f32_e32 v53, v75, v53
	v_mul_f32_e32 v56, 0x3d800000, v56
	v_add_f32_e32 v53, v76, v53
	v_mul_f32_e32 v56, 0x3fb8aa3b, v56
	v_add_f32_e32 v53, v77, v53
	v_exp_f32_e32 v142, v56
	v_sub_f32_e32 v56, v120, v52
	v_add_f32_e32 v53, v78, v53
	v_mul_f32_e32 v56, 0x3d800000, v56
	v_add_f32_e32 v53, v79, v53
	v_mul_f32_e32 v56, 0x3fb8aa3b, v56
	v_add_f32_e32 v53, v80, v53
	v_exp_f32_e32 v143, v56
	v_sub_f32_e32 v56, v121, v52
	v_add_f32_e32 v53, v81, v53
	v_mul_f32_e32 v56, 0x3d800000, v56
	v_add_f32_e32 v53, v82, v53
	v_mul_f32_e32 v56, 0x3fb8aa3b, v56
	v_add_f32_e32 v53, v83, v53
	v_exp_f32_e32 v144, v56
	v_sub_f32_e32 v56, v122, v52
	v_add_f32_e32 v53, v84, v53
	v_mul_f32_e32 v56, 0x3d800000, v56
	v_add_f32_e32 v53, v85, v53
	v_mul_f32_e32 v56, 0x3fb8aa3b, v56
	v_add_f32_e32 v53, v86, v53
	v_exp_f32_e32 v145, v56
	v_sub_f32_e32 v56, v123, v52
	v_add_f32_e32 v53, v87, v53
	v_mul_f32_e32 v56, 0x3d800000, v56
	v_add_f32_e32 v53, v88, v53
	v_mul_f32_e32 v56, 0x3fb8aa3b, v56
	v_add_f32_e32 v53, v89, v53
	v_exp_f32_e32 v146, v56
	v_sub_f32_e32 v56, v124, v52
	v_add_f32_e32 v53, v90, v53
	v_mul_f32_e32 v56, 0x3d800000, v56
	v_add_f32_e32 v53, v91, v53
	v_mul_f32_e32 v56, 0x3fb8aa3b, v56
	v_add_f32_e32 v53, v92, v53
	v_exp_f32_e32 v147, v56
	v_sub_f32_e32 v56, v125, v52
	v_add_f32_e32 v53, v93, v53
	v_mul_f32_e32 v56, 0x3d800000, v56
	v_add_f32_e32 v53, v139, v53
	v_mul_f32_e32 v56, 0x3fb8aa3b, v56
	v_add_f32_e32 v53, v140, v53
	v_exp_f32_e32 v148, v56
	v_sub_f32_e32 v56, v126, v52
	v_add_f32_e32 v53, v141, v53
	v_mul_f32_e32 v56, 0x3d800000, v56
	v_add_f32_e32 v53, v142, v53
	v_mul_f32_e32 v56, 0x3fb8aa3b, v56
	v_add_f32_e32 v53, v143, v53
	v_exp_f32_e32 v149, v56
	v_sub_f32_e32 v56, v127, v52
	v_add_f32_e32 v53, v144, v53
	v_mul_f32_e32 v56, 0x3d800000, v56
	v_sub_f32_e32 v4, v4, v52
	v_add_f32_e32 v53, v145, v53
	v_mul_f32_e32 v56, 0x3fb8aa3b, v56
	v_mul_f32_e32 v4, 0x3d800000, v4
	v_sub_f32_e32 v5, v5, v52
	v_add_f32_e32 v53, v146, v53
	v_exp_f32_e32 v150, v56
	v_mul_f32_e32 v4, 0x3fb8aa3b, v4
	v_mul_f32_e32 v5, 0x3d800000, v5
	v_add_f32_e32 v53, v147, v53
	v_exp_f32_e32 v151, v4
	v_mul_f32_e32 v5, 0x3fb8aa3b, v5
	v_add_f32_e32 v53, v148, v53
	v_exp_f32_e32 v152, v5
	v_sub_f32_e32 v5, v6, v52
	v_add_f32_e32 v53, v149, v53
	v_mul_f32_e32 v5, 0x3d800000, v5
	v_add_f32_e32 v53, v150, v53
	v_mul_f32_e32 v5, 0x3fb8aa3b, v5
	v_add_f32_e32 v4, v151, v53
	v_exp_f32_e32 v153, v5
	v_sub_f32_e32 v5, v7, v52
	v_cvt_pk_bf16_f32 v52, v48, v49
	v_cvt_pk_bf16_f32 v53, v50, v51
	v_cvt_pk_bf16_f32 v54, v54, v55
	v_cvt_pk_bf16_f32 v55, v60, v61
	v_cvt_pk_bf16_f32 v48, v62, v63
	v_cvt_pk_bf16_f32 v49, v64, v65
	v_cvt_pk_bf16_f32 v50, v66, v67
	v_cvt_pk_bf16_f32 v51, v68, v69
	ds_read_b64_tr_b16 v[60:61], v169
	ds_read_b64_tr_b16 v[64:65], v169 offset:32
	ds_read_b64_tr_b16 v[62:63], v169 offset:8448
	ds_read_b64_tr_b16 v[66:67], v169 offset:16896
	ds_read_b64_tr_b16 v[68:69], v169 offset:25344
	v_cvt_pk_bf16_f32 v56, v8, v9
	v_cvt_pk_bf16_f32 v57, v10, v11
	v_cvt_pk_bf16_f32 v58, v44, v45
	v_cvt_pk_bf16_f32 v59, v46, v47
	v_cvt_pk_bf16_f32 v44, v70, v71
	v_cvt_pk_bf16_f32 v45, v72, v73
	s_waitcnt lgkmcnt(2)
	v_mfma_f32_16x16x32_bf16 v[60:63], v[60:63], v[56:59], 0
	v_cvt_pk_bf16_f32 v46, v74, v75
	v_cvt_pk_bf16_f32 v47, v76, v77
	v_cvt_pk_bf16_f32 v8, v78, v79
	s_waitcnt lgkmcnt(0)
	v_mfma_f32_16x16x32_bf16 v[60:63], v[66:69], v[52:55], v[60:63]
	ds_read_b64_tr_b16 v[66:67], v169 offset:8480
	ds_read_b64_tr_b16 v[68:69], v169 offset:16928
	ds_read_b64_tr_b16 v[70:71], v169 offset:25376
	v_mul_f32_e32 v5, 0x3d800000, v5
	v_mul_f32_e32 v5, 0x3fb8aa3b, v5
	s_waitcnt lgkmcnt(2)
	v_mfma_f32_16x16x32_bf16 v[64:67], v[64:67], v[56:59], 0
	v_exp_f32_e32 v154, v5
	v_add_f32_e32 v4, v152, v4
	v_add_f32_e32 v4, v153, v4
	s_waitcnt lgkmcnt(0)
	v_mfma_f32_16x16x32_bf16 v[64:67], v[68:71], v[52:55], v[64:67]
	ds_read_b64_tr_b16 v[68:69], v169 offset:64
	ds_read_b64_tr_b16 v[70:71], v169 offset:8512
	ds_read_b64_tr_b16 v[72:73], v169 offset:16960
	ds_read_b64_tr_b16 v[74:75], v169 offset:25408
	v_cvt_pk_bf16_f32 v9, v80, v81
	v_cvt_pk_bf16_f32 v10, v82, v83
	s_waitcnt lgkmcnt(2)
	v_mfma_f32_16x16x32_bf16 v[68:71], v[68:71], v[56:59], 0
	v_add_f32_e32 v4, v154, v4
	ds_bpermute_b32 v5, v171, v4
	v_cvt_pk_bf16_f32 v11, v84, v85
	s_waitcnt lgkmcnt(1)
	v_mfma_f32_16x16x32_bf16 v[68:71], v[72:75], v[52:55], v[68:71]
	ds_read_b64_tr_b16 v[72:73], v169 offset:96
	ds_read_b64_tr_b16 v[74:75], v169 offset:8544
	ds_read_b64_tr_b16 v[76:77], v169 offset:16992
	ds_read_b64_tr_b16 v[78:79], v169 offset:25440
	v_cvt_pk_bf16_f32 v6, v90, v91
	s_waitcnt lgkmcnt(4)
	v_add_f32_e32 v137, v4, v5
	s_waitcnt lgkmcnt(2)
	v_mfma_f32_16x16x32_bf16 v[72:75], v[72:75], v[56:59], 0
	v_cvt_pk_bf16_f32 v4, v86, v87
	v_cvt_pk_bf16_f32 v5, v88, v89
	v_cvt_pk_bf16_f32 v7, v92, v93
	s_waitcnt lgkmcnt(0)
	v_mfma_f32_16x16x32_bf16 v[108:111], v[76:79], v[52:55], v[72:75]
	s_nop 2
	ds_read_b64_tr_b16 v[72:73], v169 offset:128
	ds_read_b64_tr_b16 v[74:75], v169 offset:8576
	ds_read_b64_tr_b16 v[76:77], v169 offset:17024
	ds_read_b64_tr_b16 v[78:79], v169 offset:25472
	ds_bpermute_b32 v138, v172, v137
	s_waitcnt lgkmcnt(3)
	v_mfma_f32_16x16x32_bf16 v[72:75], v[72:75], v[56:59], 0
	s_waitcnt lgkmcnt(1)
	v_mfma_f32_16x16x32_bf16 v[72:75], v[76:79], v[52:55], v[72:75]
	ds_read_b64_tr_b16 v[76:77], v169 offset:160
	ds_read_b64_tr_b16 v[78:79], v169 offset:8608
	ds_read_b64_tr_b16 v[80:81], v169 offset:17056
	ds_read_b64_tr_b16 v[82:83], v169 offset:25504
	s_waitcnt lgkmcnt(2)
	v_mfma_f32_16x16x32_bf16 v[76:79], v[76:79], v[56:59], 0
	s_waitcnt lgkmcnt(0)
	v_mfma_f32_16x16x32_bf16 v[76:79], v[80:83], v[52:55], v[76:79]
	ds_read_b64_tr_b16 v[80:81], v169 offset:192
	ds_read_b64_tr_b16 v[82:83], v169 offset:8640
	ds_read_b64_tr_b16 v[84:85], v169 offset:17088
	ds_read_b64_tr_b16 v[86:87], v169 offset:25536
	s_waitcnt lgkmcnt(2)
	v_mfma_f32_16x16x32_bf16 v[80:83], v[80:83], v[56:59], 0
	s_waitcnt lgkmcnt(0)
	v_mfma_f32_16x16x32_bf16 v[80:83], v[84:87], v[52:55], v[80:83]
	ds_read_b64_tr_b16 v[84:85], v169 offset:224
	ds_read_b64_tr_b16 v[86:87], v169 offset:8672
	ds_read_b64_tr_b16 v[88:89], v169 offset:17120
	ds_read_b64_tr_b16 v[90:91], v169 offset:25568
	s_waitcnt lgkmcnt(2)
	v_mfma_f32_16x16x32_bf16 v[84:87], v[84:87], v[56:59], 0
	s_waitcnt lgkmcnt(0)
	v_mfma_f32_16x16x32_bf16 v[112:115], v[88:91], v[52:55], v[84:87]
	s_nop 5
	ds_read_b64_tr_b16 v[84:85], v169 offset:256
	ds_read_b64_tr_b16 v[86:87], v169 offset:8704
	ds_read_b64_tr_b16 v[88:89], v169 offset:17152
	ds_read_b64_tr_b16 v[90:91], v169 offset:25600
	s_waitcnt lgkmcnt(2)
	v_mfma_f32_16x16x32_bf16 v[84:87], v[84:87], v[56:59], 0
	s_waitcnt lgkmcnt(0)
	v_mfma_f32_16x16x32_bf16 v[84:87], v[88:91], v[52:55], v[84:87]
	ds_read_b64_tr_b16 v[88:89], v169 offset:288
	ds_read_b64_tr_b16 v[90:91], v169 offset:8736
	ds_read_b64_tr_b16 v[92:93], v169 offset:17184
	ds_read_b64_tr_b16 v[94:95], v169 offset:25632
	s_waitcnt lgkmcnt(2)
	v_mfma_f32_16x16x32_bf16 v[88:91], v[88:91], v[56:59], 0
	s_waitcnt lgkmcnt(0)
	v_mfma_f32_16x16x32_bf16 v[88:91], v[92:95], v[52:55], v[88:91]
	ds_read_b64_tr_b16 v[92:93], v169 offset:320
	ds_read_b64_tr_b16 v[94:95], v169 offset:8768
	ds_read_b64_tr_b16 v[96:97], v169 offset:17216
	ds_read_b64_tr_b16 v[98:99], v169 offset:25664
	s_waitcnt lgkmcnt(2)
	v_mfma_f32_16x16x32_bf16 v[92:95], v[92:95], v[56:59], 0
	s_waitcnt lgkmcnt(0)
	v_mfma_f32_16x16x32_bf16 v[92:95], v[96:99], v[52:55], v[92:95]
	ds_read_b64_tr_b16 v[96:97], v169 offset:352
	ds_read_b64_tr_b16 v[98:99], v169 offset:8800
	ds_read_b64_tr_b16 v[100:101], v169 offset:17248
	ds_read_b64_tr_b16 v[102:103], v169 offset:25696
	s_waitcnt lgkmcnt(2)
	v_mfma_f32_16x16x32_bf16 v[96:99], v[96:99], v[56:59], 0
	s_waitcnt lgkmcnt(0)
	v_mfma_f32_16x16x32_bf16 v[116:119], v[100:103], v[52:55], v[96:99]
	s_nop 5
	ds_read_b64_tr_b16 v[96:97], v169 offset:384
	ds_read_b64_tr_b16 v[98:99], v169 offset:8832
	ds_read_b64_tr_b16 v[100:101], v169 offset:17280
	ds_read_b64_tr_b16 v[102:103], v169 offset:25728
	s_waitcnt lgkmcnt(2)
	v_mfma_f32_16x16x32_bf16 v[96:99], v[96:99], v[56:59], 0
	s_waitcnt lgkmcnt(0)
	v_mfma_f32_16x16x32_bf16 v[96:99], v[100:103], v[52:55], v[96:99]
	ds_read_b64_tr_b16 v[100:101], v169 offset:416
	ds_read_b64_tr_b16 v[102:103], v169 offset:8864
	ds_read_b64_tr_b16 v[104:105], v169 offset:17312
	ds_read_b64_tr_b16 v[106:107], v169 offset:25760
	s_waitcnt lgkmcnt(2)
	v_mfma_f32_16x16x32_bf16 v[100:103], v[100:103], v[56:59], 0
	s_waitcnt lgkmcnt(0)
	v_mfma_f32_16x16x32_bf16 v[100:103], v[104:107], v[52:55], v[100:103]
	ds_read_b64_tr_b16 v[104:105], v169 offset:448
	ds_read_b64_tr_b16 v[106:107], v169 offset:8896
	ds_read_b64_tr_b16 v[120:121], v169 offset:17344
	ds_read_b64_tr_b16 v[122:123], v169 offset:25792
	s_waitcnt lgkmcnt(2)
	v_mfma_f32_16x16x32_bf16 v[104:107], v[104:107], v[56:59], 0
	s_waitcnt lgkmcnt(0)
	v_mfma_f32_16x16x32_bf16 v[104:107], v[120:123], v[52:55], v[104:107]
	ds_read_b64_tr_b16 v[120:121], v169 offset:480
	ds_read_b64_tr_b16 v[122:123], v169 offset:8928
	ds_read_b64_tr_b16 v[124:125], v169 offset:17376
	ds_read_b64_tr_b16 v[126:127], v169 offset:25824
	s_waitcnt vmcnt(7)
	ds_write_b128 v168, v[12:15]
	s_waitcnt vmcnt(6)
	ds_write_b128 v168, v[16:19] offset:128
	s_waitcnt vmcnt(5)
	ds_write_b128 v168, v[20:23] offset:256
	s_waitcnt vmcnt(4)
	ds_write_b128 v168, v[24:27] offset:384
	global_load_dwordx4 v[12:15], v[160:161], off offset:2048
	global_load_dwordx4 v[16:19], v[160:161], off offset:2176
	global_load_dwordx4 v[20:23], v[160:161], off offset:2304
	global_load_dwordx4 v[24:27], v[160:161], off offset:2432
	s_waitcnt lgkmcnt(6)
	v_mfma_f32_16x16x32_bf16 v[56:59], v[120:123], v[56:59], 0
	s_waitcnt lgkmcnt(0)
	s_barrier
	s_waitcnt lgkmcnt(4)
	v_mfma_f32_16x16x32_bf16 v[120:123], v[124:127], v[52:55], v[56:59]
	ds_read_b64_tr_b16 v[52:53], v3
	s_nop 3
	ds_read_b64_tr_b16 v[56:57], v3 offset:32
	ds_read_b64_tr_b16 v[54:55], v3 offset:8448
	ds_read_b64_tr_b16 v[124:125], v3 offset:16896
	ds_read_b64_tr_b16 v[126:127], v3 offset:25344
	s_waitcnt lgkmcnt(2)
	v_mfma_f32_16x16x32_bf16 v[52:55], v[52:55], v[48:51], v[60:63]
	ds_read_b64_tr_b16 v[58:59], v3 offset:8480
	s_nop 1
	ds_read_b64_tr_b16 v[60:61], v3 offset:16928
	ds_read_b64_tr_b16 v[62:63], v3 offset:25376
	s_waitcnt lgkmcnt(2)
	v_mfma_f32_16x16x32_bf16 v[56:59], v[56:59], v[48:51], v[64:67]
	s_waitcnt lgkmcnt(0)
	v_mfma_f32_16x16x32_bf16 v[56:59], v[60:63], v[44:47], v[56:59]
	ds_read_b64_tr_b16 v[60:61], v3 offset:64
	ds_read_b64_tr_b16 v[62:63], v3 offset:8512
	ds_read_b64_tr_b16 v[64:65], v3 offset:16960
	ds_read_b64_tr_b16 v[66:67], v3 offset:25408
	s_waitcnt lgkmcnt(2)
	v_mfma_f32_16x16x32_bf16 v[60:63], v[60:63], v[48:51], v[68:71]
	s_waitcnt lgkmcnt(0)
	v_mfma_f32_16x16x32_bf16 v[60:63], v[64:67], v[44:47], v[60:63]
	ds_read_b64_tr_b16 v[64:65], v3 offset:96
	ds_read_b64_tr_b16 v[66:67], v3 offset:8544
	ds_read_b64_tr_b16 v[68:69], v3 offset:16992
	ds_read_b64_tr_b16 v[70:71], v3 offset:25440
	s_waitcnt lgkmcnt(2)
	v_mfma_f32_16x16x32_bf16 v[64:67], v[64:67], v[48:51], v[108:111]
	s_waitcnt lgkmcnt(0)
	v_mfma_f32_16x16x32_bf16 v[64:67], v[68:71], v[44:47], v[64:67]
	ds_read_b64_tr_b16 v[68:69], v3 offset:128
	ds_read_b64_tr_b16 v[70:71], v3 offset:8576
	ds_read_b64_tr_b16 v[108:109], v3 offset:17024
	ds_read_b64_tr_b16 v[110:111], v3 offset:25472
	s_waitcnt lgkmcnt(2)
	v_mfma_f32_16x16x32_bf16 v[68:71], v[68:71], v[48:51], v[72:75]
	s_waitcnt lgkmcnt(0)
	v_mfma_f32_16x16x32_bf16 v[68:71], v[108:111], v[44:47], v[68:71]
	s_nop 0
	ds_read_b64_tr_b16 v[72:73], v3 offset:160
	ds_read_b64_tr_b16 v[74:75], v3 offset:8608
	ds_read_b64_tr_b16 v[108:109], v3 offset:17056
	ds_read_b64_tr_b16 v[110:111], v3 offset:25504
	s_waitcnt lgkmcnt(2)
	v_mfma_f32_16x16x32_bf16 v[72:75], v[72:75], v[48:51], v[76:79]
	s_waitcnt lgkmcnt(0)
	v_mfma_f32_16x16x32_bf16 v[108:111], v[108:111], v[44:47], v[72:75]
	s_nop 5
	ds_read_b64_tr_b16 v[72:73], v3 offset:192
	ds_read_b64_tr_b16 v[74:75], v3 offset:8640
	ds_read_b64_tr_b16 v[76:77], v3 offset:17088
	ds_read_b64_tr_b16 v[78:79], v3 offset:25536
	s_waitcnt lgkmcnt(2)
	v_mfma_f32_16x16x32_bf16 v[72:75], v[72:75], v[48:51], v[80:83]
	v_mfma_f32_16x16x32_bf16 v[52:55], v[124:127], v[44:47], v[52:55]
	s_waitcnt lgkmcnt(0)
	v_mfma_f32_16x16x32_bf16 v[124:127], v[76:79], v[44:47], v[72:75]
	s_nop 4
	ds_read_b64_tr_b16 v[72:73], v3 offset:224
	ds_read_b64_tr_b16 v[74:75], v3 offset:8672
	ds_read_b64_tr_b16 v[76:77], v3 offset:17120
	ds_read_b64_tr_b16 v[78:79], v3 offset:25568
	s_waitcnt lgkmcnt(2)
	v_mfma_f32_16x16x32_bf16 v[72:75], v[72:75], v[48:51], v[112:115]
	s_waitcnt lgkmcnt(0)
	v_mfma_f32_16x16x32_bf16 v[132:135], v[76:79], v[44:47], v[72:75]
	s_nop 5
	ds_read_b64_tr_b16 v[72:73], v3 offset:256
	ds_read_b64_tr_b16 v[74:75], v3 offset:8704
	ds_read_b64_tr_b16 v[76:77], v3 offset:17152
	ds_read_b64_tr_b16 v[78:79], v3 offset:25600
	s_waitcnt lgkmcnt(2)
	v_mfma_f32_16x16x32_bf16 v[72:75], v[72:75], v[48:51], v[84:87]
	s_waitcnt lgkmcnt(0)
	v_mfma_f32_16x16x32_bf16 v[112:115], v[76:79], v[44:47], v[72:75]
	s_nop 5
	ds_read_b64_tr_b16 v[72:73], v3 offset:288
	ds_read_b64_tr_b16 v[74:75], v3 offset:8736
	ds_read_b64_tr_b16 v[76:77], v3 offset:17184
	ds_read_b64_tr_b16 v[78:79], v3 offset:25632
	s_waitcnt lgkmcnt(2)
	v_mfma_f32_16x16x32_bf16 v[72:75], v[72:75], v[48:51], v[88:91]
	s_waitcnt lgkmcnt(0)
	v_mfma_f32_16x16x32_bf16 v[128:131], v[76:79], v[44:47], v[72:75]
	s_nop 5
	ds_read_b64_tr_b16 v[72:73], v3 offset:320
	ds_read_b64_tr_b16 v[74:75], v3 offset:8768
	ds_read_b64_tr_b16 v[76:77], v3 offset:17216
	ds_read_b64_tr_b16 v[78:79], v3 offset:25664
	s_waitcnt lgkmcnt(2)
	v_mfma_f32_16x16x32_bf16 v[72:75], v[72:75], v[48:51], v[92:95]
	s_waitcnt lgkmcnt(0)
	v_mfma_f32_16x16x32_bf16 v[92:95], v[76:79], v[44:47], v[72:75]
	s_nop 5
	ds_read_b64_tr_b16 v[72:73], v3 offset:352
	ds_read_b64_tr_b16 v[74:75], v3 offset:8800
	ds_read_b64_tr_b16 v[76:77], v3 offset:17248
	ds_read_b64_tr_b16 v[78:79], v3 offset:25696
	s_waitcnt lgkmcnt(2)
	v_mfma_f32_16x16x32_bf16 v[72:75], v[72:75], v[48:51], v[116:119]
	s_waitcnt lgkmcnt(0)
	v_mfma_f32_16x16x32_bf16 v[116:119], v[76:79], v[44:47], v[72:75]
	s_nop 5
	ds_read_b64_tr_b16 v[72:73], v3 offset:384
	ds_read_b64_tr_b16 v[74:75], v3 offset:8832
	ds_read_b64_tr_b16 v[76:77], v3 offset:17280
	ds_read_b64_tr_b16 v[78:79], v3 offset:25728
	s_waitcnt lgkmcnt(2)
	v_mfma_f32_16x16x32_bf16 v[72:75], v[72:75], v[48:51], v[96:99]
	s_waitcnt lgkmcnt(0)
	v_mfma_f32_16x16x32_bf16 v[96:99], v[76:79], v[44:47], v[72:75]
	s_nop 5
	ds_read_b64_tr_b16 v[72:73], v3 offset:416
	ds_read_b64_tr_b16 v[74:75], v3 offset:8864
	ds_read_b64_tr_b16 v[76:77], v3 offset:17312
	ds_read_b64_tr_b16 v[78:79], v3 offset:25760
	s_waitcnt lgkmcnt(2)
	v_mfma_f32_16x16x32_bf16 v[72:75], v[72:75], v[48:51], v[100:103]
	s_waitcnt lgkmcnt(0)
	v_mfma_f32_16x16x32_bf16 v[100:103], v[76:79], v[44:47], v[72:75]
	s_nop 5
	ds_read_b64_tr_b16 v[72:73], v3 offset:448
	ds_read_b64_tr_b16 v[74:75], v3 offset:8896
	ds_read_b64_tr_b16 v[76:77], v3 offset:17344
	ds_read_b64_tr_b16 v[78:79], v3 offset:25792
	s_waitcnt lgkmcnt(2)
	v_mfma_f32_16x16x32_bf16 v[72:75], v[72:75], v[48:51], v[104:107]
	s_waitcnt lgkmcnt(0)
	v_mfma_f32_16x16x32_bf16 v[104:107], v[76:79], v[44:47], v[72:75]
	s_nop 5
	ds_read_b64_tr_b16 v[72:73], v3 offset:480
	ds_read_b64_tr_b16 v[74:75], v3 offset:8928
	ds_read_b64_tr_b16 v[76:77], v3 offset:17376
	ds_read_b64_tr_b16 v[78:79], v3 offset:25824
	s_waitcnt vmcnt(7)
	ds_write_b128 v170, v[28:31]
	s_waitcnt vmcnt(6)
	ds_write_b128 v170, v[32:35] offset:128
	s_waitcnt vmcnt(5)
	ds_write_b128 v170, v[36:39] offset:256
	s_waitcnt vmcnt(4)
	ds_write_b128 v170, v[40:43] offset:384
	s_waitcnt lgkmcnt(0)
	s_barrier
	ds_read_b64_tr_b16 v[28:29], v169
	ds_read_b64_tr_b16 v[32:33], v169 offset:32
	ds_read_b64_tr_b16 v[30:31], v169 offset:8448
	ds_read_b64_tr_b16 v[34:35], v169 offset:16896
	ds_read_b64_tr_b16 v[36:37], v169 offset:25344
	s_waitcnt lgkmcnt(11)
	v_mfma_f32_16x16x32_bf16 v[48:51], v[72:75], v[48:51], v[120:123]
	s_waitcnt lgkmcnt(2)
	v_mfma_f32_16x16x32_bf16 v[28:31], v[28:31], v[8:11], v[52:55]
	v_mfma_f32_16x16x32_bf16 v[88:91], v[76:79], v[44:47], v[48:51]
	s_waitcnt lgkmcnt(0)
	v_mfma_f32_16x16x32_bf16 v[76:79], v[34:37], v[4:7], v[28:31]
	ds_read_b64_tr_b16 v[34:35], v169 offset:8480
	s_nop 3
	ds_read_b64_tr_b16 v[28:29], v169 offset:16928
	ds_read_b64_tr_b16 v[30:31], v169 offset:25376
	s_waitcnt lgkmcnt(2)
	v_mfma_f32_16x16x32_bf16 v[32:35], v[32:35], v[8:11], v[56:59]
	s_waitcnt lgkmcnt(0)
	v_mfma_f32_16x16x32_bf16 v[80:83], v[28:31], v[4:7], v[32:35]
	ds_read_b64_tr_b16 v[28:29], v169 offset:64
	ds_read_b64_tr_b16 v[30:31], v169 offset:8512
	s_nop 3
	ds_read_b64_tr_b16 v[32:33], v169 offset:16960
	ds_read_b64_tr_b16 v[34:35], v169 offset:25408
	s_waitcnt lgkmcnt(2)
	v_mfma_f32_16x16x32_bf16 v[28:31], v[28:31], v[8:11], v[60:63]
	s_waitcnt lgkmcnt(0)
	v_mfma_f32_16x16x32_bf16 v[84:87], v[32:35], v[4:7], v[28:31]
	s_nop 5
	ds_read_b64_tr_b16 v[28:29], v169 offset:96
	ds_read_b64_tr_b16 v[30:31], v169 offset:8544
	ds_read_b64_tr_b16 v[32:33], v169 offset:16992
	ds_read_b64_tr_b16 v[34:35], v169 offset:25440
	s_waitcnt lgkmcnt(2)
	v_mfma_f32_16x16x32_bf16 v[28:31], v[28:31], v[8:11], v[64:67]
	s_waitcnt lgkmcnt(0)
	v_mfma_f32_16x16x32_bf16 v[72:75], v[32:35], v[4:7], v[28:31]
	s_nop 5
	ds_read_b64_tr_b16 v[28:29], v169 offset:128
	ds_read_b64_tr_b16 v[30:31], v169 offset:8576
	ds_read_b64_tr_b16 v[32:33], v169 offset:17024
	ds_read_b64_tr_b16 v[34:35], v169 offset:25472
	s_waitcnt lgkmcnt(2)
	v_mfma_f32_16x16x32_bf16 v[28:31], v[28:31], v[8:11], v[68:71]
	s_waitcnt lgkmcnt(0)
	v_mfma_f32_16x16x32_bf16 v[28:31], v[32:35], v[4:7], v[28:31]
	ds_read_b64_tr_b16 v[32:33], v169 offset:160
	ds_read_b64_tr_b16 v[34:35], v169 offset:8608
	ds_read_b64_tr_b16 v[36:37], v169 offset:17056
	ds_read_b64_tr_b16 v[38:39], v169 offset:25504
	s_waitcnt lgkmcnt(2)
	v_mfma_f32_16x16x32_bf16 v[32:35], v[32:35], v[8:11], v[108:111]
	s_waitcnt lgkmcnt(0)
	v_mfma_f32_16x16x32_bf16 v[32:35], v[36:39], v[4:7], v[32:35]
	ds_read_b64_tr_b16 v[36:37], v169 offset:192
	ds_read_b64_tr_b16 v[38:39], v169 offset:8640
	ds_read_b64_tr_b16 v[40:41], v169 offset:17088
	ds_read_b64_tr_b16 v[42:43], v169 offset:25536
	s_waitcnt lgkmcnt(2)
	v_mfma_f32_16x16x32_bf16 v[36:39], v[36:39], v[8:11], v[124:127]
	s_waitcnt lgkmcnt(0)
	v_mfma_f32_16x16x32_bf16 v[36:39], v[40:43], v[4:7], v[36:39]
	ds_read_b64_tr_b16 v[40:41], v169 offset:224
	ds_read_b64_tr_b16 v[42:43], v169 offset:8672
	ds_read_b64_tr_b16 v[44:45], v169 offset:17120
	ds_read_b64_tr_b16 v[46:47], v169 offset:25568
	s_waitcnt lgkmcnt(2)
	v_mfma_f32_16x16x32_bf16 v[40:43], v[40:43], v[8:11], v[132:135]
	s_waitcnt lgkmcnt(0)
	v_mfma_f32_16x16x32_bf16 v[64:67], v[44:47], v[4:7], v[40:43]
	s_nop 5
	ds_read_b64_tr_b16 v[40:41], v169 offset:256
	ds_read_b64_tr_b16 v[42:43], v169 offset:8704
	ds_read_b64_tr_b16 v[44:45], v169 offset:17152
	ds_read_b64_tr_b16 v[46:47], v169 offset:25600
	s_waitcnt lgkmcnt(2)
	v_mfma_f32_16x16x32_bf16 v[40:43], v[40:43], v[8:11], v[112:115]
	s_waitcnt lgkmcnt(0)
	v_mfma_f32_16x16x32_bf16 v[40:43], v[44:47], v[4:7], v[40:43]
	ds_read_b64_tr_b16 v[44:45], v169 offset:288
	ds_read_b64_tr_b16 v[46:47], v169 offset:8736
	ds_read_b64_tr_b16 v[48:49], v169 offset:17184
	ds_read_b64_tr_b16 v[50:51], v169 offset:25632
	s_waitcnt lgkmcnt(2)
	v_mfma_f32_16x16x32_bf16 v[44:47], v[44:47], v[8:11], v[128:131]
	s_waitcnt lgkmcnt(0)
	v_mfma_f32_16x16x32_bf16 v[44:47], v[48:51], v[4:7], v[44:47]
	ds_read_b64_tr_b16 v[48:49], v169 offset:320
	ds_read_b64_tr_b16 v[50:51], v169 offset:8768
	ds_read_b64_tr_b16 v[52:53], v169 offset:17216
	ds_read_b64_tr_b16 v[54:55], v169 offset:25664
	s_waitcnt lgkmcnt(2)
	v_mfma_f32_16x16x32_bf16 v[48:51], v[48:51], v[8:11], v[92:95]
	s_waitcnt lgkmcnt(0)
	v_mfma_f32_16x16x32_bf16 v[48:51], v[52:55], v[4:7], v[48:51]
	ds_read_b64_tr_b16 v[52:53], v169 offset:352
	ds_read_b64_tr_b16 v[54:55], v169 offset:8800
	ds_read_b64_tr_b16 v[56:57], v169 offset:17248
	ds_read_b64_tr_b16 v[58:59], v169 offset:25696
	s_waitcnt lgkmcnt(2)
	v_mfma_f32_16x16x32_bf16 v[52:55], v[52:55], v[8:11], v[116:119]
	s_waitcnt lgkmcnt(0)
	v_mfma_f32_16x16x32_bf16 v[68:71], v[56:59], v[4:7], v[52:55]
	s_nop 5
	ds_read_b64_tr_b16 v[52:53], v169 offset:384
	ds_read_b64_tr_b16 v[54:55], v169 offset:8832
	ds_read_b64_tr_b16 v[56:57], v169 offset:17280
	ds_read_b64_tr_b16 v[58:59], v169 offset:25728
	s_waitcnt lgkmcnt(2)
	v_mfma_f32_16x16x32_bf16 v[52:55], v[52:55], v[8:11], v[96:99]
	s_waitcnt lgkmcnt(0)
	v_mfma_f32_16x16x32_bf16 v[52:55], v[56:59], v[4:7], v[52:55]
	ds_read_b64_tr_b16 v[56:57], v169 offset:416
	ds_read_b64_tr_b16 v[58:59], v169 offset:8864
	ds_read_b64_tr_b16 v[60:61], v169 offset:17312
	ds_read_b64_tr_b16 v[62:63], v169 offset:25760
	s_waitcnt lgkmcnt(2)
	v_mfma_f32_16x16x32_bf16 v[56:59], v[56:59], v[8:11], v[100:103]
	s_waitcnt lgkmcnt(0)
	v_mfma_f32_16x16x32_bf16 v[56:59], v[60:63], v[4:7], v[56:59]
	ds_read_b64_tr_b16 v[60:61], v169 offset:448
	ds_read_b64_tr_b16 v[62:63], v169 offset:8896
	ds_read_b64_tr_b16 v[92:93], v169 offset:17344
	ds_read_b64_tr_b16 v[94:95], v169 offset:25792
	s_waitcnt lgkmcnt(2)
	v_mfma_f32_16x16x32_bf16 v[60:63], v[60:63], v[8:11], v[104:107]
	s_waitcnt lgkmcnt(0)
	v_mfma_f32_16x16x32_bf16 v[60:63], v[92:95], v[4:7], v[60:63]
	ds_read_b64_tr_b16 v[92:93], v169 offset:480
	ds_read_b64_tr_b16 v[94:95], v169 offset:8928
	ds_read_b64_tr_b16 v[96:97], v169 offset:17376
	ds_read_b64_tr_b16 v[98:99], v169 offset:25824
	s_waitcnt vmcnt(3)
	ds_write_b128 v168, v[12:15]
	s_waitcnt vmcnt(2)
	ds_write_b128 v168, v[16:19] offset:128
	s_waitcnt vmcnt(1)
	ds_write_b128 v168, v[20:23] offset:256
	s_waitcnt vmcnt(0)
	ds_write_b128 v168, v[24:27] offset:384
	s_waitcnt lgkmcnt(0)
	s_waitcnt lgkmcnt(6)
	v_mfma_f32_16x16x32_bf16 v[8:11], v[92:95], v[8:11], v[88:91]
	s_barrier
	v_cvt_pk_bf16_f32 v20, v139, v140
	s_waitcnt lgkmcnt(4)
	v_mfma_f32_16x16x32_bf16 v[4:7], v[96:99], v[4:7], v[8:11]
	s_nop 3
	ds_read_b64_tr_b16 v[8:9], v3
	ds_read_b64_tr_b16 v[24:25], v3 offset:32
	ds_read_b64_tr_b16 v[10:11], v3 offset:8448
	ds_read_b64_tr_b16 v[12:13], v3 offset:16896
	ds_read_b64_tr_b16 v[14:15], v3 offset:25344
	v_cvt_pk_bf16_f32 v21, v141, v142
	v_cvt_pk_bf16_f32 v22, v143, v144
	v_cvt_pk_bf16_f32 v23, v145, v146
	v_cvt_pk_bf16_f32 v16, v147, v148
	v_cvt_pk_bf16_f32 v17, v149, v150
	s_waitcnt lgkmcnt(2)
	v_mfma_f32_16x16x32_bf16 v[8:11], v[8:11], v[20:23], v[76:79]
	v_cvt_pk_bf16_f32 v18, v151, v152
	v_cvt_pk_bf16_f32 v19, v153, v154
	v_add_u32_e32 v88, 0x80, v136
	v_ashrrev_i32_e32 v89, 31, v88
	s_waitcnt lgkmcnt(0)
	v_mfma_f32_16x16x32_bf16 v[12:15], v[12:15], v[16:19], v[8:11]
	ds_read_b64_tr_b16 v[26:27], v3 offset:8480
	s_nop 1
	ds_read_b64_tr_b16 v[8:9], v3 offset:16928
	ds_read_b64_tr_b16 v[10:11], v3 offset:25376
	s_waitcnt lgkmcnt(2)
	v_mfma_f32_16x16x32_bf16 v[24:27], v[24:27], v[20:23], v[80:83]
	s_waitcnt lgkmcnt(0)
	v_mfma_f32_16x16x32_bf16 v[8:11], v[8:11], v[16:19], v[24:27]
	s_nop 5
	ds_read_b64_tr_b16 v[24:25], v3 offset:64
	ds_read_b64_tr_b16 v[26:27], v3 offset:8512
	ds_read_b64_tr_b16 v[76:77], v3 offset:16960
	ds_read_b64_tr_b16 v[78:79], v3 offset:25408
	s_waitcnt lgkmcnt(2)
	v_mfma_f32_16x16x32_bf16 v[24:27], v[24:27], v[20:23], v[84:87]
	s_waitcnt lgkmcnt(0)
	v_mfma_f32_16x16x32_bf16 v[24:27], v[76:79], v[16:19], v[24:27]
	ds_read_b64_tr_b16 v[76:77], v3 offset:96
	ds_read_b64_tr_b16 v[78:79], v3 offset:8544
	ds_read_b64_tr_b16 v[80:81], v3 offset:16992
	ds_read_b64_tr_b16 v[82:83], v3 offset:25440
	s_waitcnt lgkmcnt(2)
	v_mfma_f32_16x16x32_bf16 v[72:75], v[76:79], v[20:23], v[72:75]
	s_waitcnt lgkmcnt(0)
	v_mfma_f32_16x16x32_bf16 v[72:75], v[80:83], v[16:19], v[72:75]
	ds_read_b64_tr_b16 v[76:77], v3 offset:128
	ds_read_b64_tr_b16 v[78:79], v3 offset:8576
	ds_read_b64_tr_b16 v[80:81], v3 offset:17024
	ds_read_b64_tr_b16 v[82:83], v3 offset:25472
	s_waitcnt lgkmcnt(2)
	v_mfma_f32_16x16x32_bf16 v[28:31], v[76:79], v[20:23], v[28:31]
	s_waitcnt lgkmcnt(0)
	v_mfma_f32_16x16x32_bf16 v[28:31], v[80:83], v[16:19], v[28:31]
	ds_read_b64_tr_b16 v[76:77], v3 offset:160
	ds_read_b64_tr_b16 v[78:79], v3 offset:8608
	ds_read_b64_tr_b16 v[80:81], v3 offset:17056
	ds_read_b64_tr_b16 v[82:83], v3 offset:25504
	s_waitcnt lgkmcnt(2)
	v_mfma_f32_16x16x32_bf16 v[32:35], v[76:79], v[20:23], v[32:35]
	s_waitcnt lgkmcnt(0)
	v_mfma_f32_16x16x32_bf16 v[32:35], v[80:83], v[16:19], v[32:35]
	ds_read_b64_tr_b16 v[76:77], v3 offset:192
	ds_read_b64_tr_b16 v[78:79], v3 offset:8640
	ds_read_b64_tr_b16 v[80:81], v3 offset:17088
	ds_read_b64_tr_b16 v[82:83], v3 offset:25536
	s_waitcnt lgkmcnt(2)
	v_mfma_f32_16x16x32_bf16 v[36:39], v[76:79], v[20:23], v[36:39]
	s_waitcnt lgkmcnt(0)
	v_mfma_f32_16x16x32_bf16 v[36:39], v[80:83], v[16:19], v[36:39]
	ds_read_b64_tr_b16 v[76:77], v3 offset:224
	ds_read_b64_tr_b16 v[78:79], v3 offset:8672
	ds_read_b64_tr_b16 v[80:81], v3 offset:17120
	ds_read_b64_tr_b16 v[82:83], v3 offset:25568
	s_waitcnt lgkmcnt(2)
	v_mfma_f32_16x16x32_bf16 v[64:67], v[76:79], v[20:23], v[64:67]
	s_waitcnt lgkmcnt(0)
	v_mfma_f32_16x16x32_bf16 v[64:67], v[80:83], v[16:19], v[64:67]
	ds_read_b64_tr_b16 v[76:77], v3 offset:256
	ds_read_b64_tr_b16 v[78:79], v3 offset:8704
	ds_read_b64_tr_b16 v[80:81], v3 offset:17152
	ds_read_b64_tr_b16 v[82:83], v3 offset:25600
	s_waitcnt lgkmcnt(2)
	v_mfma_f32_16x16x32_bf16 v[40:43], v[76:79], v[20:23], v[40:43]
	s_waitcnt lgkmcnt(0)
	v_mfma_f32_16x16x32_bf16 v[40:43], v[80:83], v[16:19], v[40:43]
	ds_read_b64_tr_b16 v[76:77], v3 offset:288
	ds_read_b64_tr_b16 v[78:79], v3 offset:8736
	ds_read_b64_tr_b16 v[80:81], v3 offset:17184
	ds_read_b64_tr_b16 v[82:83], v3 offset:25632
	s_waitcnt lgkmcnt(2)
	v_mfma_f32_16x16x32_bf16 v[44:47], v[76:79], v[20:23], v[44:47]
	s_waitcnt lgkmcnt(0)
	v_mfma_f32_16x16x32_bf16 v[44:47], v[80:83], v[16:19], v[44:47]
	ds_read_b64_tr_b16 v[76:77], v3 offset:320
	ds_read_b64_tr_b16 v[78:79], v3 offset:8768
	ds_read_b64_tr_b16 v[80:81], v3 offset:17216
	ds_read_b64_tr_b16 v[82:83], v3 offset:25664
	s_waitcnt lgkmcnt(2)
	v_mfma_f32_16x16x32_bf16 v[48:51], v[76:79], v[20:23], v[48:51]
	s_waitcnt lgkmcnt(0)
	v_mfma_f32_16x16x32_bf16 v[48:51], v[80:83], v[16:19], v[48:51]
	ds_read_b64_tr_b16 v[76:77], v3 offset:352
	ds_read_b64_tr_b16 v[78:79], v3 offset:8800
	ds_read_b64_tr_b16 v[80:81], v3 offset:17248
	ds_read_b64_tr_b16 v[82:83], v3 offset:25696
	s_waitcnt lgkmcnt(2)
	v_mfma_f32_16x16x32_bf16 v[68:71], v[76:79], v[20:23], v[68:71]
	s_waitcnt lgkmcnt(0)
	v_mfma_f32_16x16x32_bf16 v[68:71], v[80:83], v[16:19], v[68:71]
	ds_read_b64_tr_b16 v[76:77], v3 offset:384
	ds_read_b64_tr_b16 v[78:79], v3 offset:8832
	ds_read_b64_tr_b16 v[80:81], v3 offset:17280
	ds_read_b64_tr_b16 v[82:83], v3 offset:25728
	s_waitcnt lgkmcnt(2)
	v_mfma_f32_16x16x32_bf16 v[52:55], v[76:79], v[20:23], v[52:55]
	s_waitcnt lgkmcnt(0)
	v_mfma_f32_16x16x32_bf16 v[52:55], v[80:83], v[16:19], v[52:55]
	ds_read_b64_tr_b16 v[76:77], v3 offset:416
	ds_read_b64_tr_b16 v[78:79], v3 offset:8864
	ds_read_b64_tr_b16 v[80:81], v3 offset:17312
	ds_read_b64_tr_b16 v[82:83], v3 offset:25760
	s_waitcnt lgkmcnt(2)
	v_mfma_f32_16x16x32_bf16 v[56:59], v[76:79], v[20:23], v[56:59]
	s_waitcnt lgkmcnt(0)
	v_mfma_f32_16x16x32_bf16 v[56:59], v[80:83], v[16:19], v[56:59]
	ds_read_b64_tr_b16 v[76:77], v3 offset:448
	ds_read_b64_tr_b16 v[78:79], v3 offset:8896
	ds_read_b64_tr_b16 v[80:81], v3 offset:17344
	ds_read_b64_tr_b16 v[82:83], v3 offset:25792
	s_waitcnt lgkmcnt(2)
	v_mfma_f32_16x16x32_bf16 v[60:63], v[76:79], v[20:23], v[60:63]
	s_waitcnt lgkmcnt(0)
	v_mfma_f32_16x16x32_bf16 v[60:63], v[80:83], v[16:19], v[60:63]
	ds_read_b64_tr_b16 v[76:77], v3 offset:480
	ds_read_b64_tr_b16 v[78:79], v3 offset:8928
	ds_read_b64_tr_b16 v[80:81], v3 offset:17376
	ds_read_b64_tr_b16 v[82:83], v3 offset:25824
	v_add_f32_e32 v3, v137, v138
	s_waitcnt lgkmcnt(2)
	v_mfma_f32_16x16x32_bf16 v[4:7], v[76:79], v[20:23], v[4:7]
	s_waitcnt lgkmcnt(0)
	v_mfma_f32_16x16x32_bf16 v[4:7], v[80:83], v[16:19], v[4:7]
	v_div_scale_f32 v16, s[12:13], v3, v3, 1.0
	v_rcp_f32_e32 v17, v16
	s_nop 0
	v_fma_f32 v18, -v16, v17, 1.0
	v_fmac_f32_e32 v17, v18, v17
	v_div_scale_f32 v18, vcc, 1.0, v3, 1.0
	v_mul_f32_e32 v19, v18, v17
	v_fma_f32 v20, -v16, v19, v18
	v_fmac_f32_e32 v19, v20, v17
	v_fma_f32 v16, -v16, v19, v18
	v_div_fmas_f32 v16, v16, v17, v19
	v_lshlrev_b64 v[18:19], 11, v[88:89]
	v_lshl_add_u64 v[18:19], s[10:11], 0, v[18:19]
	v_div_fixup_f32 v16, v16, v3, 1.0
	v_mad_i64_i32 v[18:19], s[6:7], s6, v155, v[18:19]
	v_lshl_add_u64 v[18:19], v[18:19], 0, s[8:9]
	v_pk_mul_f32 v[8:9], v[16:17], v[8:9] op_sel_hi:[0,1]
	v_pk_mul_f32 v[10:11], v[16:17], v[10:11] op_sel_hi:[0,1]
	v_lshl_add_u64 v[0:1], v[18:19], 0, v[0:1]
	v_cvt_pk_bf16_f32 v8, v8, v9
	v_cvt_pk_bf16_f32 v9, v10, v11
	global_store_dwordx2 v[0:1], v[8:9], off offset:32
	v_pk_mul_f32 v[8:9], v[16:17], v[24:25] op_sel_hi:[0,1]
	v_pk_mul_f32 v[10:11], v[16:17], v[26:27] op_sel_hi:[0,1]
	v_cvt_pk_bf16_f32 v8, v8, v9
	v_cvt_pk_bf16_f32 v9, v10, v11
	global_store_dwordx2 v[0:1], v[8:9], off offset:64
	v_pk_mul_f32 v[8:9], v[16:17], v[72:73] op_sel_hi:[0,1]
	v_pk_mul_f32 v[10:11], v[16:17], v[74:75] op_sel_hi:[0,1]
	v_cvt_pk_bf16_f32 v8, v8, v9
	v_cvt_pk_bf16_f32 v9, v10, v11
	global_store_dwordx2 v[0:1], v[8:9], off offset:96
	v_pk_mul_f32 v[8:9], v[16:17], v[28:29] op_sel_hi:[0,1]
	v_pk_mul_f32 v[10:11], v[16:17], v[30:31] op_sel_hi:[0,1]
	v_cvt_pk_bf16_f32 v8, v8, v9
	v_cvt_pk_bf16_f32 v9, v10, v11
	global_store_dwordx2 v[0:1], v[8:9], off offset:128
	v_pk_mul_f32 v[8:9], v[16:17], v[32:33] op_sel_hi:[0,1]
	v_pk_mul_f32 v[10:11], v[16:17], v[34:35] op_sel_hi:[0,1]
	v_cvt_pk_bf16_f32 v8, v8, v9
	v_cvt_pk_bf16_f32 v9, v10, v11
	global_store_dwordx2 v[0:1], v[8:9], off offset:160
	v_pk_mul_f32 v[8:9], v[16:17], v[36:37] op_sel_hi:[0,1]
	v_pk_mul_f32 v[10:11], v[16:17], v[38:39] op_sel_hi:[0,1]
	v_cvt_pk_bf16_f32 v8, v8, v9
	v_cvt_pk_bf16_f32 v9, v10, v11
	global_store_dwordx2 v[0:1], v[8:9], off offset:192
	v_pk_mul_f32 v[8:9], v[16:17], v[64:65] op_sel_hi:[0,1]
	v_pk_mul_f32 v[10:11], v[16:17], v[66:67] op_sel_hi:[0,1]
	v_cvt_pk_bf16_f32 v8, v8, v9
	v_cvt_pk_bf16_f32 v9, v10, v11
	global_store_dwordx2 v[0:1], v[8:9], off offset:224
	v_pk_mul_f32 v[8:9], v[16:17], v[40:41] op_sel_hi:[0,1]
	v_pk_mul_f32 v[10:11], v[16:17], v[42:43] op_sel_hi:[0,1]
	v_cvt_pk_bf16_f32 v8, v8, v9
	v_cvt_pk_bf16_f32 v9, v10, v11
	global_store_dwordx2 v[0:1], v[8:9], off offset:256
	v_pk_mul_f32 v[8:9], v[16:17], v[44:45] op_sel_hi:[0,1]
	v_pk_mul_f32 v[10:11], v[16:17], v[46:47] op_sel_hi:[0,1]
	v_cvt_pk_bf16_f32 v8, v8, v9
	v_cvt_pk_bf16_f32 v9, v10, v11
	global_store_dwordx2 v[0:1], v[8:9], off offset:288
	v_pk_mul_f32 v[8:9], v[16:17], v[48:49] op_sel_hi:[0,1]
	v_pk_mul_f32 v[10:11], v[16:17], v[50:51] op_sel_hi:[0,1]
	v_cvt_pk_bf16_f32 v8, v8, v9
	v_cvt_pk_bf16_f32 v9, v10, v11
	global_store_dwordx2 v[0:1], v[8:9], off offset:320
	v_pk_mul_f32 v[8:9], v[16:17], v[68:69] op_sel_hi:[0,1]
	v_pk_mul_f32 v[10:11], v[16:17], v[70:71] op_sel_hi:[0,1]
	v_cvt_pk_bf16_f32 v8, v8, v9
	v_cvt_pk_bf16_f32 v9, v10, v11
	global_store_dwordx2 v[0:1], v[8:9], off offset:352
	v_pk_mul_f32 v[8:9], v[16:17], v[52:53] op_sel_hi:[0,1]
	v_pk_mul_f32 v[10:11], v[16:17], v[54:55] op_sel_hi:[0,1]
	v_cvt_pk_bf16_f32 v8, v8, v9
	v_cvt_pk_bf16_f32 v9, v10, v11
	global_store_dwordx2 v[0:1], v[8:9], off offset:384
	v_pk_mul_f32 v[8:9], v[16:17], v[56:57] op_sel_hi:[0,1]
	v_pk_mul_f32 v[10:11], v[16:17], v[58:59] op_sel_hi:[0,1]
	v_cvt_pk_bf16_f32 v8, v8, v9
	v_cvt_pk_bf16_f32 v9, v10, v11
	v_pk_mul_f32 v[12:13], v[16:17], v[12:13] op_sel_hi:[0,1]
	v_pk_mul_f32 v[14:15], v[16:17], v[14:15] op_sel_hi:[0,1]
	global_store_dwordx2 v[0:1], v[8:9], off offset:416
	v_pk_mul_f32 v[8:9], v[16:17], v[60:61] op_sel_hi:[0,1]
	v_pk_mul_f32 v[10:11], v[16:17], v[62:63] op_sel_hi:[0,1]
	v_pk_mul_f32 v[4:5], v[16:17], v[4:5] op_sel_hi:[0,1]
	v_pk_mul_f32 v[6:7], v[16:17], v[6:7] op_sel_hi:[0,1]
	v_cvt_pk_bf16_f32 v12, v12, v13
	v_cvt_pk_bf16_f32 v13, v14, v15
	v_cvt_pk_bf16_f32 v8, v8, v9
	v_cvt_pk_bf16_f32 v9, v10, v11
	v_cvt_pk_bf16_f32 v4, v4, v5
	v_cvt_pk_bf16_f32 v5, v6, v7
	global_store_dwordx2 v[0:1], v[12:13], off
	global_store_dwordx2 v[0:1], v[8:9], off offset:448
	global_store_dwordx2 v[0:1], v[4:5], off offset:480
	s_waitcnt lgkmcnt(0)
	s_barrier
